# hyena conv K-split over all 8 waves (waves 4-7 take half the d range, partial accumulators reduced through LDS in f32)
# speedup vs baseline: 1.0452x; 1.0129x over previous
; DI f32x16 zero16() { f32x16 z; for (int i = 0; i < 16; ++i) z[i] = 0.f; return z; }
; DI void hy_conv(f32x16 (&acc)[4], const u16* abase, const u16* U, const u16* Zrow, int a0, int li, int g) {
; #pragma unroll
;   for (int i = 0; i < 4; ++i) acc[i] = zero16();
;   u32x4 W[14];
;   bf16x8 bf[8];
;   int d = a0 - 63;
; #pragma unroll
;   for (int x = 0; x < 14; ++x) W[x] = hy_afrag(abase, 8 * d + x - 7);
; DI void hyena_item(const P& p, int l, int c, char* smem) {
;     ...
;     for (int i = 0; i < 4; ++i) {
;       const int q = tid + NT * i;
;       const int bt = q >> 10, t8 = (q & 1023) * 8;
;       const u16* row = p.hyT + (size_t)c * HYP + bt * SEQ;
;       float o0[4], o1[4];
;       sconv4(row, t8, w0, w1, w2, bs, o0);
;       sconv4(row, t8 + 4, w0, w1, w2, bs, o1);
;       uint4 ov;
;       ov.x = pack2(o0[0], o0[1]); ov.y = pack2(o0[2], o0[3]); ov.z = pack2(o1[0], o1[1]); ov.w = pack2(o1[2], o1[3]);
;       *(uint4*)(U + (bt * 64 + (t8 >> 7)) * 136 + (t8 & 127)) = ov;
;     }
;   }
;   __syncthreads();
;   const float invn0 = 1.0f / (misc[4] + misc[5] + misc[6] + misc[7]);
;   const float invn1 = 1.0f / (misc[8] + misc[9] + misc[10] + misc[11]);
;   const u16* abase = (li & 1) ? (TbO + (8192 - li + 8 * g - 1)) : (TbE + (8192 - li + 8 * g));
;   const int bt = li >> 4;
;   const int a = a0 + (li & 15);
;   f32x16 acc[4];
;   if (cwv) hy_conv(acc, abase, U, Zrow, a0, li, g);
.LBB0_433:
	s_or_b64 exec, exec, s[78:79]
	s_waitcnt vmcnt(2)
	v_and_b32_e32 v26, 0xffff0000, v10
	v_mov_b32_e32 v18, v26
	v_lshlrev_b32_e32 v10, 16, v10
	v_pk_mul_f32 v[18:19], v[2:3], v[18:19]
	v_and_b32_e32 v12, 0xffff0000, v11
	s_waitcnt vmcnt(1)
	v_lshlrev_b32_e32 v13, 16, v14
	v_lshlrev_b32_e32 v27, 16, v11
	v_pk_fma_f32 v[2:3], v[2:3], v[10:11], v[18:19] op_sel:[0,0,1] op_sel_hi:[1,0,0]
	v_pk_mov_b32 v[28:29], v[26:27], v[12:13] op_sel:[1,0]
	v_pk_fma_f32 v[2:3], v[0:1], v[26:27], v[2:3]
	v_readlane_b32 s78, v248, 10
	v_pk_add_f32 v[10:11], v[4:5], v[2:3]
	v_pk_mul_f32 v[2:3], v[8:9], v[28:29]
	s_waitcnt vmcnt(0)
	v_and_b32_e32 v28, 0xffff0000, v16
	v_pk_fma_f32 v[2:3], v[6:7], v[26:27], v[2:3]
	v_lshlrev_b32_e32 v29, 16, v17
	v_pk_fma_f32 v[2:3], v[0:1], v[12:13], v[2:3]
	v_lshlrev_b32_e32 v13, 16, v16
	v_and_b32_e32 v27, 0xffff0000, v17
	v_mov_b32_e32 v26, v29
	v_mov_b32_e32 v16, v13
	v_mov_b32_e32 v17, v28
	v_pk_mul_f32 v[16:17], v[8:9], v[16:17]
	v_pk_mul_f32 v[8:9], v[8:9], v[26:27]
	v_pk_fma_f32 v[12:13], v[6:7], v[12:13], v[16:17]
	v_pk_fma_f32 v[6:7], v[6:7], v[28:29], v[8:9]
	v_mov_b32_e32 v14, v27
	v_pk_fma_f32 v[12:13], v[0:1], v[28:29], v[12:13]
	v_pk_fma_f32 v[0:1], v[0:1], v[14:15], v[6:7]
	v_pk_add_f32 v[18:19], v[4:5], v[2:3]
	v_pk_add_f32 v[0:1], v[4:5], v[0:1]
	v_pk_add_f32 v[12:13], v[4:5], v[12:13]
	v_cvt_pk_bf16_f32 v7, v0, v1
	v_lshrrev_b32_e32 v0, 7, v25
	v_lshl_or_b32 v0, v24, 6, v0
	v_and_b32_e32 v1, 0x78, v23
	v_mul_lo_u32 v0, v0, s97
	v_lshlrev_b32_e32 v1, 1, v1
	v_cvt_pk_bf16_f32 v4, v10, v11
	v_cvt_pk_bf16_f32 v5, v18, v19
	v_cvt_pk_bf16_f32 v6, v12, v13
	v_add3_u32 v0, s69, v0, v1
	ds_write_b128 v0, v[4:7]
	v_mov_b32_e32 v0, s78
	v_readlane_b32 s78, v248, 11
	v_lshrrev_b32_e32 v188, 5, v21
	v_and_b32_e32 v230, 31, v20
	v_mov_b32_e32 v1, s78
	s_waitcnt lgkmcnt(0)
	s_barrier
	ds_read_b128 v[68:71], v0
	ds_read_b128 v[64:67], v1
	v_and_b32_e32 v0, 1, v20
	v_lshlrev_b32_e32 v1, 3, v188
	v_readlane_b32 s78, v248, 12
	v_sub_u32_e32 v1, v1, v230
	v_cmp_eq_u32_e32 vcc, 0, v0
	v_mov_b32_e32 v3, s78
	v_lshlrev_b32_e32 v2, 4, v22
	v_cndmask_b32_e64 v0, v3, 0, vcc
	v_cndmask_b32_e32 v3, v217, v207, vcc
	v_lshlrev_b32_e32 v1, 1, v1
	v_and_b32_e32 v231, 48, v2
	v_add3_u32 v225, v0, v1, v3
	v_and_b32_e32 v223, 15, v20
	v_lshlrev_b32_e32 v0, 2, v230
	v_or_b32_e32 v226, 15, v231
	v_lshlrev_b32_e32 v222, 4, v188
	v_or_b32_e32 v227, 14, v231
	v_add_u32_e32 v229, v231, v223
	v_or_b32_e32 v228, 0xffffffc1, v2
	v_and_b32_e32 v224, 64, v0
	v_mov_b32_e32 v250, 40
	v_cndmask_b32_e64 v249, v250, 0, s[6:7]
	v_add_u32_e32 v228, v228, v249
	v_mov_b32_e32 v250, 39
	v_cndmask_b32_e64 v249, 0, v250, s[6:7]
	v_sub_u32_e32 v227, v227, v249
	v_mov_b32_e32 v249, 24
	v_mov_b32_e32 v250, -15
	v_cndmask_b32_e64 v250, v250, v249, s[6:7]
	s_and_b64 vcc, exec, s[6:7]
	s_cbranch_vccnz .Lhy_pf_skip
	s_or_b32 s78, s72, 0x200
	s_mul_hi_u32 s79, s78, 0x8080
	s_mul_i32 s78, s78, 0x8080
	s_add_u32 s78, s36, s78
	s_addc_u32 s79, s37, s79
	v_and_b32_e32 v240, 0xff, v198
	v_lshlrev_b32_e32 v240, 7, v240
	global_load_dword v241, v240, s[78:79]
	s_add_u32 s78, s78, 0x1010000
	s_addc_u32 s79, s79, 0
	global_load_dword v242, v240, s[78:79]
	s_add_u32 s78, s78, 0x1010000
	s_addc_u32 s79, s79, 0
	global_load_dword v243, v240, s[78:79]
.Lhy_pf_skip:
	s_mov_b64 s[78:79], exec
	v_mov_b32_e32 v232, v228
	s_movk_i32 s88, 0xff00
	v_mad_i32_i24 v0, v232, s88, v225
	ds_read2_b32 v[156:157], v0 offset0:56 offset1:57
	ds_read2_b32 v[158:159], v0 offset0:58 offset1:59
	ds_read2_b32 v[152:153], v0 offset0:48 offset1:49
	ds_read2_b32 v[154:155], v0 offset0:50 offset1:51
	ds_read2_b32 v[144:145], v0 offset0:40 offset1:41
	ds_read2_b32 v[146:147], v0 offset0:42 offset1:43
	ds_read2_b32 v[140:141], v0 offset0:32 offset1:33
	ds_read2_b32 v[142:143], v0 offset0:34 offset1:35
	ds_read2_b32 v[128:129], v0 offset0:24 offset1:25
	ds_read2_b32 v[130:131], v0 offset0:26 offset1:27
	ds_read2_b32 v[132:133], v0 offset0:16 offset1:17
	ds_read2_b32 v[134:135], v0 offset0:18 offset1:19
	ds_read2_b32 v[120:121], v0 offset0:8 offset1:9
	ds_read2_b32 v[122:123], v0 offset0:10 offset1:11
	ds_read2_b32 v[124:125], v0 offset1:1
	ds_read2_b32 v[126:127], v0 offset0:2 offset1:3
	v_subrev_u32_e32 v1, 32, v0
	v_subrev_u32_e32 v2, 24, v0
	v_subrev_u32_e32 v3, 64, v0
	v_subrev_u32_e32 v4, 56, v0
	ds_read2_b32 v[104:105], v1 offset1:1
	ds_read2_b32 v[106:107], v2 offset1:1
	ds_read2_b32 v[96:97], v3 offset1:1
	ds_read2_b32 v[98:99], v4 offset1:1
	v_add_u32_e32 v1, 0xffffffa0, v0
	v_add_u32_e32 v2, 0xffffffa8, v0
	v_add_u32_e32 v3, 0xffffff80, v0
	v_add_u32_e32 v4, 0xffffff88, v0
	ds_read2_b32 v[100:101], v1 offset1:1
	ds_read2_b32 v[102:103], v2 offset1:1
	ds_read2_b32 v[108:109], v3 offset1:1
	ds_read2_b32 v[110:111], v4 offset1:1
	v_add_u32_e32 v1, 0xffffff60, v0
	v_add_u32_e32 v2, 0xffffff68, v0
	v_add_u32_e32 v3, 0xffffff40, v0
	v_add_u32_e32 v0, 0xffffff48, v0
	ds_read2_b32 v[112:113], v1 offset1:1
	ds_read2_b32 v[114:115], v2 offset1:1
	ds_read2_b32 v[116:117], v3 offset1:1
	ds_read2_b32 v[118:119], v0 offset1:1
	v_add_u32_e32 v0, v229, v224
	v_sub_u32_e32 v0, v0, v232
	v_mov_b32_e32 v1, s69
	v_mad_u32_u24 v233, v0, s97, v1
	v_mov_b32_e32 v0, 0
	v_sub_u32_e32 v234, v229, v232
	s_mov_b64 s[88:89], 0
	v_mov_b32_e32 v1, v0
	v_mov_b32_e32 v2, v0
	v_mov_b32_e32 v3, v0
	v_mov_b32_e32 v4, v0
	v_mov_b32_e32 v5, v0
	v_mov_b32_e32 v6, v0
	v_mov_b32_e32 v7, v0
	v_mov_b32_e32 v8, v0
	v_mov_b32_e32 v9, v0
	v_mov_b32_e32 v10, v0
	v_mov_b32_e32 v11, v0
	v_mov_b32_e32 v12, v0
	v_mov_b32_e32 v13, v0
	v_mov_b32_e32 v14, v0
	v_mov_b32_e32 v15, v0
	v_mov_b32_e32 v16, v0
	v_mov_b32_e32 v17, v0
	v_mov_b32_e32 v18, v0
	v_mov_b32_e32 v19, v0
	v_mov_b32_e32 v20, v0
	v_mov_b32_e32 v21, v0
	v_mov_b32_e32 v22, v0
	v_mov_b32_e32 v23, v0
	v_mov_b32_e32 v24, v0
	v_mov_b32_e32 v25, v0
	v_mov_b32_e32 v26, v0
	v_mov_b32_e32 v27, v0
	v_mov_b32_e32 v28, v0
	v_mov_b32_e32 v29, v0
	v_mov_b32_e32 v30, v0
	v_mov_b32_e32 v31, v0
	v_mov_b32_e32 v32, v0
	v_mov_b32_e32 v33, v0
	v_mov_b32_e32 v34, v0
	v_mov_b32_e32 v35, v0
	v_mov_b32_e32 v36, v0
	v_mov_b32_e32 v37, v0
	v_mov_b32_e32 v38, v0
	v_mov_b32_e32 v39, v0
	v_mov_b32_e32 v40, v0
	v_mov_b32_e32 v41, v0
	v_mov_b32_e32 v42, v0
	v_mov_b32_e32 v43, v0
	v_mov_b32_e32 v44, v0
	v_mov_b32_e32 v45, v0
	v_mov_b32_e32 v46, v0
	v_mov_b32_e32 v47, v0
	v_mov_b32_e32 v48, v0
	v_mov_b32_e32 v49, v0
	v_mov_b32_e32 v50, v0
	v_mov_b32_e32 v51, v0
	v_mov_b32_e32 v52, v0
	v_mov_b32_e32 v53, v0
	v_mov_b32_e32 v54, v0
	v_mov_b32_e32 v55, v0
	v_mov_b32_e32 v56, v0
	v_mov_b32_e32 v57, v0
	v_mov_b32_e32 v58, v0
	v_mov_b32_e32 v59, v0
	v_mov_b32_e32 v60, v0
	v_mov_b32_e32 v61, v0
	v_mov_b32_e32 v62, v0
	v_mov_b32_e32 v63, v0
; #define MFMA(a, b, c) __builtin_amdgcn_mfma_f32_32x32x16_bf16((a), (b), (c), 0, 0, 0)
; DI void hy_conv(f32x16 (&acc)[4], const u16* abase, const u16* U, const u16* Zrow, int a0, int li, int g) {
;     ...
;   for (; d <= a0 + 15; ++d) {
;     hy_bfrag(bf, U, Zrow, a0, li, g, d);
;     u32x4 Wn[8];
;     const int dn = (d < a0 + 15) ? d + 1 : d;
; #pragma unroll
;     for (int x = 0; x < 8; ++x) Wn[x] = hy_afrag(abase, 8 * dn + x - 1);
; #pragma unroll
;     for (int kc = 0; kc < 8; ++kc)
; #pragma unroll
;       for (int I = 0; I < 4; ++I) acc[I] = MFMA(__builtin_bit_cast(bf16x8, W[2 * I - kc + 7]), bf[kc], acc[I]);
; #pragma unroll
;     for (int x = 0; x < 6; ++x) W[x] = W[x + 8];
; #pragma unroll
;     for (int x = 0; x < 8; ++x) W[x + 6] = Wn[x];
;   }
.LBB0_435:
	s_waitcnt lgkmcnt(8)
	v_mov_b32_e32 v87, v99
	v_mov_b32_e32 v86, v98
	v_mov_b32_e32 v85, v97
	v_mov_b32_e32 v84, v96
	s_waitcnt lgkmcnt(4)
	v_mov_b32_e32 v91, v111
	v_mov_b32_e32 v90, v110
	v_mov_b32_e32 v89, v109
	v_mov_b32_e32 v88, v108
	s_waitcnt lgkmcnt(0)
	v_mov_b32_e32 v95, v119
	v_mov_b32_e32 v94, v118
	v_mov_b32_e32 v93, v117
	v_mov_b32_e32 v92, v116
	s_add_i32 s97, 0, 0x18880
	v_cmp_gt_u32_e32 vcc, 64, v234
	v_mov_b32_e32 v96, s97
	v_mov_b32_e32 v75, v107
	v_cndmask_b32_e32 v96, v96, v233, vcc
	v_add_u32_e32 v96, v96, v222
	ds_read_b128 v[236:239], v96
	ds_read_b128 v[184:187], v96 offset:32
	ds_read_b128 v[180:183], v96 offset:64
	ds_read_b128 v[176:179], v96 offset:96
	ds_read_b128 v[172:175], v96 offset:128
	ds_read_b128 v[168:171], v96 offset:160
	ds_read_b128 v[164:167], v96 offset:192
	ds_read_b128 v[160:163], v96 offset:224
	s_waitcnt lgkmcnt(7)
	v_mfma_f32_32x32x16_bf16 v[48:63], v[124:127], v[236:239], v[48:63]
	v_mov_b32_e32 v74, v106
	v_mov_b32_e32 v73, v105
	v_mov_b32_e32 v72, v104
	v_mov_b32_e32 v79, v103
	v_mov_b32_e32 v78, v102
	v_mov_b32_e32 v77, v101
	v_mov_b32_e32 v76, v100
	v_mfma_f32_32x32x16_bf16 v[32:47], v[84:87], v[236:239], v[32:47]
	v_mov_b32_e32 v83, v115
	v_mov_b32_e32 v82, v114
	v_mov_b32_e32 v81, v113
	v_mov_b32_e32 v80, v112
	v_cmp_lt_i32_e32 vcc, v232, v226
	v_add_u32_e32 v235, 1, v232
	v_add_u32_e32 v233, 0xfffffef0, v233
	v_mfma_f32_32x32x16_bf16 v[16:31], v[88:91], v[236:239], v[16:31]
	v_cndmask_b32_e32 v96, v232, v235, vcc
	v_lshlrev_b32_e32 v116, 8, v96
	v_sub_u32_e32 v96, v225, v116
	ds_read2_b32 v[136:137], v96 offset0:8 offset1:9
	ds_read2_b32 v[138:139], v96 offset0:10 offset1:11
	ds_read2_b32 v[148:149], v96 offset1:1
	ds_read2_b32 v[150:151], v96 offset0:2 offset1:3
	v_xad_u32 v96, v116, s93, v225
	v_xad_u32 v98, v116, s92, v225
	v_xad_u32 v102, v116, s60, v225
	v_mfma_f32_32x32x16_bf16 v[0:15], v[92:95], v[236:239], v[0:15]
	v_xad_u32 v110, v116, s54, v225
	v_xad_u32 v114, v116, s55, v225
	v_xad_u32 v118, v116, s66, v225
	ds_read2_b32 v[104:105], v96 offset1:1
	ds_read2_b32 v[106:107], v96 offset0:2 offset1:3
	ds_read2_b32 v[96:97], v98 offset1:1
	ds_read2_b32 v[98:99], v98 offset0:2 offset1:3
	ds_read2_b32 v[100:101], v102 offset1:1
	ds_read2_b32 v[102:103], v102 offset0:2 offset1:3
	ds_read2_b32 v[108:109], v110 offset1:1
	ds_read2_b32 v[110:111], v110 offset0:2 offset1:3
	s_waitcnt lgkmcnt(14)
	v_mfma_f32_32x32x16_bf16 v[48:63], v[120:123], v[184:187], v[48:63]
	ds_read2_b32 v[112:113], v114 offset1:1
	ds_read2_b32 v[114:115], v114 offset0:2 offset1:3
	ds_read2_b32 v[116:117], v118 offset1:1
	ds_read2_b32 v[118:119], v118 offset0:2 offset1:3
	v_cmp_eq_u32_e32 vcc, v232, v227
	v_add_u32_e32 v234, -1, v234
	s_or_b64 s[88:89], vcc, s[88:89]
	v_mov_b32_e32 v232, v235
	v_mfma_f32_32x32x16_bf16 v[32:47], v[72:75], v[184:187], v[32:47]
	v_mfma_f32_32x32x16_bf16 v[16:31], v[76:79], v[184:187], v[16:31]
	v_mfma_f32_32x32x16_bf16 v[0:15], v[80:83], v[184:187], v[0:15]
	v_mfma_f32_32x32x16_bf16 v[48:63], v[132:135], v[180:183], v[48:63]
	v_mfma_f32_32x32x16_bf16 v[32:47], v[124:127], v[180:183], v[32:47]
	v_mfma_f32_32x32x16_bf16 v[16:31], v[84:87], v[180:183], v[16:31]
	v_mfma_f32_32x32x16_bf16 v[0:15], v[88:91], v[180:183], v[0:15]
	v_mfma_f32_32x32x16_bf16 v[48:63], v[128:131], v[176:179], v[48:63]
	v_mfma_f32_32x32x16_bf16 v[32:47], v[120:123], v[176:179], v[32:47]
	v_mfma_f32_32x32x16_bf16 v[16:31], v[72:75], v[176:179], v[16:31]
	v_mfma_f32_32x32x16_bf16 v[0:15], v[76:79], v[176:179], v[0:15]
	v_mfma_f32_32x32x16_bf16 v[48:63], v[140:143], v[172:175], v[48:63]
	v_mfma_f32_32x32x16_bf16 v[32:47], v[132:135], v[172:175], v[32:47]
	v_mfma_f32_32x32x16_bf16 v[16:31], v[124:127], v[172:175], v[16:31]
	v_mfma_f32_32x32x16_bf16 v[0:15], v[84:87], v[172:175], v[0:15]
	v_mfma_f32_32x32x16_bf16 v[48:63], v[144:147], v[168:171], v[48:63]
	v_mfma_f32_32x32x16_bf16 v[32:47], v[128:131], v[168:171], v[32:47]
	v_mfma_f32_32x32x16_bf16 v[16:31], v[120:123], v[168:171], v[16:31]
	v_mfma_f32_32x32x16_bf16 v[0:15], v[72:75], v[168:171], v[0:15]
	s_waitcnt lgkmcnt(14)
	v_mfma_f32_32x32x16_bf16 v[48:63], v[152:155], v[164:167], v[48:63]
	v_mov_b32_e32 v152, v84
	v_mov_b32_e32 v153, v85
	v_mov_b32_e32 v154, v86
	v_mov_b32_e32 v155, v87
	v_mfma_f32_32x32x16_bf16 v[32:47], v[140:143], v[164:167], v[32:47]
	v_mov_b32_e32 v140, v88
	v_mov_b32_e32 v141, v89
	v_mov_b32_e32 v142, v90
	v_mov_b32_e32 v143, v91
	v_mfma_f32_32x32x16_bf16 v[16:31], v[132:135], v[164:167], v[16:31]
	v_mov_b32_e32 v132, v92
	v_mov_b32_e32 v133, v93
	v_mov_b32_e32 v134, v94
	v_mov_b32_e32 v135, v95
	v_mfma_f32_32x32x16_bf16 v[0:15], v[124:127], v[164:167], v[0:15]
	s_waitcnt lgkmcnt(13)
	v_mov_b32_e32 v124, v148
	v_mov_b32_e32 v125, v149
	s_waitcnt lgkmcnt(12)
	v_mov_b32_e32 v126, v150
	v_mov_b32_e32 v127, v151
	v_mfma_f32_32x32x16_bf16 v[48:63], v[156:159], v[160:163], v[48:63]
	v_mov_b32_e32 v156, v72
	v_mov_b32_e32 v157, v73
	v_mov_b32_e32 v158, v74
	v_mov_b32_e32 v159, v75
	v_mfma_f32_32x32x16_bf16 v[32:47], v[144:147], v[160:163], v[32:47]
	v_mov_b32_e32 v144, v76
	v_mov_b32_e32 v145, v77
	v_mov_b32_e32 v146, v78
	v_mov_b32_e32 v147, v79
	v_mfma_f32_32x32x16_bf16 v[16:31], v[128:131], v[160:163], v[16:31]
	v_mov_b32_e32 v128, v80
	v_mov_b32_e32 v129, v81
	v_mov_b32_e32 v130, v82
	v_mov_b32_e32 v131, v83
	v_mfma_f32_32x32x16_bf16 v[0:15], v[120:123], v[160:163], v[0:15]
	v_mov_b32_e32 v120, v136
	v_mov_b32_e32 v121, v137
	v_mov_b32_e32 v122, v138
	v_mov_b32_e32 v123, v139
	s_andn2_b64 exec, exec, s[88:89]
	s_cbranch_execnz .LBB0_435
; #define MFMA(a, b, c) __builtin_amdgcn_mfma_f32_32x32x16_bf16((a), (b), (c), 0, 0, 0)
; DI void hy_conv(f32x16 (&acc)[4], const u16* abase, const u16* U, const u16* Zrow, int a0, int li, int g) {
;     ...
;   for (; d <= a0 + 15; ++d) {
;     hy_bfrag(bf, U, Zrow, a0, li, g, d);
;     u32x4 Wn[8];
;     const int dn = (d < a0 + 15) ? d + 1 : d;
; #pragma unroll
;     for (int x = 0; x < 8; ++x) Wn[x] = hy_afrag(abase, 8 * dn + x - 1);
; #pragma unroll
;     for (int kc = 0; kc < 8; ++kc)
; #pragma unroll
;       for (int I = 0; I < 4; ++I) acc[I] = MFMA(__builtin_bit_cast(bf16x8, W[2 * I - kc + 7]), bf[kc], acc[I]);
; #pragma unroll
;     for (int x = 0; x < 6; ++x) W[x] = W[x + 8];
; #pragma unroll
;     for (int x = 0; x < 8; ++x) W[x + 6] = Wn[x];
;   }
; DI void hyena_item(const P& p, int l, int c, char* smem) {
;     ...
;   if (cwv) hy_conv(acc, abase, U, Zrow, a0, li, g);
;   __syncthreads();
	s_or_b64 exec, exec, s[88:89]
	v_add_u32_e32 v120, v250, v223
	v_add_u32_e32 v121, v224, v120
	v_mov_b32_e32 v122, s69
	s_movk_i32 s88, 0x110
	v_mad_i32_i24 v121, v121, s88, v122
	v_mov_b32_e32 v122, s97
	v_cmp_gt_u32_e32 vcc, 64, v120
	s_movk_i32 s97, 0x110
	s_nop 0
	v_cndmask_b32_e32 v120, v122, v121, vcc
	v_add_u32_e32 v124, v120, v222
	ds_read_b128 v[120:123], v124
	s_waitcnt lgkmcnt(0)
	v_mfma_f32_32x32x16_bf16 v[48:63], v[148:151], v[120:123], v[48:63]
	v_mfma_f32_32x32x16_bf16 v[32:47], v[96:99], v[120:123], v[32:47]
	v_mfma_f32_32x32x16_bf16 v[16:31], v[108:111], v[120:123], v[16:31]
	v_mfma_f32_32x32x16_bf16 v[0:15], v[116:119], v[120:123], v[0:15]
	ds_read_b128 v[116:119], v124 offset:32
	s_waitcnt lgkmcnt(0)
	v_mfma_f32_32x32x16_bf16 v[48:63], v[136:139], v[116:119], v[48:63]
	v_mfma_f32_32x32x16_bf16 v[32:47], v[104:107], v[116:119], v[32:47]
	v_mfma_f32_32x32x16_bf16 v[16:31], v[100:103], v[116:119], v[16:31]
	v_mfma_f32_32x32x16_bf16 v[0:15], v[112:115], v[116:119], v[0:15]
	ds_read_b128 v[112:115], v124 offset:64
	s_waitcnt lgkmcnt(0)
	v_mfma_f32_32x32x16_bf16 v[48:63], v[92:95], v[112:115], v[48:63]
	v_mfma_f32_32x32x16_bf16 v[32:47], v[148:151], v[112:115], v[32:47]
	v_mfma_f32_32x32x16_bf16 v[16:31], v[96:99], v[112:115], v[16:31]
	v_mfma_f32_32x32x16_bf16 v[0:15], v[108:111], v[112:115], v[0:15]
	ds_read_b128 v[108:111], v124 offset:96
	s_waitcnt lgkmcnt(0)
	v_mfma_f32_32x32x16_bf16 v[48:63], v[80:83], v[108:111], v[48:63]
	v_mfma_f32_32x32x16_bf16 v[32:47], v[136:139], v[108:111], v[32:47]
	v_mfma_f32_32x32x16_bf16 v[16:31], v[104:107], v[108:111], v[16:31]
	v_mfma_f32_32x32x16_bf16 v[0:15], v[100:103], v[108:111], v[0:15]
	ds_read_b128 v[100:103], v124 offset:128
	s_waitcnt lgkmcnt(0)
	v_mfma_f32_32x32x16_bf16 v[48:63], v[88:91], v[100:103], v[48:63]
	v_mfma_f32_32x32x16_bf16 v[32:47], v[92:95], v[100:103], v[32:47]
	v_mfma_f32_32x32x16_bf16 v[16:31], v[148:151], v[100:103], v[16:31]
	v_mfma_f32_32x32x16_bf16 v[0:15], v[96:99], v[100:103], v[0:15]
	ds_read_b128 v[96:99], v124 offset:160
	s_waitcnt lgkmcnt(0)
	v_mfma_f32_32x32x16_bf16 v[48:63], v[76:79], v[96:99], v[48:63]
	v_mfma_f32_32x32x16_bf16 v[32:47], v[80:83], v[96:99], v[32:47]
	v_mfma_f32_32x32x16_bf16 v[16:31], v[136:139], v[96:99], v[16:31]
	v_mfma_f32_32x32x16_bf16 v[0:15], v[104:107], v[96:99], v[0:15]
	ds_read_b128 v[96:99], v124 offset:192
	s_waitcnt lgkmcnt(0)
	v_mfma_f32_32x32x16_bf16 v[48:63], v[84:87], v[96:99], v[48:63]
	ds_read_b128 v[84:87], v124 offset:224
	v_mfma_f32_32x32x16_bf16 v[32:47], v[88:91], v[96:99], v[32:47]
	v_mfma_f32_32x32x16_bf16 v[16:31], v[92:95], v[96:99], v[16:31]
	v_mfma_f32_32x32x16_bf16 v[0:15], v[148:151], v[96:99], v[0:15]
	s_waitcnt lgkmcnt(0)
	v_mfma_f32_32x32x16_bf16 v[48:63], v[72:75], v[84:87], v[48:63]
	v_mfma_f32_32x32x16_bf16 v[32:47], v[76:79], v[84:87], v[32:47]
	v_mfma_f32_32x32x16_bf16 v[16:31], v[80:83], v[84:87], v[16:31]
	v_mfma_f32_32x32x16_bf16 v[0:15], v[136:139], v[84:87], v[0:15]
.LBB0_437:
	s_or_b64 exec, exec, s[78:79]
	v_or_b32_e32 v231, v231, v223
	v_lshrrev_b32_e32 v230, 4, v230
	v_lshlrev_b32_e32 v186, 2, v188
	v_lshlrev_b32_e32 v187, 7, v231
	v_lshlrev_b32_e32 v232, 13, v230
	v_lshlrev_b32_e32 v184, 14, v230
	v_or_b32_e32 v233, v187, v186
	s_waitcnt lgkmcnt(0)
	s_barrier
	v_and_b32_e32 v249, 0xff, v198
	v_lshlrev_b32_e32 v249, 4, v249
	s_and_b64 vcc, exec, s[6:7]
	s_cbranch_vccnz .Lhy0_rd_main
	s_nop 15
	ds_write_b128 v249, v[0:3] offset:0
	ds_write_b128 v249, v[4:7] offset:4096
	ds_write_b128 v249, v[8:11] offset:8192
	ds_write_b128 v249, v[12:15] offset:12288
	ds_write_b128 v249, v[16:19] offset:16384
	ds_write_b128 v249, v[20:23] offset:20480
	ds_write_b128 v249, v[24:27] offset:24576
	ds_write_b128 v249, v[28:31] offset:28672
	ds_write_b128 v249, v[32:35] offset:32768
	ds_write_b128 v249, v[36:39] offset:36864
	ds_write_b128 v249, v[40:43] offset:40960
	ds_write_b128 v249, v[44:47] offset:45056
	ds_write_b128 v249, v[48:51] offset:49152
	ds_write_b128 v249, v[52:55] offset:53248
	ds_write_b128 v249, v[56:59] offset:57344
	ds_write_b128 v249, v[60:63] offset:61440
	s_waitcnt lgkmcnt(0)
.Lhy0_rd_main:
	s_barrier
	s_and_b64 vcc, exec, s[6:7]
	s_cbranch_vccz .Lhy0_rd_done
	ds_read_b128 v[88:91], v249 offset:0
	ds_read_b128 v[92:95], v249 offset:4096
	ds_read_b128 v[96:99], v249 offset:8192
	ds_read_b128 v[100:103], v249 offset:12288
	ds_read_b128 v[104:107], v249 offset:16384
	ds_read_b128 v[108:111], v249 offset:20480
	ds_read_b128 v[112:115], v249 offset:24576
	ds_read_b128 v[116:119], v249 offset:28672
	ds_read_b128 v[120:123], v249 offset:32768
	s_waitcnt lgkmcnt(8)
	v_add_f32_e32 v0, v0, v88
	v_add_f32_e32 v1, v1, v89
	v_add_f32_e32 v2, v2, v90
	v_add_f32_e32 v3, v3, v91
	ds_read_b128 v[124:127], v249 offset:36864
	s_waitcnt lgkmcnt(8)
	v_add_f32_e32 v4, v4, v92
	v_add_f32_e32 v5, v5, v93
	v_add_f32_e32 v6, v6, v94
	v_add_f32_e32 v7, v7, v95
	ds_read_b128 v[128:131], v249 offset:40960
	s_waitcnt lgkmcnt(8)
	v_add_f32_e32 v8, v8, v96
	v_add_f32_e32 v9, v9, v97
	v_add_f32_e32 v10, v10, v98
	v_add_f32_e32 v11, v11, v99
	ds_read_b128 v[132:135], v249 offset:45056
	s_waitcnt lgkmcnt(8)
	v_add_f32_e32 v12, v12, v100
	v_add_f32_e32 v13, v13, v101
	v_add_f32_e32 v14, v14, v102
	v_add_f32_e32 v15, v15, v103
	ds_read_b128 v[136:139], v249 offset:49152
	s_waitcnt lgkmcnt(8)
	v_add_f32_e32 v16, v16, v104
	v_add_f32_e32 v17, v17, v105
	v_add_f32_e32 v18, v18, v106
	v_add_f32_e32 v19, v19, v107
	ds_read_b128 v[140:143], v249 offset:53248
	s_waitcnt lgkmcnt(8)
	v_add_f32_e32 v20, v20, v108
	v_add_f32_e32 v21, v21, v109
	v_add_f32_e32 v22, v22, v110
	v_add_f32_e32 v23, v23, v111
	ds_read_b128 v[144:147], v249 offset:57344
	s_waitcnt lgkmcnt(8)
; DI void hyena_item(const P& p, int l, int c, char* smem) {
;     ...
;   if (cwv) {
;     const float d0 = p.fbias[(size_t)(l * 2 + 0) * 512 + c];
;     const float v0 = cw[c], v1 = cw[1536 + c], v2 = cw[3072 + c], vb = cbias[c];
;     const float x0 = cw[512 + c], x1 = cw[1536 + 512 + c], x2 = cw[3072 + 512 + c], xb = cbias[512 + c];
;     const u16* rowv = p.hyT + (size_t)c * HYP + bt * SEQ;
;     const u16* rowx = p.hyT + (size_t)(512 + c) * HYP + bt * SEQ;
; #pragma unroll
;     for (int I = 0; I < 4; ++I)
; #pragma unroll
;       for (int rq = 0; rq < 4; ++rq) {
;         const int bq = 32 * I + 8 * rq + 4 * g;
;         const int t4 = 128 * a + bq;
;         float pv[4], px[4];
;         sconv4(rowv, t4, v0, v1, v2, vb, pv);
;         sconv4(rowx, t4, x0, x1, x2, xb, px);
;         float zz[4];
; #pragma unroll
;         for (int j = 0; j < 4; ++j) zz[j] = px[j] * (acc[I][4 * rq + j] * invn0 + pv[j] * d0);
;         uint2 ov; ov.x = pack2(zz[0], zz[1]); ov.y = pack2(zz[2], zz[3]);
;         *(uint2*)(U + (bt * 64 + a) * 136 + bq) = ov;
;       }
	v_add_f32_e32 v24, v24, v112
	v_add_f32_e32 v25, v25, v113
	v_add_f32_e32 v26, v26, v114
	v_add_f32_e32 v27, v27, v115
	ds_read_b128 v[148:151], v249 offset:61440
	s_waitcnt lgkmcnt(8)
	v_add_f32_e32 v28, v28, v116
	v_add_f32_e32 v29, v29, v117
	v_add_f32_e32 v30, v30, v118
	v_add_f32_e32 v31, v31, v119
	s_waitcnt lgkmcnt(7)
	v_add_f32_e32 v32, v32, v120
	v_add_f32_e32 v33, v33, v121
	v_add_f32_e32 v34, v34, v122
	v_add_f32_e32 v35, v35, v123
	s_waitcnt lgkmcnt(6)
	v_add_f32_e32 v36, v36, v124
	v_add_f32_e32 v37, v37, v125
	v_add_f32_e32 v38, v38, v126
	v_add_f32_e32 v39, v39, v127
	s_waitcnt lgkmcnt(5)
	v_add_f32_e32 v40, v40, v128
	v_add_f32_e32 v41, v41, v129
	v_add_f32_e32 v42, v42, v130
	v_add_f32_e32 v43, v43, v131
	s_waitcnt lgkmcnt(4)
	v_add_f32_e32 v44, v44, v132
	v_add_f32_e32 v45, v45, v133
	v_add_f32_e32 v46, v46, v134
	v_add_f32_e32 v47, v47, v135
	s_waitcnt lgkmcnt(3)
	v_add_f32_e32 v48, v48, v136
	v_add_f32_e32 v49, v49, v137
	v_add_f32_e32 v50, v50, v138
	v_add_f32_e32 v51, v51, v139
	s_waitcnt lgkmcnt(2)
	v_add_f32_e32 v52, v52, v140
	v_add_f32_e32 v53, v53, v141
	v_add_f32_e32 v54, v54, v142
	v_add_f32_e32 v55, v55, v143
	s_waitcnt lgkmcnt(1)
	v_add_f32_e32 v56, v56, v144
	v_add_f32_e32 v57, v57, v145
	v_add_f32_e32 v58, v58, v146
	v_add_f32_e32 v59, v59, v147
	s_waitcnt lgkmcnt(0)
	v_add_f32_e32 v60, v60, v148
	v_add_f32_e32 v61, v61, v149
	v_add_f32_e32 v62, v62, v150
	v_add_f32_e32 v63, v63, v151
.Lhy0_rd_done:
	s_barrier
	s_and_saveexec_b64 s[78:79], s[6:7]
	s_cbranch_execz .LBB0_447
	v_readlane_b32 s88, v248, 24
	s_nop 1
	s_add_i32 s88, s72, s88
	s_mov_b32 s89, s57
	s_lshl_b64 s[88:89], s[88:89], 2
	s_add_u32 s88, s20, s88
	s_addc_u32 s89, s21, s89
	global_load_dword v239, v189, s[88:89]
	global_load_dword v240, v189, s[74:75]
	global_load_dword v241, v189, s[80:81]
	global_load_dword v242, v189, s[82:83]
	global_load_dword v243, v189, s[84:85]
	global_load_dword v247, v189, s[84:85] offset:2048
	global_load_dword v244, v189, s[74:75] offset:2048
	global_load_dword v245, v204, s[74:75]
	global_load_dword v246, v205, s[74:75] offset:2048
	s_add_u32 s100, s86, -4
	s_addc_u32 s101, s87, -1
	s_or_b32 s98, s72, 0x200
	s_mul_hi_u32 s99, s98, 0x8080
	s_mul_i32 s98, s98, 0x8080
	s_add_u32 s98, s36, s98
	s_addc_u32 s99, s37, s99
	s_add_u32 s98, s98, -4
	s_addc_u32 s99, s99, -1
	v_lshl_add_u32 v234, v233, 1, v184
	global_load_dwordx4 v[72:75], v234, s[100:101] offset:0
	global_load_dwordx4 v[76:79], v234, s[98:99] offset:0
	global_load_dwordx4 v[80:83], v234, s[100:101] offset:16
	global_load_dwordx4 v[84:87], v234, s[98:99] offset:16
	global_load_dwordx4 v[88:91], v234, s[100:101] offset:32
	global_load_dwordx4 v[92:95], v234, s[98:99] offset:32
	global_load_dwordx4 v[96:99], v234, s[100:101] offset:48
	global_load_dwordx4 v[100:103], v234, s[98:99] offset:48
	global_load_dwordx4 v[104:107], v234, s[100:101] offset:64
	global_load_dwordx4 v[108:111], v234, s[98:99] offset:64
	global_load_dwordx4 v[112:115], v234, s[100:101] offset:80
	global_load_dwordx4 v[116:119], v234, s[98:99] offset:80
	global_load_dwordx4 v[120:123], v234, s[100:101] offset:96
	global_load_dwordx4 v[124:127], v234, s[98:99] offset:96
	global_load_dwordx4 v[128:131], v234, s[100:101] offset:112
	global_load_dwordx4 v[132:135], v234, s[98:99] offset:112
	v_add_f32_e32 v238, v68, v69
	v_add_f32_e32 v238, v238, v70
	v_add_f32_e32 v238, v238, v71
	v_div_scale_f32 v169, s[88:89], v238, v238, 1.0
	v_rcp_f32_e32 v170, v169
	s_nop 0
	v_fma_f32 v171, -v169, v170, 1.0
	v_fmac_f32_e32 v170, v171, v170
	v_div_scale_f32 v171, vcc, 1.0, v238, 1.0
	v_mul_f32_e32 v236, v171, v170
	v_fma_f32 v237, -v169, v236, v171
	v_fmac_f32_e32 v236, v237, v170
	v_fma_f32 v169, -v169, v236, v171
	v_div_fmas_f32 v169, v169, v170, v236
	v_div_fixup_f32 v238, v169, v238, 1.0
	v_lshl_or_b32 v235, v230, 6, v231
	v_mul_u32_u24_e32 v235, 0x110, v235
	v_lshlrev_b32_e32 v236, 1, v186
	v_add3_u32 v235, s69, v235, v236
	s_waitcnt vmcnt(8)
	v_cmp_ne_u32_e32 vcc, 0, v233
	s_nop 1
	v_and_b32_e32 v168, 0xffff0000, v72
	v_cndmask_b32_e32 v168, 0, v168, vcc
	v_lshlrev_b32_e32 v169, 16, v73
	v_and_b32_e32 v170, 0xffff0000, v73
	v_lshlrev_b32_e32 v171, 16, v74
	v_and_b32_e32 v172, 0xffff0000, v74
	v_lshlrev_b32_e32 v173, 16, v75
	v_mul_f32_e32 v174, v240, v168
	v_fmac_f32_e32 v174, v241, v169
	v_fmac_f32_e32 v174, v242, v170
	v_add_f32_e32 v174, v243, v174
	v_mul_f32_e32 v175, v240, v169
	v_fmac_f32_e32 v175, v241, v170
	v_fmac_f32_e32 v175, v242, v171
	v_add_f32_e32 v175, v243, v175
	v_mul_f32_e32 v176, v240, v170
	v_fmac_f32_e32 v176, v241, v171
	v_fmac_f32_e32 v176, v242, v172
	v_add_f32_e32 v176, v243, v176
	v_mul_f32_e32 v177, v240, v171
	v_fmac_f32_e32 v177, v241, v172
	v_fmac_f32_e32 v177, v242, v173
	v_add_f32_e32 v177, v243, v177
	v_mul_f32_e32 v174, v239, v174
	v_mul_f32_e32 v175, v239, v175
	v_mul_f32_e32 v176, v239, v176
	v_mul_f32_e32 v177, v239, v177
	v_fmac_f32_e32 v174, v238, v48
	v_fmac_f32_e32 v175, v238, v49
	v_fmac_f32_e32 v176, v238, v50
	v_fmac_f32_e32 v177, v238, v51
	v_and_b32_e32 v168, 0xffff0000, v76
	v_cndmask_b32_e32 v168, 0, v168, vcc
	v_lshlrev_b32_e32 v169, 16, v77
	v_and_b32_e32 v170, 0xffff0000, v77
	v_lshlrev_b32_e32 v171, 16, v78
	v_and_b32_e32 v172, 0xffff0000, v78
	v_lshlrev_b32_e32 v173, 16, v79
	v_mul_f32_e32 v178, v244, v168
	v_fmac_f32_e32 v178, v245, v169
	v_fmac_f32_e32 v178, v246, v170
	v_add_f32_e32 v178, v247, v178
	v_mul_f32_e32 v179, v244, v169
	v_fmac_f32_e32 v179, v245, v170
	v_fmac_f32_e32 v179, v246, v171
	v_add_f32_e32 v179, v247, v179
	v_mul_f32_e32 v180, v244, v170
	v_fmac_f32_e32 v180, v245, v171
	v_fmac_f32_e32 v180, v246, v172
; DI void hyena_item(const P& p, int l, int c, char* smem) {
;     ...
; #pragma unroll
;     for (int I = 0; I < 4; ++I)
; #pragma unroll
;       for (int rq = 0; rq < 4; ++rq) {
;         const int bq = 32 * I + 8 * rq + 4 * g;
;         const int t4 = 128 * a + bq;
;         float pv[4], px[4];
;         sconv4(rowv, t4, v0, v1, v2, vb, pv);
;         sconv4(rowx, t4, x0, x1, x2, xb, px);
;         float zz[4];
; #pragma unroll
;         for (int j = 0; j < 4; ++j) zz[j] = px[j] * (acc[I][4 * rq + j] * invn0 + pv[j] * d0);
;         uint2 ov; ov.x = pack2(zz[0], zz[1]); ov.y = pack2(zz[2], zz[3]);
;         *(uint2*)(U + (bt * 64 + a) * 136 + bq) = ov;
;       }
	v_add_f32_e32 v180, v247, v180
	v_mul_f32_e32 v181, v244, v171
	v_fmac_f32_e32 v181, v245, v172
	v_fmac_f32_e32 v181, v246, v173
	v_add_f32_e32 v181, v247, v181
	v_mul_f32_e32 v174, v174, v178
	v_mul_f32_e32 v175, v175, v179
	v_mul_f32_e32 v176, v176, v180
	v_mul_f32_e32 v177, v177, v181
	v_cvt_pk_bf16_f32 v182, v174, v175
	v_cvt_pk_bf16_f32 v183, v176, v177
	ds_write_b64 v235, v[182:183] offset:0
	v_and_b32_e32 v168, 0xffff0000, v80
	v_lshlrev_b32_e32 v169, 16, v81
	v_and_b32_e32 v170, 0xffff0000, v81
	v_lshlrev_b32_e32 v171, 16, v82
	v_and_b32_e32 v172, 0xffff0000, v82
	v_lshlrev_b32_e32 v173, 16, v83
	v_mul_f32_e32 v174, v240, v168
	v_fmac_f32_e32 v174, v241, v169
	v_fmac_f32_e32 v174, v242, v170
	v_add_f32_e32 v174, v243, v174
	v_mul_f32_e32 v175, v240, v169
	v_fmac_f32_e32 v175, v241, v170
	v_fmac_f32_e32 v175, v242, v171
	v_add_f32_e32 v175, v243, v175
	v_mul_f32_e32 v176, v240, v170
	v_fmac_f32_e32 v176, v241, v171
	v_fmac_f32_e32 v176, v242, v172
	v_add_f32_e32 v176, v243, v176
	v_mul_f32_e32 v177, v240, v171
	v_fmac_f32_e32 v177, v241, v172
	v_fmac_f32_e32 v177, v242, v173
	v_add_f32_e32 v177, v243, v177
	v_mul_f32_e32 v174, v239, v174
	v_mul_f32_e32 v175, v239, v175
	v_mul_f32_e32 v176, v239, v176
	v_mul_f32_e32 v177, v239, v177
	v_fmac_f32_e32 v174, v238, v52
	v_fmac_f32_e32 v175, v238, v53
	v_fmac_f32_e32 v176, v238, v54
	v_fmac_f32_e32 v177, v238, v55
	v_and_b32_e32 v168, 0xffff0000, v84
	v_lshlrev_b32_e32 v169, 16, v85
	v_and_b32_e32 v170, 0xffff0000, v85
	v_lshlrev_b32_e32 v171, 16, v86
	v_and_b32_e32 v172, 0xffff0000, v86
	v_lshlrev_b32_e32 v173, 16, v87
	v_mul_f32_e32 v178, v244, v168
	v_fmac_f32_e32 v178, v245, v169
	v_fmac_f32_e32 v178, v246, v170
	v_add_f32_e32 v178, v247, v178
	v_mul_f32_e32 v179, v244, v169
	v_fmac_f32_e32 v179, v245, v170
	v_fmac_f32_e32 v179, v246, v171
	v_add_f32_e32 v179, v247, v179
	v_mul_f32_e32 v180, v244, v170
	v_fmac_f32_e32 v180, v245, v171
	v_fmac_f32_e32 v180, v246, v172
	v_add_f32_e32 v180, v247, v180
	v_mul_f32_e32 v181, v244, v171
	v_fmac_f32_e32 v181, v245, v172
	v_fmac_f32_e32 v181, v246, v173
	v_add_f32_e32 v181, v247, v181
	v_mul_f32_e32 v174, v174, v178
	v_mul_f32_e32 v175, v175, v179
	v_mul_f32_e32 v176, v176, v180
	v_mul_f32_e32 v177, v177, v181
	v_cvt_pk_bf16_f32 v182, v174, v175
	v_cvt_pk_bf16_f32 v183, v176, v177
	ds_write_b64 v235, v[182:183] offset:16
	v_and_b32_e32 v168, 0xffff0000, v88
	v_lshlrev_b32_e32 v169, 16, v89
	v_and_b32_e32 v170, 0xffff0000, v89
	v_lshlrev_b32_e32 v171, 16, v90
	v_and_b32_e32 v172, 0xffff0000, v90
	v_lshlrev_b32_e32 v173, 16, v91
	v_mul_f32_e32 v174, v240, v168
	v_fmac_f32_e32 v174, v241, v169
	v_fmac_f32_e32 v174, v242, v170
	v_add_f32_e32 v174, v243, v174
	v_mul_f32_e32 v175, v240, v169
	v_fmac_f32_e32 v175, v241, v170
	v_fmac_f32_e32 v175, v242, v171
	v_add_f32_e32 v175, v243, v175
	v_mul_f32_e32 v176, v240, v170
	v_fmac_f32_e32 v176, v241, v171
	v_fmac_f32_e32 v176, v242, v172
	v_add_f32_e32 v176, v243, v176
	v_mul_f32_e32 v177, v240, v171
	v_fmac_f32_e32 v177, v241, v172
	v_fmac_f32_e32 v177, v242, v173
	v_add_f32_e32 v177, v243, v177
	v_mul_f32_e32 v174, v239, v174
	v_mul_f32_e32 v175, v239, v175
	v_mul_f32_e32 v176, v239, v176
	v_mul_f32_e32 v177, v239, v177
	v_fmac_f32_e32 v174, v238, v56
	v_fmac_f32_e32 v175, v238, v57
	v_fmac_f32_e32 v176, v238, v58
	v_fmac_f32_e32 v177, v238, v59
	v_and_b32_e32 v168, 0xffff0000, v92
	v_lshlrev_b32_e32 v169, 16, v93
	v_and_b32_e32 v170, 0xffff0000, v93
	v_lshlrev_b32_e32 v171, 16, v94
	v_and_b32_e32 v172, 0xffff0000, v94
	v_lshlrev_b32_e32 v173, 16, v95
	v_mul_f32_e32 v178, v244, v168
	v_fmac_f32_e32 v178, v245, v169
	v_fmac_f32_e32 v178, v246, v170
	v_add_f32_e32 v178, v247, v178
	v_mul_f32_e32 v179, v244, v169
	v_fmac_f32_e32 v179, v245, v170
	v_fmac_f32_e32 v179, v246, v171
	v_add_f32_e32 v179, v247, v179
	v_mul_f32_e32 v180, v244, v170
	v_fmac_f32_e32 v180, v245, v171
	v_fmac_f32_e32 v180, v246, v172
	v_add_f32_e32 v180, v247, v180
	v_mul_f32_e32 v181, v244, v171
	v_fmac_f32_e32 v181, v245, v172
	v_fmac_f32_e32 v181, v246, v173
	v_add_f32_e32 v181, v247, v181
	v_mul_f32_e32 v174, v174, v178
	v_mul_f32_e32 v175, v175, v179
	v_mul_f32_e32 v176, v176, v180
	v_mul_f32_e32 v177, v177, v181
	v_cvt_pk_bf16_f32 v182, v174, v175
	v_cvt_pk_bf16_f32 v183, v176, v177
	ds_write_b64 v235, v[182:183] offset:32
	v_and_b32_e32 v168, 0xffff0000, v96
	v_lshlrev_b32_e32 v169, 16, v97
	v_and_b32_e32 v170, 0xffff0000, v97
	v_lshlrev_b32_e32 v171, 16, v98
	v_and_b32_e32 v172, 0xffff0000, v98
	v_lshlrev_b32_e32 v173, 16, v99
	v_mul_f32_e32 v174, v240, v168
	v_fmac_f32_e32 v174, v241, v169
	v_fmac_f32_e32 v174, v242, v170
	v_add_f32_e32 v174, v243, v174
	v_mul_f32_e32 v175, v240, v169
	v_fmac_f32_e32 v175, v241, v170
	v_fmac_f32_e32 v175, v242, v171
	v_add_f32_e32 v175, v243, v175
	v_mul_f32_e32 v176, v240, v170
	v_fmac_f32_e32 v176, v241, v171
	v_fmac_f32_e32 v176, v242, v172
	v_add_f32_e32 v176, v243, v176
	v_mul_f32_e32 v177, v240, v171
	v_fmac_f32_e32 v177, v241, v172
	v_fmac_f32_e32 v177, v242, v173
	v_add_f32_e32 v177, v243, v177
	v_mul_f32_e32 v174, v239, v174
	v_mul_f32_e32 v175, v239, v175
	v_mul_f32_e32 v176, v239, v176
	v_mul_f32_e32 v177, v239, v177
	v_fmac_f32_e32 v174, v238, v60
	v_fmac_f32_e32 v175, v238, v61
	v_fmac_f32_e32 v176, v238, v62
	v_fmac_f32_e32 v177, v238, v63
	v_and_b32_e32 v168, 0xffff0000, v100
	v_lshlrev_b32_e32 v169, 16, v101
	v_and_b32_e32 v170, 0xffff0000, v101
	v_lshlrev_b32_e32 v171, 16, v102
	v_and_b32_e32 v172, 0xffff0000, v102
	v_lshlrev_b32_e32 v173, 16, v103
	v_mul_f32_e32 v178, v244, v168
	v_fmac_f32_e32 v178, v245, v169
	v_fmac_f32_e32 v178, v246, v170
	v_add_f32_e32 v178, v247, v178
	v_mul_f32_e32 v179, v244, v169
	v_fmac_f32_e32 v179, v245, v170
	v_fmac_f32_e32 v179, v246, v171
	v_add_f32_e32 v179, v247, v179
	v_mul_f32_e32 v180, v244, v170
	v_fmac_f32_e32 v180, v245, v171
	v_fmac_f32_e32 v180, v246, v172
	v_add_f32_e32 v180, v247, v180
	v_mul_f32_e32 v181, v244, v171
	v_fmac_f32_e32 v181, v245, v172
	v_fmac_f32_e32 v181, v246, v173
	v_add_f32_e32 v181, v247, v181
	v_mul_f32_e32 v174, v174, v178
	v_mul_f32_e32 v175, v175, v179
	v_mul_f32_e32 v176, v176, v180
	v_mul_f32_e32 v177, v177, v181
	v_cvt_pk_bf16_f32 v182, v174, v175
	v_cvt_pk_bf16_f32 v183, v176, v177
	ds_write_b64 v235, v[182:183] offset:48
	global_load_dwordx4 v[136:139], v234, s[100:101] offset:128
	global_load_dwordx4 v[140:143], v234, s[98:99] offset:128
	global_load_dwordx4 v[144:147], v234, s[100:101] offset:144
	global_load_dwordx4 v[148:151], v234, s[98:99] offset:144
	global_load_dwordx4 v[152:155], v234, s[100:101] offset:160
	global_load_dwordx4 v[156:159], v234, s[98:99] offset:160
	global_load_dwordx4 v[160:163], v234, s[100:101] offset:176
	global_load_dwordx4 v[164:167], v234, s[98:99] offset:176
	s_waitcnt vmcnt(8)
; DI void hyena_item(const P& p, int l, int c, char* smem) {
;     ...
; #pragma unroll
;     for (int I = 0; I < 4; ++I)
; #pragma unroll
;       for (int rq = 0; rq < 4; ++rq) {
;         const int bq = 32 * I + 8 * rq + 4 * g;
;         const int t4 = 128 * a + bq;
;         float pv[4], px[4];
;         sconv4(rowv, t4, v0, v1, v2, vb, pv);
;         sconv4(rowx, t4, x0, x1, x2, xb, px);
;         float zz[4];
; #pragma unroll
;         for (int j = 0; j < 4; ++j) zz[j] = px[j] * (acc[I][4 * rq + j] * invn0 + pv[j] * d0);
;         uint2 ov; ov.x = pack2(zz[0], zz[1]); ov.y = pack2(zz[2], zz[3]);
;         *(uint2*)(U + (bt * 64 + a) * 136 + bq) = ov;
;       }
	v_and_b32_e32 v168, 0xffff0000, v104
	v_lshlrev_b32_e32 v169, 16, v105
	v_and_b32_e32 v170, 0xffff0000, v105
	v_lshlrev_b32_e32 v171, 16, v106
	v_and_b32_e32 v172, 0xffff0000, v106
	v_lshlrev_b32_e32 v173, 16, v107
	v_mul_f32_e32 v174, v240, v168
	v_fmac_f32_e32 v174, v241, v169
	v_fmac_f32_e32 v174, v242, v170
	v_add_f32_e32 v174, v243, v174
	v_mul_f32_e32 v175, v240, v169
	v_fmac_f32_e32 v175, v241, v170
	v_fmac_f32_e32 v175, v242, v171
	v_add_f32_e32 v175, v243, v175
	v_mul_f32_e32 v176, v240, v170
	v_fmac_f32_e32 v176, v241, v171
	v_fmac_f32_e32 v176, v242, v172
	v_add_f32_e32 v176, v243, v176
	v_mul_f32_e32 v177, v240, v171
	v_fmac_f32_e32 v177, v241, v172
	v_fmac_f32_e32 v177, v242, v173
	v_add_f32_e32 v177, v243, v177
	v_mul_f32_e32 v174, v239, v174
	v_mul_f32_e32 v175, v239, v175
	v_mul_f32_e32 v176, v239, v176
	v_mul_f32_e32 v177, v239, v177
	v_fmac_f32_e32 v174, v238, v32
	v_fmac_f32_e32 v175, v238, v33
	v_fmac_f32_e32 v176, v238, v34
	v_fmac_f32_e32 v177, v238, v35
	v_and_b32_e32 v168, 0xffff0000, v108
	v_lshlrev_b32_e32 v169, 16, v109
	v_and_b32_e32 v170, 0xffff0000, v109
	v_lshlrev_b32_e32 v171, 16, v110
	v_and_b32_e32 v172, 0xffff0000, v110
	v_lshlrev_b32_e32 v173, 16, v111
	v_mul_f32_e32 v178, v244, v168
	v_fmac_f32_e32 v178, v245, v169
	v_fmac_f32_e32 v178, v246, v170
	v_add_f32_e32 v178, v247, v178
	v_mul_f32_e32 v179, v244, v169
	v_fmac_f32_e32 v179, v245, v170
	v_fmac_f32_e32 v179, v246, v171
	v_add_f32_e32 v179, v247, v179
	v_mul_f32_e32 v180, v244, v170
	v_fmac_f32_e32 v180, v245, v171
	v_fmac_f32_e32 v180, v246, v172
	v_add_f32_e32 v180, v247, v180
	v_mul_f32_e32 v181, v244, v171
	v_fmac_f32_e32 v181, v245, v172
	v_fmac_f32_e32 v181, v246, v173
	v_add_f32_e32 v181, v247, v181
	v_mul_f32_e32 v174, v174, v178
	v_mul_f32_e32 v175, v175, v179
	v_mul_f32_e32 v176, v176, v180
	v_mul_f32_e32 v177, v177, v181
	v_cvt_pk_bf16_f32 v182, v174, v175
	v_cvt_pk_bf16_f32 v183, v176, v177
	ds_write_b64 v235, v[182:183] offset:64
	v_and_b32_e32 v168, 0xffff0000, v112
	v_lshlrev_b32_e32 v169, 16, v113
	v_and_b32_e32 v170, 0xffff0000, v113
	v_lshlrev_b32_e32 v171, 16, v114
	v_and_b32_e32 v172, 0xffff0000, v114
	v_lshlrev_b32_e32 v173, 16, v115
	v_mul_f32_e32 v174, v240, v168
	v_fmac_f32_e32 v174, v241, v169
	v_fmac_f32_e32 v174, v242, v170
	v_add_f32_e32 v174, v243, v174
	v_mul_f32_e32 v175, v240, v169
	v_fmac_f32_e32 v175, v241, v170
	v_fmac_f32_e32 v175, v242, v171
	v_add_f32_e32 v175, v243, v175
	v_mul_f32_e32 v176, v240, v170
	v_fmac_f32_e32 v176, v241, v171
	v_fmac_f32_e32 v176, v242, v172
	v_add_f32_e32 v176, v243, v176
	v_mul_f32_e32 v177, v240, v171
	v_fmac_f32_e32 v177, v241, v172
	v_fmac_f32_e32 v177, v242, v173
	v_add_f32_e32 v177, v243, v177
	v_mul_f32_e32 v174, v239, v174
	v_mul_f32_e32 v175, v239, v175
	v_mul_f32_e32 v176, v239, v176
	v_mul_f32_e32 v177, v239, v177
	v_fmac_f32_e32 v174, v238, v36
	v_fmac_f32_e32 v175, v238, v37
	v_fmac_f32_e32 v176, v238, v38
	v_fmac_f32_e32 v177, v238, v39
	v_and_b32_e32 v168, 0xffff0000, v116
	v_lshlrev_b32_e32 v169, 16, v117
	v_and_b32_e32 v170, 0xffff0000, v117
	v_lshlrev_b32_e32 v171, 16, v118
	v_and_b32_e32 v172, 0xffff0000, v118
	v_lshlrev_b32_e32 v173, 16, v119
	v_mul_f32_e32 v178, v244, v168
	v_fmac_f32_e32 v178, v245, v169
	v_fmac_f32_e32 v178, v246, v170
	v_add_f32_e32 v178, v247, v178
	v_mul_f32_e32 v179, v244, v169
	v_fmac_f32_e32 v179, v245, v170
	v_fmac_f32_e32 v179, v246, v171
	v_add_f32_e32 v179, v247, v179
	v_mul_f32_e32 v180, v244, v170
	v_fmac_f32_e32 v180, v245, v171
	v_fmac_f32_e32 v180, v246, v172
	v_add_f32_e32 v180, v247, v180
	v_mul_f32_e32 v181, v244, v171
	v_fmac_f32_e32 v181, v245, v172
	v_fmac_f32_e32 v181, v246, v173
	v_add_f32_e32 v181, v247, v181
	v_mul_f32_e32 v174, v174, v178
	v_mul_f32_e32 v175, v175, v179
	v_mul_f32_e32 v176, v176, v180
	v_mul_f32_e32 v177, v177, v181
	v_cvt_pk_bf16_f32 v182, v174, v175
	v_cvt_pk_bf16_f32 v183, v176, v177
	ds_write_b64 v235, v[182:183] offset:80
	v_and_b32_e32 v168, 0xffff0000, v120
	v_lshlrev_b32_e32 v169, 16, v121
	v_and_b32_e32 v170, 0xffff0000, v121
	v_lshlrev_b32_e32 v171, 16, v122
	v_and_b32_e32 v172, 0xffff0000, v122
	v_lshlrev_b32_e32 v173, 16, v123
	v_mul_f32_e32 v174, v240, v168
	v_fmac_f32_e32 v174, v241, v169
	v_fmac_f32_e32 v174, v242, v170
	v_add_f32_e32 v174, v243, v174
	v_mul_f32_e32 v175, v240, v169
	v_fmac_f32_e32 v175, v241, v170
	v_fmac_f32_e32 v175, v242, v171
	v_add_f32_e32 v175, v243, v175
	v_mul_f32_e32 v176, v240, v170
	v_fmac_f32_e32 v176, v241, v171
	v_fmac_f32_e32 v176, v242, v172
	v_add_f32_e32 v176, v243, v176
	v_mul_f32_e32 v177, v240, v171
	v_fmac_f32_e32 v177, v241, v172
	v_fmac_f32_e32 v177, v242, v173
	v_add_f32_e32 v177, v243, v177
	v_mul_f32_e32 v174, v239, v174
	v_mul_f32_e32 v175, v239, v175
	v_mul_f32_e32 v176, v239, v176
	v_mul_f32_e32 v177, v239, v177
	v_fmac_f32_e32 v174, v238, v40
	v_fmac_f32_e32 v175, v238, v41
	v_fmac_f32_e32 v176, v238, v42
	v_fmac_f32_e32 v177, v238, v43
	v_and_b32_e32 v168, 0xffff0000, v124
	v_lshlrev_b32_e32 v169, 16, v125
	v_and_b32_e32 v170, 0xffff0000, v125
	v_lshlrev_b32_e32 v171, 16, v126
	v_and_b32_e32 v172, 0xffff0000, v126
	v_lshlrev_b32_e32 v173, 16, v127
	v_mul_f32_e32 v178, v244, v168
	v_fmac_f32_e32 v178, v245, v169
	v_fmac_f32_e32 v178, v246, v170
	v_add_f32_e32 v178, v247, v178
	v_mul_f32_e32 v179, v244, v169
	v_fmac_f32_e32 v179, v245, v170
	v_fmac_f32_e32 v179, v246, v171
	v_add_f32_e32 v179, v247, v179
	v_mul_f32_e32 v180, v244, v170
	v_fmac_f32_e32 v180, v245, v171
	v_fmac_f32_e32 v180, v246, v172
	v_add_f32_e32 v180, v247, v180
	v_mul_f32_e32 v181, v244, v171
	v_fmac_f32_e32 v181, v245, v172
	v_fmac_f32_e32 v181, v246, v173
; DI void hyena_item(const P& p, int l, int c, char* smem) {
;     ...
; #pragma unroll
;     for (int I = 0; I < 4; ++I)
; #pragma unroll
;       for (int rq = 0; rq < 4; ++rq) {
;         const int bq = 32 * I + 8 * rq + 4 * g;
;         const int t4 = 128 * a + bq;
;         float pv[4], px[4];
;         sconv4(rowv, t4, v0, v1, v2, vb, pv);
;         sconv4(rowx, t4, x0, x1, x2, xb, px);
;         float zz[4];
; #pragma unroll
;         for (int j = 0; j < 4; ++j) zz[j] = px[j] * (acc[I][4 * rq + j] * invn0 + pv[j] * d0);
;         uint2 ov; ov.x = pack2(zz[0], zz[1]); ov.y = pack2(zz[2], zz[3]);
;         *(uint2*)(U + (bt * 64 + a) * 136 + bq) = ov;
;       }
	v_add_f32_e32 v181, v247, v181
	v_mul_f32_e32 v174, v174, v178
	v_mul_f32_e32 v175, v175, v179
	v_mul_f32_e32 v176, v176, v180
	v_mul_f32_e32 v177, v177, v181
	v_cvt_pk_bf16_f32 v182, v174, v175
	v_cvt_pk_bf16_f32 v183, v176, v177
	ds_write_b64 v235, v[182:183] offset:96
	v_and_b32_e32 v168, 0xffff0000, v128
	v_lshlrev_b32_e32 v169, 16, v129
	v_and_b32_e32 v170, 0xffff0000, v129
	v_lshlrev_b32_e32 v171, 16, v130
	v_and_b32_e32 v172, 0xffff0000, v130
	v_lshlrev_b32_e32 v173, 16, v131
	v_mul_f32_e32 v174, v240, v168
	v_fmac_f32_e32 v174, v241, v169
	v_fmac_f32_e32 v174, v242, v170
	v_add_f32_e32 v174, v243, v174
	v_mul_f32_e32 v175, v240, v169
	v_fmac_f32_e32 v175, v241, v170
	v_fmac_f32_e32 v175, v242, v171
	v_add_f32_e32 v175, v243, v175
	v_mul_f32_e32 v176, v240, v170
	v_fmac_f32_e32 v176, v241, v171
	v_fmac_f32_e32 v176, v242, v172
	v_add_f32_e32 v176, v243, v176
	v_mul_f32_e32 v177, v240, v171
	v_fmac_f32_e32 v177, v241, v172
	v_fmac_f32_e32 v177, v242, v173
	v_add_f32_e32 v177, v243, v177
	v_mul_f32_e32 v174, v239, v174
	v_mul_f32_e32 v175, v239, v175
	v_mul_f32_e32 v176, v239, v176
	v_mul_f32_e32 v177, v239, v177
	v_fmac_f32_e32 v174, v238, v44
	v_fmac_f32_e32 v175, v238, v45
	v_fmac_f32_e32 v176, v238, v46
	v_fmac_f32_e32 v177, v238, v47
	v_and_b32_e32 v168, 0xffff0000, v132
	v_lshlrev_b32_e32 v169, 16, v133
	v_and_b32_e32 v170, 0xffff0000, v133
	v_lshlrev_b32_e32 v171, 16, v134
	v_and_b32_e32 v172, 0xffff0000, v134
	v_lshlrev_b32_e32 v173, 16, v135
	v_mul_f32_e32 v178, v244, v168
	v_fmac_f32_e32 v178, v245, v169
	v_fmac_f32_e32 v178, v246, v170
	v_add_f32_e32 v178, v247, v178
	v_mul_f32_e32 v179, v244, v169
	v_fmac_f32_e32 v179, v245, v170
	v_fmac_f32_e32 v179, v246, v171
	v_add_f32_e32 v179, v247, v179
	v_mul_f32_e32 v180, v244, v170
	v_fmac_f32_e32 v180, v245, v171
	v_fmac_f32_e32 v180, v246, v172
	v_add_f32_e32 v180, v247, v180
	v_mul_f32_e32 v181, v244, v171
	v_fmac_f32_e32 v181, v245, v172
	v_fmac_f32_e32 v181, v246, v173
	v_add_f32_e32 v181, v247, v181
	v_mul_f32_e32 v174, v174, v178
	v_mul_f32_e32 v175, v175, v179
	v_mul_f32_e32 v176, v176, v180
	v_mul_f32_e32 v177, v177, v181
	v_cvt_pk_bf16_f32 v182, v174, v175
	v_cvt_pk_bf16_f32 v183, v176, v177
	ds_write_b64 v235, v[182:183] offset:112
	global_load_dwordx4 v[72:75], v234, s[100:101] offset:192
	global_load_dwordx4 v[76:79], v234, s[98:99] offset:192
	global_load_dwordx4 v[80:83], v234, s[100:101] offset:208
	global_load_dwordx4 v[84:87], v234, s[98:99] offset:208
	global_load_dwordx4 v[88:91], v234, s[100:101] offset:224
	global_load_dwordx4 v[92:95], v234, s[98:99] offset:224
	global_load_dwordx4 v[96:99], v234, s[100:101] offset:240
	global_load_dwordx4 v[100:103], v234, s[98:99] offset:240
	s_waitcnt vmcnt(8)
	v_and_b32_e32 v168, 0xffff0000, v136
	v_lshlrev_b32_e32 v169, 16, v137
	v_and_b32_e32 v170, 0xffff0000, v137
	v_lshlrev_b32_e32 v171, 16, v138
	v_and_b32_e32 v172, 0xffff0000, v138
	v_lshlrev_b32_e32 v173, 16, v139
	v_mul_f32_e32 v174, v240, v168
	v_fmac_f32_e32 v174, v241, v169
	v_fmac_f32_e32 v174, v242, v170
	v_add_f32_e32 v174, v243, v174
	v_mul_f32_e32 v175, v240, v169
	v_fmac_f32_e32 v175, v241, v170
	v_fmac_f32_e32 v175, v242, v171
	v_add_f32_e32 v175, v243, v175
	v_mul_f32_e32 v176, v240, v170
	v_fmac_f32_e32 v176, v241, v171
	v_fmac_f32_e32 v176, v242, v172
	v_add_f32_e32 v176, v243, v176
	v_mul_f32_e32 v177, v240, v171
	v_fmac_f32_e32 v177, v241, v172
	v_fmac_f32_e32 v177, v242, v173
	v_add_f32_e32 v177, v243, v177
	v_mul_f32_e32 v174, v239, v174
	v_mul_f32_e32 v175, v239, v175
	v_mul_f32_e32 v176, v239, v176
	v_mul_f32_e32 v177, v239, v177
	v_fmac_f32_e32 v174, v238, v16
	v_fmac_f32_e32 v175, v238, v17
	v_fmac_f32_e32 v176, v238, v18
	v_fmac_f32_e32 v177, v238, v19
	v_and_b32_e32 v168, 0xffff0000, v140
	v_lshlrev_b32_e32 v169, 16, v141
	v_and_b32_e32 v170, 0xffff0000, v141
	v_lshlrev_b32_e32 v171, 16, v142
	v_and_b32_e32 v172, 0xffff0000, v142
	v_lshlrev_b32_e32 v173, 16, v143
	v_mul_f32_e32 v178, v244, v168
	v_fmac_f32_e32 v178, v245, v169
	v_fmac_f32_e32 v178, v246, v170
	v_add_f32_e32 v178, v247, v178
	v_mul_f32_e32 v179, v244, v169
	v_fmac_f32_e32 v179, v245, v170
	v_fmac_f32_e32 v179, v246, v171
	v_add_f32_e32 v179, v247, v179
	v_mul_f32_e32 v180, v244, v170
	v_fmac_f32_e32 v180, v245, v171
	v_fmac_f32_e32 v180, v246, v172
	v_add_f32_e32 v180, v247, v180
	v_mul_f32_e32 v181, v244, v171
	v_fmac_f32_e32 v181, v245, v172
	v_fmac_f32_e32 v181, v246, v173
	v_add_f32_e32 v181, v247, v181
	v_mul_f32_e32 v174, v174, v178
	v_mul_f32_e32 v175, v175, v179
	v_mul_f32_e32 v176, v176, v180
	v_mul_f32_e32 v177, v177, v181
	v_cvt_pk_bf16_f32 v182, v174, v175
	v_cvt_pk_bf16_f32 v183, v176, v177
	ds_write_b64 v235, v[182:183] offset:128
	v_and_b32_e32 v168, 0xffff0000, v144
	v_lshlrev_b32_e32 v169, 16, v145
	v_and_b32_e32 v170, 0xffff0000, v145
	v_lshlrev_b32_e32 v171, 16, v146
	v_and_b32_e32 v172, 0xffff0000, v146
	v_lshlrev_b32_e32 v173, 16, v147
	v_mul_f32_e32 v174, v240, v168
	v_fmac_f32_e32 v174, v241, v169
	v_fmac_f32_e32 v174, v242, v170
	v_add_f32_e32 v174, v243, v174
	v_mul_f32_e32 v175, v240, v169
	v_fmac_f32_e32 v175, v241, v170
	v_fmac_f32_e32 v175, v242, v171
	v_add_f32_e32 v175, v243, v175
	v_mul_f32_e32 v176, v240, v170
	v_fmac_f32_e32 v176, v241, v171
	v_fmac_f32_e32 v176, v242, v172
	v_add_f32_e32 v176, v243, v176
	v_mul_f32_e32 v177, v240, v171
	v_fmac_f32_e32 v177, v241, v172
	v_fmac_f32_e32 v177, v242, v173
	v_add_f32_e32 v177, v243, v177
	v_mul_f32_e32 v174, v239, v174
	v_mul_f32_e32 v175, v239, v175
	v_mul_f32_e32 v176, v239, v176
	v_mul_f32_e32 v177, v239, v177
	v_fmac_f32_e32 v174, v238, v20
	v_fmac_f32_e32 v175, v238, v21
; DI float bf2f(unsigned v) { return __uint_as_float(v << 16); }
; DI float bflo(unsigned v) { return __uint_as_float(v << 16); }
; DI float bfhi(unsigned v) { return __uint_as_float(v & 0xffff0000u); }
; DI void sconv4(const u16* row, int t4, float w0, float w1, float w2, float bias, float (&o)[4]) {
;   const uint2 v = *(const uint2*)(row + t4);
;   const float x0 = bflo(v.x), x1 = bfhi(v.x), x2 = bflo(v.y), x3 = bfhi(v.y);
;   const float xm = (t4 > 0) ? bf2f(row[t4 - 1]) : 0.f;
;   const float xp = (t4 + 4 < SEQ) ? bf2f(row[t4 + 4]) : 0.f;
;   o[0] = w0 * xm + w1 * x0 + w2 * x1 + bias;
;   o[1] = w0 * x0 + w1 * x1 + w2 * x2 + bias;
;   o[2] = w0 * x1 + w1 * x2 + w2 * x3 + bias;
;   o[3] = w0 * x2 + w1 * x3 + w2 * xp + bias;
; }
; DI void hyena_item(const P& p, int l, int c, char* smem) {
;     ...
;         const int bq = 32 * I + 8 * rq + 4 * g;
;         const int t4 = 128 * a + bq;
;         float pv[4], px[4];
;         sconv4(rowv, t4, v0, v1, v2, vb, pv);
;         sconv4(rowx, t4, x0, x1, x2, xb, px);
;         float zz[4];
; #pragma unroll
;         for (int j = 0; j < 4; ++j) zz[j] = px[j] * (acc[I][4 * rq + j] * invn0 + pv[j] * d0);
;         uint2 ov; ov.x = pack2(zz[0], zz[1]); ov.y = pack2(zz[2], zz[3]);
;         *(uint2*)(U + (bt * 64 + a) * 136 + bq) = ov;
	v_fmac_f32_e32 v176, v238, v22
	v_fmac_f32_e32 v177, v238, v23
	v_and_b32_e32 v168, 0xffff0000, v148
	v_lshlrev_b32_e32 v169, 16, v149
	v_and_b32_e32 v170, 0xffff0000, v149
	v_lshlrev_b32_e32 v171, 16, v150
	v_and_b32_e32 v172, 0xffff0000, v150
	v_lshlrev_b32_e32 v173, 16, v151
	v_mul_f32_e32 v178, v244, v168
	v_fmac_f32_e32 v178, v245, v169
	v_fmac_f32_e32 v178, v246, v170
	v_add_f32_e32 v178, v247, v178
	v_mul_f32_e32 v179, v244, v169
	v_fmac_f32_e32 v179, v245, v170
	v_fmac_f32_e32 v179, v246, v171
	v_add_f32_e32 v179, v247, v179
	v_mul_f32_e32 v180, v244, v170
	v_fmac_f32_e32 v180, v245, v171
	v_fmac_f32_e32 v180, v246, v172
	v_add_f32_e32 v180, v247, v180
	v_mul_f32_e32 v181, v244, v171
	v_fmac_f32_e32 v181, v245, v172
	v_fmac_f32_e32 v181, v246, v173
	v_add_f32_e32 v181, v247, v181
	v_mul_f32_e32 v174, v174, v178
	v_mul_f32_e32 v175, v175, v179
	v_mul_f32_e32 v176, v176, v180
	v_mul_f32_e32 v177, v177, v181
	v_cvt_pk_bf16_f32 v182, v174, v175
	v_cvt_pk_bf16_f32 v183, v176, v177
	ds_write_b64 v235, v[182:183] offset:144
	v_and_b32_e32 v168, 0xffff0000, v152
	v_lshlrev_b32_e32 v169, 16, v153
	v_and_b32_e32 v170, 0xffff0000, v153
	v_lshlrev_b32_e32 v171, 16, v154
	v_and_b32_e32 v172, 0xffff0000, v154
	v_lshlrev_b32_e32 v173, 16, v155
	v_mul_f32_e32 v174, v240, v168
	v_fmac_f32_e32 v174, v241, v169
	v_fmac_f32_e32 v174, v242, v170
	v_add_f32_e32 v174, v243, v174
	v_mul_f32_e32 v175, v240, v169
	v_fmac_f32_e32 v175, v241, v170
	v_fmac_f32_e32 v175, v242, v171
	v_add_f32_e32 v175, v243, v175
	v_mul_f32_e32 v176, v240, v170
	v_fmac_f32_e32 v176, v241, v171
	v_fmac_f32_e32 v176, v242, v172
	v_add_f32_e32 v176, v243, v176
	v_mul_f32_e32 v177, v240, v171
	v_fmac_f32_e32 v177, v241, v172
	v_fmac_f32_e32 v177, v242, v173
	v_add_f32_e32 v177, v243, v177
	v_mul_f32_e32 v174, v239, v174
	v_mul_f32_e32 v175, v239, v175
	v_mul_f32_e32 v176, v239, v176
	v_mul_f32_e32 v177, v239, v177
	v_fmac_f32_e32 v174, v238, v24
	v_fmac_f32_e32 v175, v238, v25
	v_fmac_f32_e32 v176, v238, v26
	v_fmac_f32_e32 v177, v238, v27
	v_and_b32_e32 v168, 0xffff0000, v156
	v_lshlrev_b32_e32 v169, 16, v157
	v_and_b32_e32 v170, 0xffff0000, v157
	v_lshlrev_b32_e32 v171, 16, v158
	v_and_b32_e32 v172, 0xffff0000, v158
	v_lshlrev_b32_e32 v173, 16, v159
	v_mul_f32_e32 v178, v244, v168
	v_fmac_f32_e32 v178, v245, v169
	v_fmac_f32_e32 v178, v246, v170
	v_add_f32_e32 v178, v247, v178
	v_mul_f32_e32 v179, v244, v169
	v_fmac_f32_e32 v179, v245, v170
	v_fmac_f32_e32 v179, v246, v171
	v_add_f32_e32 v179, v247, v179
	v_mul_f32_e32 v180, v244, v170
	v_fmac_f32_e32 v180, v245, v171
	v_fmac_f32_e32 v180, v246, v172
	v_add_f32_e32 v180, v247, v180
	v_mul_f32_e32 v181, v244, v171
	v_fmac_f32_e32 v181, v245, v172
	v_fmac_f32_e32 v181, v246, v173
	v_add_f32_e32 v181, v247, v181
	v_mul_f32_e32 v174, v174, v178
	v_mul_f32_e32 v175, v175, v179
	v_mul_f32_e32 v176, v176, v180
	v_mul_f32_e32 v177, v177, v181
	v_cvt_pk_bf16_f32 v182, v174, v175
	v_cvt_pk_bf16_f32 v183, v176, v177
	ds_write_b64 v235, v[182:183] offset:160
	v_and_b32_e32 v168, 0xffff0000, v160
	v_lshlrev_b32_e32 v169, 16, v161
	v_and_b32_e32 v170, 0xffff0000, v161
	v_lshlrev_b32_e32 v171, 16, v162
	v_and_b32_e32 v172, 0xffff0000, v162
	v_lshlrev_b32_e32 v173, 16, v163
	v_mul_f32_e32 v174, v240, v168
	v_fmac_f32_e32 v174, v241, v169
	v_fmac_f32_e32 v174, v242, v170
	v_add_f32_e32 v174, v243, v174
	v_mul_f32_e32 v175, v240, v169
	v_fmac_f32_e32 v175, v241, v170
	v_fmac_f32_e32 v175, v242, v171
	v_add_f32_e32 v175, v243, v175
	v_mul_f32_e32 v176, v240, v170
	v_fmac_f32_e32 v176, v241, v171
	v_fmac_f32_e32 v176, v242, v172
	v_add_f32_e32 v176, v243, v176
	v_mul_f32_e32 v177, v240, v171
	v_fmac_f32_e32 v177, v241, v172
	v_fmac_f32_e32 v177, v242, v173
	v_add_f32_e32 v177, v243, v177
	v_mul_f32_e32 v174, v239, v174
	v_mul_f32_e32 v175, v239, v175
	v_mul_f32_e32 v176, v239, v176
	v_mul_f32_e32 v177, v239, v177
	v_fmac_f32_e32 v174, v238, v28
	v_fmac_f32_e32 v175, v238, v29
	v_fmac_f32_e32 v176, v238, v30
	v_fmac_f32_e32 v177, v238, v31
	v_and_b32_e32 v168, 0xffff0000, v164
	v_lshlrev_b32_e32 v169, 16, v165
	v_and_b32_e32 v170, 0xffff0000, v165
	v_lshlrev_b32_e32 v171, 16, v166
	v_and_b32_e32 v172, 0xffff0000, v166
	v_lshlrev_b32_e32 v173, 16, v167
	v_mul_f32_e32 v178, v244, v168
	v_fmac_f32_e32 v178, v245, v169
	v_fmac_f32_e32 v178, v246, v170
	v_add_f32_e32 v178, v247, v178
	v_mul_f32_e32 v179, v244, v169
	v_fmac_f32_e32 v179, v245, v170
	v_fmac_f32_e32 v179, v246, v171
	v_add_f32_e32 v179, v247, v179
	v_mul_f32_e32 v180, v244, v170
	v_fmac_f32_e32 v180, v245, v171
	v_fmac_f32_e32 v180, v246, v172
	v_add_f32_e32 v180, v247, v180
	v_mul_f32_e32 v181, v244, v171
	v_fmac_f32_e32 v181, v245, v172
	v_fmac_f32_e32 v181, v246, v173
	v_add_f32_e32 v181, v247, v181
	v_mul_f32_e32 v174, v174, v178
	v_mul_f32_e32 v175, v175, v179
	v_mul_f32_e32 v176, v176, v180
	v_mul_f32_e32 v177, v177, v181
	v_cvt_pk_bf16_f32 v182, v174, v175
	v_cvt_pk_bf16_f32 v183, v176, v177
	ds_write_b64 v235, v[182:183] offset:176
	s_waitcnt vmcnt(0)
; DI float bf2f(unsigned v) { return __uint_as_float(v << 16); }
; DI float bflo(unsigned v) { return __uint_as_float(v << 16); }
; DI float bfhi(unsigned v) { return __uint_as_float(v & 0xffff0000u); }
; DI void sconv4(const u16* row, int t4, float w0, float w1, float w2, float bias, float (&o)[4]) {
;   const uint2 v = *(const uint2*)(row + t4);
;   const float x0 = bflo(v.x), x1 = bfhi(v.x), x2 = bflo(v.y), x3 = bfhi(v.y);
;   const float xm = (t4 > 0) ? bf2f(row[t4 - 1]) : 0.f;
;   const float xp = (t4 + 4 < SEQ) ? bf2f(row[t4 + 4]) : 0.f;
;   o[0] = w0 * xm + w1 * x0 + w2 * x1 + bias;
;   o[1] = w0 * x0 + w1 * x1 + w2 * x2 + bias;
;   o[2] = w0 * x1 + w1 * x2 + w2 * x3 + bias;
;   o[3] = w0 * x2 + w1 * x3 + w2 * xp + bias;
; }
; DI void hyena_item(const P& p, int l, int c, char* smem) {
;     ...
;         const int bq = 32 * I + 8 * rq + 4 * g;
;         const int t4 = 128 * a + bq;
;         float pv[4], px[4];
;         sconv4(rowv, t4, v0, v1, v2, vb, pv);
;         sconv4(rowx, t4, x0, x1, x2, xb, px);
;         float zz[4];
; #pragma unroll
;         for (int j = 0; j < 4; ++j) zz[j] = px[j] * (acc[I][4 * rq + j] * invn0 + pv[j] * d0);
;         uint2 ov; ov.x = pack2(zz[0], zz[1]); ov.y = pack2(zz[2], zz[3]);
;         *(uint2*)(U + (bt * 64 + a) * 136 + bq) = ov;
	v_and_b32_e32 v168, 0xffff0000, v72
	v_lshlrev_b32_e32 v169, 16, v73
	v_and_b32_e32 v170, 0xffff0000, v73
	v_lshlrev_b32_e32 v171, 16, v74
	v_and_b32_e32 v172, 0xffff0000, v74
	v_lshlrev_b32_e32 v173, 16, v75
	v_mul_f32_e32 v174, v240, v168
	v_fmac_f32_e32 v174, v241, v169
	v_fmac_f32_e32 v174, v242, v170
	v_add_f32_e32 v174, v243, v174
	v_mul_f32_e32 v175, v240, v169
	v_fmac_f32_e32 v175, v241, v170
	v_fmac_f32_e32 v175, v242, v171
	v_add_f32_e32 v175, v243, v175
	v_mul_f32_e32 v176, v240, v170
	v_fmac_f32_e32 v176, v241, v171
	v_fmac_f32_e32 v176, v242, v172
	v_add_f32_e32 v176, v243, v176
	v_mul_f32_e32 v177, v240, v171
	v_fmac_f32_e32 v177, v241, v172
	v_fmac_f32_e32 v177, v242, v173
	v_add_f32_e32 v177, v243, v177
	v_mul_f32_e32 v174, v239, v174
	v_mul_f32_e32 v175, v239, v175
	v_mul_f32_e32 v176, v239, v176
	v_mul_f32_e32 v177, v239, v177
	v_fmac_f32_e32 v174, v238, v0
	v_fmac_f32_e32 v175, v238, v1
	v_fmac_f32_e32 v176, v238, v2
	v_fmac_f32_e32 v177, v238, v3
	v_and_b32_e32 v168, 0xffff0000, v76
	v_lshlrev_b32_e32 v169, 16, v77
	v_and_b32_e32 v170, 0xffff0000, v77
	v_lshlrev_b32_e32 v171, 16, v78
	v_and_b32_e32 v172, 0xffff0000, v78
	v_lshlrev_b32_e32 v173, 16, v79
	v_mul_f32_e32 v178, v244, v168
	v_fmac_f32_e32 v178, v245, v169
	v_fmac_f32_e32 v178, v246, v170
	v_add_f32_e32 v178, v247, v178
	v_mul_f32_e32 v179, v244, v169
	v_fmac_f32_e32 v179, v245, v170
	v_fmac_f32_e32 v179, v246, v171
	v_add_f32_e32 v179, v247, v179
	v_mul_f32_e32 v180, v244, v170
	v_fmac_f32_e32 v180, v245, v171
	v_fmac_f32_e32 v180, v246, v172
	v_add_f32_e32 v180, v247, v180
	v_mul_f32_e32 v181, v244, v171
	v_fmac_f32_e32 v181, v245, v172
	v_fmac_f32_e32 v181, v246, v173
	v_add_f32_e32 v181, v247, v181
	v_mul_f32_e32 v174, v174, v178
	v_mul_f32_e32 v175, v175, v179
	v_mul_f32_e32 v176, v176, v180
	v_mul_f32_e32 v177, v177, v181
	v_cvt_pk_bf16_f32 v182, v174, v175
	v_cvt_pk_bf16_f32 v183, v176, v177
	ds_write_b64 v235, v[182:183] offset:192
	v_and_b32_e32 v168, 0xffff0000, v80
	v_lshlrev_b32_e32 v169, 16, v81
	v_and_b32_e32 v170, 0xffff0000, v81
	v_lshlrev_b32_e32 v171, 16, v82
	v_and_b32_e32 v172, 0xffff0000, v82
	v_lshlrev_b32_e32 v173, 16, v83
	v_mul_f32_e32 v174, v240, v168
	v_fmac_f32_e32 v174, v241, v169
	v_fmac_f32_e32 v174, v242, v170
	v_add_f32_e32 v174, v243, v174
	v_mul_f32_e32 v175, v240, v169
	v_fmac_f32_e32 v175, v241, v170
	v_fmac_f32_e32 v175, v242, v171
	v_add_f32_e32 v175, v243, v175
	v_mul_f32_e32 v176, v240, v170
	v_fmac_f32_e32 v176, v241, v171
	v_fmac_f32_e32 v176, v242, v172
	v_add_f32_e32 v176, v243, v176
	v_mul_f32_e32 v177, v240, v171
	v_fmac_f32_e32 v177, v241, v172
	v_fmac_f32_e32 v177, v242, v173
	v_add_f32_e32 v177, v243, v177
	v_mul_f32_e32 v174, v239, v174
	v_mul_f32_e32 v175, v239, v175
	v_mul_f32_e32 v176, v239, v176
	v_mul_f32_e32 v177, v239, v177
	v_fmac_f32_e32 v174, v238, v4
	v_fmac_f32_e32 v175, v238, v5
	v_fmac_f32_e32 v176, v238, v6
	v_fmac_f32_e32 v177, v238, v7
	v_and_b32_e32 v168, 0xffff0000, v84
	v_lshlrev_b32_e32 v169, 16, v85
	v_and_b32_e32 v170, 0xffff0000, v85
	v_lshlrev_b32_e32 v171, 16, v86
	v_and_b32_e32 v172, 0xffff0000, v86
	v_lshlrev_b32_e32 v173, 16, v87
	v_mul_f32_e32 v178, v244, v168
	v_fmac_f32_e32 v178, v245, v169
	v_fmac_f32_e32 v178, v246, v170
	v_add_f32_e32 v178, v247, v178
	v_mul_f32_e32 v179, v244, v169
	v_fmac_f32_e32 v179, v245, v170
	v_fmac_f32_e32 v179, v246, v171
	v_add_f32_e32 v179, v247, v179
	v_mul_f32_e32 v180, v244, v170
	v_fmac_f32_e32 v180, v245, v171
	v_fmac_f32_e32 v180, v246, v172
	v_add_f32_e32 v180, v247, v180
	v_mul_f32_e32 v181, v244, v171
	v_fmac_f32_e32 v181, v245, v172
	v_fmac_f32_e32 v181, v246, v173
	v_add_f32_e32 v181, v247, v181
	v_mul_f32_e32 v174, v174, v178
	v_mul_f32_e32 v175, v175, v179
	v_mul_f32_e32 v176, v176, v180
	v_mul_f32_e32 v177, v177, v181
	v_cvt_pk_bf16_f32 v182, v174, v175
	v_cvt_pk_bf16_f32 v183, v176, v177
	ds_write_b64 v235, v[182:183] offset:208
	v_and_b32_e32 v168, 0xffff0000, v88
	v_lshlrev_b32_e32 v169, 16, v89
; DI float bf2f(unsigned v) { return __uint_as_float(v << 16); }
; DI float bflo(unsigned v) { return __uint_as_float(v << 16); }
; DI float bfhi(unsigned v) { return __uint_as_float(v & 0xffff0000u); }
; DI void sconv4(const u16* row, int t4, float w0, float w1, float w2, float bias, float (&o)[4]) {
;   const uint2 v = *(const uint2*)(row + t4);
;   const float x0 = bflo(v.x), x1 = bfhi(v.x), x2 = bflo(v.y), x3 = bfhi(v.y);
;   const float xm = (t4 > 0) ? bf2f(row[t4 - 1]) : 0.f;
;   const float xp = (t4 + 4 < SEQ) ? bf2f(row[t4 + 4]) : 0.f;
;   o[0] = w0 * xm + w1 * x0 + w2 * x1 + bias;
;   o[1] = w0 * x0 + w1 * x1 + w2 * x2 + bias;
;   o[2] = w0 * x1 + w1 * x2 + w2 * x3 + bias;
;   o[3] = w0 * x2 + w1 * x3 + w2 * xp + bias;
; }
; DI void hyena_item(const P& p, int l, int c, char* smem) {
;     ...
;         const int bq = 32 * I + 8 * rq + 4 * g;
;         const int t4 = 128 * a + bq;
;         float pv[4], px[4];
;         sconv4(rowv, t4, v0, v1, v2, vb, pv);
;         sconv4(rowx, t4, x0, x1, x2, xb, px);
;         float zz[4];
; #pragma unroll
;         for (int j = 0; j < 4; ++j) zz[j] = px[j] * (acc[I][4 * rq + j] * invn0 + pv[j] * d0);
;         uint2 ov; ov.x = pack2(zz[0], zz[1]); ov.y = pack2(zz[2], zz[3]);
;         *(uint2*)(U + (bt * 64 + a) * 136 + bq) = ov;
	v_and_b32_e32 v170, 0xffff0000, v89
	v_lshlrev_b32_e32 v171, 16, v90
	v_and_b32_e32 v172, 0xffff0000, v90
	v_lshlrev_b32_e32 v173, 16, v91
	v_mul_f32_e32 v174, v240, v168
	v_fmac_f32_e32 v174, v241, v169
	v_fmac_f32_e32 v174, v242, v170
	v_add_f32_e32 v174, v243, v174
	v_mul_f32_e32 v175, v240, v169
	v_fmac_f32_e32 v175, v241, v170
	v_fmac_f32_e32 v175, v242, v171
	v_add_f32_e32 v175, v243, v175
	v_mul_f32_e32 v176, v240, v170
	v_fmac_f32_e32 v176, v241, v171
	v_fmac_f32_e32 v176, v242, v172
	v_add_f32_e32 v176, v243, v176
	v_mul_f32_e32 v177, v240, v171
	v_fmac_f32_e32 v177, v241, v172
	v_fmac_f32_e32 v177, v242, v173
	v_add_f32_e32 v177, v243, v177
	v_mul_f32_e32 v174, v239, v174
	v_mul_f32_e32 v175, v239, v175
	v_mul_f32_e32 v176, v239, v176
	v_mul_f32_e32 v177, v239, v177
	v_fmac_f32_e32 v174, v238, v8
	v_fmac_f32_e32 v175, v238, v9
	v_fmac_f32_e32 v176, v238, v10
	v_fmac_f32_e32 v177, v238, v11
	v_and_b32_e32 v168, 0xffff0000, v92
	v_lshlrev_b32_e32 v169, 16, v93
	v_and_b32_e32 v170, 0xffff0000, v93
	v_lshlrev_b32_e32 v171, 16, v94
	v_and_b32_e32 v172, 0xffff0000, v94
	v_lshlrev_b32_e32 v173, 16, v95
	v_mul_f32_e32 v178, v244, v168
	v_fmac_f32_e32 v178, v245, v169
	v_fmac_f32_e32 v178, v246, v170
	v_add_f32_e32 v178, v247, v178
	v_mul_f32_e32 v179, v244, v169
	v_fmac_f32_e32 v179, v245, v170
	v_fmac_f32_e32 v179, v246, v171
	v_add_f32_e32 v179, v247, v179
	v_mul_f32_e32 v180, v244, v170
	v_fmac_f32_e32 v180, v245, v171
	v_fmac_f32_e32 v180, v246, v172
	v_add_f32_e32 v180, v247, v180
	v_mul_f32_e32 v181, v244, v171
	v_fmac_f32_e32 v181, v245, v172
	v_fmac_f32_e32 v181, v246, v173
	v_add_f32_e32 v181, v247, v181
	v_mul_f32_e32 v174, v174, v178
	v_mul_f32_e32 v175, v175, v179
	v_mul_f32_e32 v176, v176, v180
	v_mul_f32_e32 v177, v177, v181
	v_cvt_pk_bf16_f32 v182, v174, v175
	v_cvt_pk_bf16_f32 v183, v176, v177
	ds_write_b64 v235, v[182:183] offset:224
	v_cmp_ne_u32_e32 vcc, 0x1f84, v233
	s_nop 1
	v_and_b32_e32 v168, 0xffff0000, v96
	v_lshlrev_b32_e32 v169, 16, v97
	v_and_b32_e32 v170, 0xffff0000, v97
	v_lshlrev_b32_e32 v171, 16, v98
	v_and_b32_e32 v172, 0xffff0000, v98
	v_lshlrev_b32_e32 v173, 16, v99
	v_cndmask_b32_e32 v173, 0, v173, vcc
	v_mul_f32_e32 v174, v240, v168
	v_fmac_f32_e32 v174, v241, v169
	v_fmac_f32_e32 v174, v242, v170
	v_add_f32_e32 v174, v243, v174
	v_mul_f32_e32 v175, v240, v169
	v_fmac_f32_e32 v175, v241, v170
	v_fmac_f32_e32 v175, v242, v171
	v_add_f32_e32 v175, v243, v175
	v_mul_f32_e32 v176, v240, v170
	v_fmac_f32_e32 v176, v241, v171
	v_fmac_f32_e32 v176, v242, v172
	v_add_f32_e32 v176, v243, v176
	v_mul_f32_e32 v177, v240, v171
	v_fmac_f32_e32 v177, v241, v172
	v_fmac_f32_e32 v177, v242, v173
	v_add_f32_e32 v177, v243, v177
	v_mul_f32_e32 v174, v239, v174
	v_mul_f32_e32 v175, v239, v175
	v_mul_f32_e32 v176, v239, v176
	v_mul_f32_e32 v177, v239, v177
	v_fmac_f32_e32 v174, v238, v12
	v_fmac_f32_e32 v175, v238, v13
	v_fmac_f32_e32 v176, v238, v14
	v_fmac_f32_e32 v177, v238, v15
	v_and_b32_e32 v168, 0xffff0000, v100
	v_lshlrev_b32_e32 v169, 16, v101
	v_and_b32_e32 v170, 0xffff0000, v101
	v_lshlrev_b32_e32 v171, 16, v102
	v_and_b32_e32 v172, 0xffff0000, v102
	v_lshlrev_b32_e32 v173, 16, v103
	v_cndmask_b32_e32 v173, 0, v173, vcc
	v_mul_f32_e32 v178, v244, v168
	v_fmac_f32_e32 v178, v245, v169
	v_fmac_f32_e32 v178, v246, v170
	v_add_f32_e32 v178, v247, v178
	v_mul_f32_e32 v179, v244, v169
	v_fmac_f32_e32 v179, v245, v170
	v_fmac_f32_e32 v179, v246, v171
	v_add_f32_e32 v179, v247, v179
	v_mul_f32_e32 v180, v244, v170
	v_fmac_f32_e32 v180, v245, v171
	v_fmac_f32_e32 v180, v246, v172
	v_add_f32_e32 v180, v247, v180
	v_mul_f32_e32 v181, v244, v171
	v_fmac_f32_e32 v181, v245, v172
	v_fmac_f32_e32 v181, v246, v173
	v_add_f32_e32 v181, v247, v181
	v_mul_f32_e32 v174, v174, v178
	v_mul_f32_e32 v175, v175, v179
	v_mul_f32_e32 v176, v176, v180
	v_mul_f32_e32 v177, v177, v181
	v_cvt_pk_bf16_f32 v182, v174, v175
	v_cvt_pk_bf16_f32 v183, v176, v177
	ds_write_b64 v235, v[182:183] offset:240

; #define MFMA(a, b, c) __builtin_amdgcn_mfma_f32_32x32x16_bf16((a), (b), (c), 0, 0, 0)
; DI f32x16 zero16() { f32x16 z; for (int i = 0; i < 16; ++i) z[i] = 0.f; return z; }
; DI void hy_conv(f32x16 (&acc)[4], const u16* abase, const u16* U, const u16* Zrow, int a0, int li, int g) {
; #pragma unroll
;   for (int i = 0; i < 4; ++i) acc[i] = zero16();
;   u32x4 W[14];
;   bf16x8 bf[8];
;   int d = a0 - 63;
; #pragma unroll
;   for (int x = 0; x < 14; ++x) W[x] = hy_afrag(abase, 8 * d + x - 7);
;   for (; d <= a0 + 15; ++d) {
;     hy_bfrag(bf, U, Zrow, a0, li, g, d);
;     u32x4 Wn[8];
;     const int dn = (d < a0 + 15) ? d + 1 : d;
; #pragma unroll
;     for (int x = 0; x < 8; ++x) Wn[x] = hy_afrag(abase, 8 * dn + x - 1);
; #pragma unroll
;     for (int kc = 0; kc < 8; ++kc)
; #pragma unroll
;       for (int I = 0; I < 4; ++I) acc[I] = MFMA(__builtin_bit_cast(bf16x8, W[2 * I - kc + 7]), bf[kc], acc[I]);
; #pragma unroll
;     for (int x = 0; x < 6; ++x) W[x] = W[x + 8];
; #pragma unroll
;     for (int x = 0; x < 8; ++x) W[x + 6] = Wn[x];
;   }
.LBB0_455:
	s_or_b64 exec, exec, s[8:9]
	s_waitcnt vmcnt(0)
	ds_write_b128 v221, v[0:3] offset:24576
	v_perm_b32 v0, v0, v1, s68
	v_perm_b32 v1, v1, v2, s68
	v_perm_b32 v2, v2, v3, s68
	v_or_b32_sdwa v3, v6, v3 dst_sel:DWORD dst_unused:UNUSED_PAD src0_sel:DWORD src1_sel:WORD_1
	s_mov_b64 s[10:11], 0
	s_mov_b64 s[8:9], 0
	ds_write_b128 v221, v[0:3] offset:57408
	s_waitcnt lgkmcnt(0)
	s_barrier
	s_mov_b64 s[100:101], s[6:7]
	s_mov_b64 s[12:13], exec
	s_movk_i32 s6, 0xff00
	v_mad_i32_i24 v0, v228, s6, v225
	ds_read2_b32 v[152:153], v0 offset0:56 offset1:57
	ds_read2_b32 v[154:155], v0 offset0:58 offset1:59
	ds_read2_b32 v[148:149], v0 offset0:48 offset1:49
	ds_read2_b32 v[150:151], v0 offset0:50 offset1:51
	ds_read2_b32 v[140:141], v0 offset0:40 offset1:41
	ds_read2_b32 v[142:143], v0 offset0:42 offset1:43
	ds_read2_b32 v[136:137], v0 offset0:32 offset1:33
	ds_read2_b32 v[138:139], v0 offset0:34 offset1:35
	ds_read2_b32 v[128:129], v0 offset0:24 offset1:25
	ds_read2_b32 v[130:131], v0 offset0:26 offset1:27
	ds_read2_b32 v[132:133], v0 offset0:16 offset1:17
	ds_read2_b32 v[134:135], v0 offset0:18 offset1:19
	ds_read2_b32 v[120:121], v0 offset0:8 offset1:9
	ds_read2_b32 v[122:123], v0 offset0:10 offset1:11
	ds_read2_b32 v[124:125], v0 offset1:1
	ds_read2_b32 v[126:127], v0 offset0:2 offset1:3
	v_subrev_u32_e32 v1, 32, v0
	v_subrev_u32_e32 v2, 24, v0
	v_subrev_u32_e32 v3, 64, v0
	v_subrev_u32_e32 v4, 56, v0
	ds_read2_b32 v[100:101], v1 offset1:1
	ds_read2_b32 v[102:103], v2 offset1:1
	ds_read2_b32 v[92:93], v3 offset1:1
	ds_read2_b32 v[94:95], v4 offset1:1
	v_add_u32_e32 v1, 0xffffffa0, v0
	v_add_u32_e32 v2, 0xffffffa8, v0
	v_add_u32_e32 v3, 0xffffff80, v0
	v_add_u32_e32 v4, 0xffffff88, v0
	ds_read2_b32 v[96:97], v1 offset1:1
	ds_read2_b32 v[98:99], v2 offset1:1
	ds_read2_b32 v[104:105], v3 offset1:1
	ds_read2_b32 v[106:107], v4 offset1:1
	v_add_u32_e32 v1, 0xffffff60, v0
	v_add_u32_e32 v2, 0xffffff68, v0
	v_add_u32_e32 v3, 0xffffff40, v0
	v_add_u32_e32 v0, 0xffffff48, v0
	ds_read2_b32 v[108:109], v1 offset1:1
	ds_read2_b32 v[110:111], v2 offset1:1
	ds_read2_b32 v[112:113], v3 offset1:1
	ds_read2_b32 v[114:115], v0 offset1:1
	v_add_u32_e32 v0, v229, v224
	v_sub_u32_e32 v0, v0, v228
	v_mov_b32_e32 v1, s69
	v_mad_u32_u24 v185, v0, s97, v1
	v_mov_b32_e32 v0, 0
	v_sub_u32_e32 v188, v229, v228
	s_mov_b64 s[6:7], 0
	v_mov_b32_e32 v1, v0
	v_mov_b32_e32 v2, v0
	v_mov_b32_e32 v3, v0
	v_mov_b32_e32 v4, v0
	v_mov_b32_e32 v5, v0
	v_mov_b32_e32 v6, v0
	v_mov_b32_e32 v7, v0
	v_mov_b32_e32 v8, v0
	v_mov_b32_e32 v9, v0
	v_mov_b32_e32 v10, v0
	v_mov_b32_e32 v11, v0
	v_mov_b32_e32 v12, v0
	v_mov_b32_e32 v13, v0
	v_mov_b32_e32 v14, v0
	v_mov_b32_e32 v15, v0
	v_mov_b32_e32 v16, v0
	v_mov_b32_e32 v17, v0
	v_mov_b32_e32 v18, v0
	v_mov_b32_e32 v19, v0
	v_mov_b32_e32 v20, v0
	v_mov_b32_e32 v21, v0
	v_mov_b32_e32 v22, v0
	v_mov_b32_e32 v23, v0
	v_mov_b32_e32 v24, v0
	v_mov_b32_e32 v25, v0
	v_mov_b32_e32 v26, v0
	v_mov_b32_e32 v27, v0
	v_mov_b32_e32 v28, v0
	v_mov_b32_e32 v29, v0
	v_mov_b32_e32 v30, v0
	v_mov_b32_e32 v31, v0
	v_mov_b32_e32 v32, v0
	v_mov_b32_e32 v33, v0
	v_mov_b32_e32 v34, v0
	v_mov_b32_e32 v35, v0
	v_mov_b32_e32 v36, v0
	v_mov_b32_e32 v37, v0
	v_mov_b32_e32 v38, v0
	v_mov_b32_e32 v39, v0
	v_mov_b32_e32 v40, v0
	v_mov_b32_e32 v41, v0
	v_mov_b32_e32 v42, v0
	v_mov_b32_e32 v43, v0
	v_mov_b32_e32 v44, v0
	v_mov_b32_e32 v45, v0
	v_mov_b32_e32 v46, v0
	v_mov_b32_e32 v47, v0
	v_mov_b32_e32 v48, v0
	v_mov_b32_e32 v49, v0
	v_mov_b32_e32 v50, v0
	v_mov_b32_e32 v51, v0
	v_mov_b32_e32 v52, v0
	v_mov_b32_e32 v53, v0
	v_mov_b32_e32 v54, v0
	v_mov_b32_e32 v55, v0
	v_mov_b32_e32 v56, v0
	v_mov_b32_e32 v57, v0
	v_mov_b32_e32 v58, v0
	v_mov_b32_e32 v59, v0
	v_mov_b32_e32 v60, v0
	v_mov_b32_e32 v61, v0
	v_mov_b32_e32 v62, v0
	v_mov_b32_e32 v63, v0
.LBB0_457:
	s_waitcnt lgkmcnt(8)
	v_mov_b32_e32 v83, v95
	v_mov_b32_e32 v82, v94
	v_mov_b32_e32 v81, v93
	v_mov_b32_e32 v80, v92
	s_waitcnt lgkmcnt(4)
	v_mov_b32_e32 v87, v107
	v_mov_b32_e32 v86, v106
	v_mov_b32_e32 v85, v105
	v_mov_b32_e32 v84, v104
	s_waitcnt lgkmcnt(0)
	v_mov_b32_e32 v91, v115
	v_mov_b32_e32 v90, v114
	v_mov_b32_e32 v89, v113
	v_mov_b32_e32 v88, v112
	s_add_i32 s8, 0, 0x18880
	v_cmp_gt_u32_e32 vcc, 64, v188
	v_mov_b32_e32 v92, s8
	v_mov_b32_e32 v71, v103
	v_cndmask_b32_e32 v92, v92, v185, vcc
	v_add_u32_e32 v92, v92, v222
	ds_read_b128 v[190:193], v92
	ds_read_b128 v[180:183], v92 offset:32
	ds_read_b128 v[176:179], v92 offset:64
	ds_read_b128 v[172:175], v92 offset:96
	ds_read_b128 v[168:171], v92 offset:128
	ds_read_b128 v[164:167], v92 offset:160
	ds_read_b128 v[160:163], v92 offset:192
	ds_read_b128 v[156:159], v92 offset:224
	s_waitcnt lgkmcnt(7)
	v_mfma_f32_32x32x16_bf16 v[48:63], v[124:127], v[190:193], v[48:63]
	v_mov_b32_e32 v70, v102
	v_mov_b32_e32 v69, v101
	v_mov_b32_e32 v68, v100
	v_mov_b32_e32 v79, v99
	v_mov_b32_e32 v78, v98
	v_mov_b32_e32 v77, v97
	v_mov_b32_e32 v76, v96
	v_mfma_f32_32x32x16_bf16 v[32:47], v[80:83], v[190:193], v[32:47]
	v_mov_b32_e32 v75, v111
	v_mov_b32_e32 v74, v110
	v_mov_b32_e32 v73, v109
	v_mov_b32_e32 v72, v108
	v_cmp_lt_i32_e32 vcc, v228, v226
	v_add_u32_e32 v194, 1, v228
	v_add_u32_e32 v185, 0xfffffef0, v185
	v_mfma_f32_32x32x16_bf16 v[16:31], v[84:87], v[190:193], v[16:31]
	v_cndmask_b32_e32 v92, v228, v194, vcc
	v_lshlrev_b32_e32 v112, 8, v92
	v_sub_u32_e32 v92, v225, v112
	ds_read2_b32 v[116:117], v92 offset0:8 offset1:9
	ds_read2_b32 v[118:119], v92 offset0:10 offset1:11
	ds_read2_b32 v[144:145], v92 offset1:1
	ds_read2_b32 v[146:147], v92 offset0:2 offset1:3
	v_xad_u32 v92, v112, s93, v225
	v_xad_u32 v94, v112, s92, v225
	v_xad_u32 v98, v112, s60, v225
	v_mfma_f32_32x32x16_bf16 v[0:15], v[88:91], v[190:193], v[0:15]
	v_xad_u32 v106, v112, s54, v225
	v_xad_u32 v110, v112, s55, v225
	v_xad_u32 v114, v112, s66, v225
	ds_read2_b32 v[100:101], v92 offset1:1
	ds_read2_b32 v[102:103], v92 offset0:2 offset1:3
	ds_read2_b32 v[92:93], v94 offset1:1
	ds_read2_b32 v[94:95], v94 offset0:2 offset1:3
	ds_read2_b32 v[96:97], v98 offset1:1
	ds_read2_b32 v[98:99], v98 offset0:2 offset1:3
	ds_read2_b32 v[104:105], v106 offset1:1
	ds_read2_b32 v[106:107], v106 offset0:2 offset1:3
	s_waitcnt lgkmcnt(14)
; #define MFMA(a, b, c) __builtin_amdgcn_mfma_f32_32x32x16_bf16((a), (b), (c), 0, 0, 0)
; DI void hy_conv(f32x16 (&acc)[4], const u16* abase, const u16* U, const u16* Zrow, int a0, int li, int g) {
;     ...
;   for (; d <= a0 + 15; ++d) {
;     hy_bfrag(bf, U, Zrow, a0, li, g, d);
;     u32x4 Wn[8];
;     const int dn = (d < a0 + 15) ? d + 1 : d;
; #pragma unroll
;     for (int x = 0; x < 8; ++x) Wn[x] = hy_afrag(abase, 8 * dn + x - 1);
; #pragma unroll
;     for (int kc = 0; kc < 8; ++kc)
; #pragma unroll
;       for (int I = 0; I < 4; ++I) acc[I] = MFMA(__builtin_bit_cast(bf16x8, W[2 * I - kc + 7]), bf[kc], acc[I]);
; #pragma unroll
;     for (int x = 0; x < 6; ++x) W[x] = W[x + 8];
; #pragma unroll
;     for (int x = 0; x < 8; ++x) W[x + 6] = Wn[x];
; DI void hyena_item(const P& p, int l, int c, char* smem) {
;     ...
;   if (cwv) {
;     const float d1 = p.fbias[(size_t)(l * 2 + 1) * 512 + c];
;     const float x0 = cw[1024 + c], x1 = cw[1536 + 1024 + c], x2 = cw[3072 + 1024 + c], xb = cbias[1024 + c];
;     const u16* rowx = p.hyT + (size_t)(1024 + c) * HYP + bt * SEQ;
;     const u16* rowg = p.hyT + (size_t)(1536 + c) * HYP + bt * SEQ;
;     u16* dst = p.YhT + (size_t)c * HYP + bt * SEQ;
	v_mfma_f32_32x32x16_bf16 v[48:63], v[120:123], v[180:183], v[48:63]
	ds_read2_b32 v[108:109], v110 offset1:1
	ds_read2_b32 v[110:111], v110 offset0:2 offset1:3
	ds_read2_b32 v[112:113], v114 offset1:1
	ds_read2_b32 v[114:115], v114 offset0:2 offset1:3
	v_cmp_eq_u32_e32 vcc, v228, v227
	v_add_u32_e32 v188, -1, v188
	s_or_b64 s[6:7], vcc, s[6:7]
	v_mov_b32_e32 v228, v194
	v_mfma_f32_32x32x16_bf16 v[32:47], v[68:71], v[180:183], v[32:47]
	v_mfma_f32_32x32x16_bf16 v[16:31], v[76:79], v[180:183], v[16:31]
	v_mfma_f32_32x32x16_bf16 v[0:15], v[72:75], v[180:183], v[0:15]
	v_mfma_f32_32x32x16_bf16 v[48:63], v[132:135], v[176:179], v[48:63]
	v_mfma_f32_32x32x16_bf16 v[32:47], v[124:127], v[176:179], v[32:47]
	v_mfma_f32_32x32x16_bf16 v[16:31], v[80:83], v[176:179], v[16:31]
	v_mfma_f32_32x32x16_bf16 v[0:15], v[84:87], v[176:179], v[0:15]
	v_mfma_f32_32x32x16_bf16 v[48:63], v[128:131], v[172:175], v[48:63]
	v_mfma_f32_32x32x16_bf16 v[32:47], v[120:123], v[172:175], v[32:47]
	v_mfma_f32_32x32x16_bf16 v[16:31], v[68:71], v[172:175], v[16:31]
	v_mfma_f32_32x32x16_bf16 v[0:15], v[76:79], v[172:175], v[0:15]
	v_mfma_f32_32x32x16_bf16 v[48:63], v[136:139], v[168:171], v[48:63]
	v_mfma_f32_32x32x16_bf16 v[32:47], v[132:135], v[168:171], v[32:47]
	v_mfma_f32_32x32x16_bf16 v[16:31], v[124:127], v[168:171], v[16:31]
	v_mfma_f32_32x32x16_bf16 v[0:15], v[80:83], v[168:171], v[0:15]
	v_mfma_f32_32x32x16_bf16 v[48:63], v[140:143], v[164:167], v[48:63]
	v_mfma_f32_32x32x16_bf16 v[32:47], v[128:131], v[164:167], v[32:47]
	v_mfma_f32_32x32x16_bf16 v[16:31], v[120:123], v[164:167], v[16:31]
	v_mfma_f32_32x32x16_bf16 v[0:15], v[68:71], v[164:167], v[0:15]
	s_waitcnt lgkmcnt(14)
	v_mfma_f32_32x32x16_bf16 v[48:63], v[148:151], v[160:163], v[48:63]
	v_mov_b32_e32 v148, v80
	v_mov_b32_e32 v149, v81
	v_mov_b32_e32 v150, v82
	v_mov_b32_e32 v151, v83
	v_mfma_f32_32x32x16_bf16 v[32:47], v[136:139], v[160:163], v[32:47]
	v_mov_b32_e32 v136, v84
	v_mov_b32_e32 v137, v85
	v_mov_b32_e32 v138, v86
	v_mov_b32_e32 v139, v87
	v_mfma_f32_32x32x16_bf16 v[16:31], v[132:135], v[160:163], v[16:31]
	v_mov_b32_e32 v132, v88
	v_mov_b32_e32 v133, v89
	v_mov_b32_e32 v134, v90
	v_mov_b32_e32 v135, v91
	v_mfma_f32_32x32x16_bf16 v[0:15], v[124:127], v[160:163], v[0:15]
	s_waitcnt lgkmcnt(13)
	v_mov_b32_e32 v124, v144
	v_mov_b32_e32 v125, v145
	s_waitcnt lgkmcnt(12)
	v_mov_b32_e32 v126, v146
	v_mov_b32_e32 v127, v147
	v_mfma_f32_32x32x16_bf16 v[48:63], v[152:155], v[156:159], v[48:63]
	v_mov_b32_e32 v152, v68
	v_mov_b32_e32 v153, v69
	v_mov_b32_e32 v154, v70
	v_mov_b32_e32 v155, v71
	v_mfma_f32_32x32x16_bf16 v[32:47], v[140:143], v[156:159], v[32:47]
	v_mov_b32_e32 v140, v76
	v_mov_b32_e32 v141, v77
	v_mov_b32_e32 v142, v78
	v_mov_b32_e32 v143, v79
	v_mfma_f32_32x32x16_bf16 v[16:31], v[128:131], v[156:159], v[16:31]
	v_mov_b32_e32 v128, v72
	v_mov_b32_e32 v129, v73
	v_mov_b32_e32 v130, v74
	v_mov_b32_e32 v131, v75
	v_mfma_f32_32x32x16_bf16 v[0:15], v[120:123], v[156:159], v[0:15]
	v_mov_b32_e32 v120, v116
	v_mov_b32_e32 v121, v117
	v_mov_b32_e32 v122, v118
	v_mov_b32_e32 v123, v119
	s_andn2_b64 exec, exec, s[6:7]
	s_cbranch_execnz .LBB0_457
	s_or_b64 exec, exec, s[6:7]
	v_add_u32_e32 v120, v250, v223
	v_add_u32_e32 v121, v224, v120
	v_mov_b32_e32 v122, s69
	v_mad_i32_i24 v121, v121, s97, v122
	v_mov_b32_e32 v122, s8
	v_cmp_gt_u32_e32 vcc, 64, v120
	v_readlane_b32 s6, v248, 24
	s_add_i32 s6, s72, s6
	v_cndmask_b32_e32 v120, v122, v121, vcc
	v_add_u32_e32 v124, v120, v222
	ds_read_b128 v[120:123], v124
	s_waitcnt lgkmcnt(0)
	v_mfma_f32_32x32x16_bf16 v[48:63], v[144:147], v[120:123], v[48:63]
	s_mov_b32 s7, s57
	s_lshl_b64 s[6:7], s[6:7], 2
	s_add_u32 s6, s20, s6
	s_addc_u32 s7, s21, s7
	s_or_b32 s8, s72, 0x400
	s_mov_b32 s9, s57
	s_lshl_b64 s[14:15], s[8:9], 2
	v_mfma_f32_32x32x16_bf16 v[32:47], v[92:95], v[120:123], v[32:47]
	s_add_u32 s76, s28, s14
	s_addc_u32 s77, s29, s15
	v_readlane_b32 s9, v248, 28
	s_add_u32 s14, s9, s14
	v_readlane_b32 s9, v248, 29
	s_addc_u32 s15, s9, s15
	v_mov_b32_e32 v185, v189
	v_mfma_f32_32x32x16_bf16 v[16:31], v[104:107], v[120:123], v[16:31]
	v_lshlrev_b32_e32 v188, 1, v233
	v_cmp_ne_u32_e32 vcc, 0, v233
	v_mfma_f32_32x32x16_bf16 v[0:15], v[112:115], v[120:123], v[0:15]
	ds_read_b128 v[112:115], v124 offset:32
	s_waitcnt lgkmcnt(0)
	v_mfma_f32_32x32x16_bf16 v[48:63], v[116:119], v[112:115], v[48:63]
	v_mfma_f32_32x32x16_bf16 v[32:47], v[100:103], v[112:115], v[32:47]
	v_mfma_f32_32x32x16_bf16 v[16:31], v[96:99], v[112:115], v[16:31]
	v_mfma_f32_32x32x16_bf16 v[0:15], v[108:111], v[112:115], v[0:15]
	ds_read_b128 v[108:111], v124 offset:64
	s_waitcnt lgkmcnt(0)
	v_mfma_f32_32x32x16_bf16 v[48:63], v[88:91], v[108:111], v[48:63]
	v_mfma_f32_32x32x16_bf16 v[32:47], v[144:147], v[108:111], v[32:47]
	v_mfma_f32_32x32x16_bf16 v[16:31], v[92:95], v[108:111], v[16:31]
	v_mfma_f32_32x32x16_bf16 v[0:15], v[104:107], v[108:111], v[0:15]
	ds_read_b128 v[104:107], v124 offset:96
	s_waitcnt lgkmcnt(0)
	v_mfma_f32_32x32x16_bf16 v[48:63], v[72:75], v[104:107], v[48:63]
	v_mfma_f32_32x32x16_bf16 v[32:47], v[116:119], v[104:107], v[32:47]
	v_mfma_f32_32x32x16_bf16 v[16:31], v[100:103], v[104:107], v[16:31]
	v_mfma_f32_32x32x16_bf16 v[0:15], v[96:99], v[104:107], v[0:15]
	ds_read_b128 v[96:99], v124 offset:128
	s_waitcnt lgkmcnt(0)
	v_mfma_f32_32x32x16_bf16 v[48:63], v[84:87], v[96:99], v[48:63]
	v_mfma_f32_32x32x16_bf16 v[32:47], v[88:91], v[96:99], v[32:47]
	v_mfma_f32_32x32x16_bf16 v[16:31], v[144:147], v[96:99], v[16:31]
	v_mfma_f32_32x32x16_bf16 v[0:15], v[92:95], v[96:99], v[0:15]
	ds_read_b128 v[92:95], v124 offset:160
	s_waitcnt lgkmcnt(0)
	v_mfma_f32_32x32x16_bf16 v[48:63], v[76:79], v[92:95], v[48:63]
	v_mfma_f32_32x32x16_bf16 v[32:47], v[72:75], v[92:95], v[32:47]
	v_mfma_f32_32x32x16_bf16 v[16:31], v[116:119], v[92:95], v[16:31]
	v_mfma_f32_32x32x16_bf16 v[0:15], v[100:103], v[92:95], v[0:15]
	ds_read_b128 v[92:95], v124 offset:192
	s_waitcnt lgkmcnt(0)
	v_mfma_f32_32x32x16_bf16 v[48:63], v[80:83], v[92:95], v[48:63]
	v_mfma_f32_32x32x16_bf16 v[32:47], v[84:87], v[92:95], v[32:47]
	v_mfma_f32_32x32x16_bf16 v[16:31], v[88:91], v[92:95], v[16:31]
	ds_read_b128 v[86:89], v124 offset:224
	s_waitcnt lgkmcnt(0)
	v_mfma_f32_32x32x16_bf16 v[48:63], v[68:71], v[86:89], v[48:63]
	v_mfma_f32_32x32x16_bf16 v[16:31], v[72:75], v[86:89], v[16:31]
	v_mfma_f32_32x32x16_bf16 v[32:47], v[76:79], v[86:89], v[32:47]
	v_mfma_f32_32x32x16_bf16 v[0:15], v[144:147], v[92:95], v[0:15]
	v_mfma_f32_32x32x16_bf16 v[0:15], v[116:119], v[86:89], v[0:15]
	s_waitcnt lgkmcnt(0)
	s_barrier
; DI void hyena_item(const P& p, int l, int c, char* smem) {
;     ...
;   if (cwv) {
;     const float d1 = p.fbias[(size_t)(l * 2 + 1) * 512 + c];
;     const float x0 = cw[1024 + c], x1 = cw[1536 + 1024 + c], x2 = cw[3072 + 1024 + c], xb = cbias[1024 + c];
;     const u16* rowx = p.hyT + (size_t)(1024 + c) * HYP + bt * SEQ;
;     const u16* rowg = p.hyT + (size_t)(1536 + c) * HYP + bt * SEQ;
;     u16* dst = p.YhT + (size_t)c * HYP + bt * SEQ;
; #pragma unroll
;     for (int I = 0; I < 4; ++I)
; #pragma unroll
;       for (int rq = 0; rq < 4; ++rq) {
;         const int bq = 32 * I + 8 * rq + 4 * g;
;         const int t4 = 128 * a + bq;
;         float px[4];
;         sconv4(rowx, t4, x0, x1, x2, xb, px);
;         const uint2 zv = *(const uint2*)(U + (bt * 64 + a) * 136 + bq);
;         const uint2 gv = *(const uint2*)(rowg + t4);
	v_and_b32_e32 v249, 0xff, v198
	v_lshlrev_b32_e32 v249, 4, v249
	s_and_b64 vcc, exec, s[100:101]
	s_cbranch_vccnz .Lhy1_rd_main
	s_nop 15
	ds_write_b128 v249, v[0:3] offset:0
	ds_write_b128 v249, v[4:7] offset:4096
	ds_write_b128 v249, v[8:11] offset:8192
	ds_write_b128 v249, v[12:15] offset:12288
	ds_write_b128 v249, v[16:19] offset:16384
	ds_write_b128 v249, v[20:23] offset:20480
	ds_write_b128 v249, v[24:27] offset:24576
	ds_write_b128 v249, v[28:31] offset:28672
	ds_write_b128 v249, v[32:35] offset:32768
	ds_write_b128 v249, v[36:39] offset:36864
	ds_write_b128 v249, v[40:43] offset:40960
	ds_write_b128 v249, v[44:47] offset:45056
	ds_write_b128 v249, v[48:51] offset:49152
	ds_write_b128 v249, v[52:55] offset:53248
	ds_write_b128 v249, v[56:59] offset:57344
	ds_write_b128 v249, v[60:63] offset:61440
	s_waitcnt lgkmcnt(0)
.Lhy1_rd_main:
	s_barrier
	s_and_b64 vcc, exec, s[100:101]
	s_cbranch_vccz .Lhy1_skip
	ds_read_b128 v[88:91], v249 offset:0
	ds_read_b128 v[92:95], v249 offset:4096
	ds_read_b128 v[96:99], v249 offset:8192
	ds_read_b128 v[100:103], v249 offset:12288
	ds_read_b128 v[104:107], v249 offset:16384
	ds_read_b128 v[108:111], v249 offset:20480
	ds_read_b128 v[112:115], v249 offset:24576
	ds_read_b128 v[116:119], v249 offset:28672
	ds_read_b128 v[120:123], v249 offset:32768
	s_waitcnt lgkmcnt(8)
	v_add_f32_e32 v0, v0, v88
	v_add_f32_e32 v1, v1, v89
	v_add_f32_e32 v2, v2, v90
	v_add_f32_e32 v3, v3, v91
	ds_read_b128 v[124:127], v249 offset:36864
	s_waitcnt lgkmcnt(8)
	v_add_f32_e32 v4, v4, v92
	v_add_f32_e32 v5, v5, v93
	v_add_f32_e32 v6, v6, v94
	v_add_f32_e32 v7, v7, v95
	ds_read_b128 v[128:131], v249 offset:40960
	s_waitcnt lgkmcnt(8)
	v_add_f32_e32 v8, v8, v96
	v_add_f32_e32 v9, v9, v97
	v_add_f32_e32 v10, v10, v98
	v_add_f32_e32 v11, v11, v99
	ds_read_b128 v[132:135], v249 offset:45056
	s_waitcnt lgkmcnt(8)
	v_add_f32_e32 v12, v12, v100
	v_add_f32_e32 v13, v13, v101
	v_add_f32_e32 v14, v14, v102
	v_add_f32_e32 v15, v15, v103
	ds_read_b128 v[136:139], v249 offset:49152
	s_waitcnt lgkmcnt(8)
	v_add_f32_e32 v16, v16, v104
	v_add_f32_e32 v17, v17, v105
	v_add_f32_e32 v18, v18, v106
	v_add_f32_e32 v19, v19, v107
	ds_read_b128 v[140:143], v249 offset:53248
	s_waitcnt lgkmcnt(8)
	v_add_f32_e32 v20, v20, v108
	v_add_f32_e32 v21, v21, v109
	v_add_f32_e32 v22, v22, v110
	v_add_f32_e32 v23, v23, v111
	ds_read_b128 v[144:147], v249 offset:57344
	s_waitcnt lgkmcnt(8)
	v_add_f32_e32 v24, v24, v112
	v_add_f32_e32 v25, v25, v113
	v_add_f32_e32 v26, v26, v114
	v_add_f32_e32 v27, v27, v115
	ds_read_b128 v[148:151], v249 offset:61440
	s_waitcnt lgkmcnt(8)
	v_add_f32_e32 v28, v28, v116
	v_add_f32_e32 v29, v29, v117
	v_add_f32_e32 v30, v30, v118
	v_add_f32_e32 v31, v31, v119
	s_waitcnt lgkmcnt(7)
	v_add_f32_e32 v32, v32, v120
	v_add_f32_e32 v33, v33, v121
	v_add_f32_e32 v34, v34, v122
	v_add_f32_e32 v35, v35, v123
	s_waitcnt lgkmcnt(6)
	v_add_f32_e32 v36, v36, v124
	v_add_f32_e32 v37, v37, v125
	v_add_f32_e32 v38, v38, v126
	v_add_f32_e32 v39, v39, v127
	s_waitcnt lgkmcnt(5)
	v_add_f32_e32 v40, v40, v128
	v_add_f32_e32 v41, v41, v129
	v_add_f32_e32 v42, v42, v130
	v_add_f32_e32 v43, v43, v131
	s_waitcnt lgkmcnt(4)
	v_add_f32_e32 v44, v44, v132
	v_add_f32_e32 v45, v45, v133
	v_add_f32_e32 v46, v46, v134
	v_add_f32_e32 v47, v47, v135
	s_waitcnt lgkmcnt(3)
	v_add_f32_e32 v48, v48, v136
	v_add_f32_e32 v49, v49, v137
	v_add_f32_e32 v50, v50, v138
	v_add_f32_e32 v51, v51, v139
	s_waitcnt lgkmcnt(2)
	v_add_f32_e32 v52, v52, v140
	v_add_f32_e32 v53, v53, v141
	v_add_f32_e32 v54, v54, v142
	v_add_f32_e32 v55, v55, v143
	s_waitcnt lgkmcnt(1)
	v_add_f32_e32 v56, v56, v144
	v_add_f32_e32 v57, v57, v145
	v_add_f32_e32 v58, v58, v146
	v_add_f32_e32 v59, v59, v147
	s_waitcnt lgkmcnt(0)
	v_add_f32_e32 v60, v60, v148
	v_add_f32_e32 v61, v61, v149
	v_add_f32_e32 v62, v62, v150
	v_add_f32_e32 v63, v63, v151
	global_load_dword v82, v204, s[74:75] offset:2048
	global_load_dword v80, v207, s[74:75]
	global_load_dword v68, v189, s[6:7] offset:2048
	global_load_dword v83, v189, s[76:77]
	global_load_dword v70, v189, s[14:15]
	s_or_b32 s98, s72, 0x400
	s_mul_hi_u32 s99, s98, 0x8080
	s_mul_i32 s98, s98, 0x8080
	s_add_u32 s98, s36, s98
	s_addc_u32 s99, s37, s99
	s_add_u32 s98, s98, -4
	s_addc_u32 s99, s99, -1
	s_or_b32 s100, s72, 0x600
	s_mul_hi_u32 s101, s100, 0x8080
	s_mul_i32 s100, s100, 0x8080
	s_add_u32 s100, s36, s100
	s_addc_u32 s101, s37, s101
	s_add_u32 s6, s48, s96
	s_addc_u32 s7, s49, s73
	v_lshl_add_u32 v234, v233, 1, v184
	global_load_dwordx4 v[88:91], v234, s[98:99] offset:0
	global_load_dwordx2 v[92:93], v234, s[100:101] offset:0
	global_load_dwordx4 v[94:97], v234, s[98:99] offset:16
	global_load_dwordx2 v[98:99], v234, s[100:101] offset:16
	global_load_dwordx4 v[100:103], v234, s[98:99] offset:32
	global_load_dwordx2 v[104:105], v234, s[100:101] offset:32
	global_load_dwordx4 v[106:109], v234, s[98:99] offset:48
	global_load_dwordx2 v[110:111], v234, s[100:101] offset:48
	global_load_dwordx4 v[112:115], v234, s[98:99] offset:64
	global_load_dwordx2 v[116:117], v234, s[100:101] offset:64
	global_load_dwordx4 v[118:121], v234, s[98:99] offset:80
	global_load_dwordx2 v[122:123], v234, s[100:101] offset:80
	global_load_dwordx4 v[124:127], v234, s[98:99] offset:96
	global_load_dwordx2 v[128:129], v234, s[100:101] offset:96
	global_load_dwordx4 v[130:133], v234, s[98:99] offset:112
	global_load_dwordx2 v[134:135], v234, s[100:101] offset:112
	v_add_f32_e32 v238, v64, v65
	v_add_f32_e32 v238, v238, v66
	v_add_f32_e32 v238, v238, v67
	v_div_scale_f32 v169, s[8:9], v238, v238, 1.0
	v_rcp_f32_e32 v170, v169
	s_nop 0
	v_fma_f32 v171, -v169, v170, 1.0
	v_fmac_f32_e32 v170, v171, v170
	v_div_scale_f32 v171, vcc, 1.0, v238, 1.0
	v_mul_f32_e32 v236, v171, v170
	v_fma_f32 v237, -v169, v236, v171
	v_fmac_f32_e32 v236, v237, v170
	v_fma_f32 v169, -v169, v236, v171
	v_div_fmas_f32 v169, v169, v170, v236
	v_div_fixup_f32 v238, v169, v238, 1.0
	v_lshl_or_b32 v235, v230, 6, v231
	v_mul_u32_u24_e32 v235, 0x110, v235
	v_lshlrev_b32_e32 v236, 1, v186
	v_add3_u32 v235, s69, v235, v236
	s_waitcnt vmcnt(8)
; DI float bf2f(unsigned v) { return __uint_as_float(v << 16); }
; DI float bflo(unsigned v) { return __uint_as_float(v << 16); }
; DI float bfhi(unsigned v) { return __uint_as_float(v & 0xffff0000u); }
; DI float siluf(float x) { return x * __builtin_amdgcn_rcpf(1.f + __expf(-x)); }
; DI void sconv4(const u16* row, int t4, float w0, float w1, float w2, float bias, float (&o)[4]) {
;   const uint2 v = *(const uint2*)(row + t4);
;   const float x0 = bflo(v.x), x1 = bfhi(v.x), x2 = bflo(v.y), x3 = bfhi(v.y);
;   const float xm = (t4 > 0) ? bf2f(row[t4 - 1]) : 0.f;
;   const float xp = (t4 + 4 < SEQ) ? bf2f(row[t4 + 4]) : 0.f;
;   o[0] = w0 * xm + w1 * x0 + w2 * x1 + bias;
;   o[1] = w0 * x0 + w1 * x1 + w2 * x2 + bias;
;   o[2] = w0 * x1 + w1 * x2 + w2 * x3 + bias;
;   o[3] = w0 * x2 + w1 * x3 + w2 * xp + bias;
; }
; DI void hyena_item(const P& p, int l, int c, char* smem) {
;     ...
;       for (int rq = 0; rq < 4; ++rq) {
;         const int bq = 32 * I + 8 * rq + 4 * g;
;         const int t4 = 128 * a + bq;
;         float px[4];
;         sconv4(rowx, t4, x0, x1, x2, xb, px);
;         const uint2 zv = *(const uint2*)(U + (bt * 64 + a) * 136 + bq);
;         const uint2 gv = *(const uint2*)(rowg + t4);
;         const float z1[4] = {bflo(zv.x), bfhi(zv.x), bflo(zv.y), bfhi(zv.y)};
;         const float gt[4] = {bflo(gv.x), bfhi(gv.x), bflo(gv.y), bfhi(gv.y)};
;         float yy[4];
; #pragma unroll
;         for (int j = 0; j < 4; ++j) yy[j] = px[j] * (acc[I][4 * rq + j] * invn1 + z1[j] * d1) * siluf(gt[j]);
;         uint2 ov; ov.x = pack2(yy[0], yy[1]); ov.y = pack2(yy[2], yy[3]);
;         *(uint2*)(dst + t4) = ov;
;       }
	ds_read_b64 v[160:161], v235 offset:0
	ds_read_b64 v[162:163], v235 offset:16
	ds_read_b64 v[164:165], v235 offset:32
	ds_read_b64 v[166:167], v235 offset:48
	v_cmp_ne_u32_e32 vcc, 0, v233
	s_nop 1
	v_and_b32_e32 v168, 0xffff0000, v88
	v_cndmask_b32_e32 v168, 0, v168, vcc
	v_lshlrev_b32_e32 v169, 16, v89
	v_and_b32_e32 v170, 0xffff0000, v89
	v_lshlrev_b32_e32 v171, 16, v90
	v_and_b32_e32 v172, 0xffff0000, v90
	v_lshlrev_b32_e32 v173, 16, v91
	v_mul_f32_e32 v178, v83, v168
	v_fmac_f32_e32 v178, v82, v169
	v_fmac_f32_e32 v178, v80, v170
	v_add_f32_e32 v178, v70, v178
	v_mul_f32_e32 v179, v83, v169
	v_fmac_f32_e32 v179, v82, v170
	v_fmac_f32_e32 v179, v80, v171
	v_add_f32_e32 v179, v70, v179
	v_mul_f32_e32 v180, v83, v170
	v_fmac_f32_e32 v180, v82, v171
	v_fmac_f32_e32 v180, v80, v172
	v_add_f32_e32 v180, v70, v180
	v_mul_f32_e32 v181, v83, v171
	v_fmac_f32_e32 v181, v82, v172
	v_fmac_f32_e32 v181, v80, v173
	v_add_f32_e32 v181, v70, v181
	s_waitcnt lgkmcnt(0)
	v_lshlrev_b32_e32 v174, 16, v160
	v_and_b32_e32 v175, 0xffff0000, v160
	v_lshlrev_b32_e32 v176, 16, v161
	v_and_b32_e32 v177, 0xffff0000, v161
	v_mul_f32_e32 v174, v68, v174
	v_mul_f32_e32 v175, v68, v175
	v_mul_f32_e32 v176, v68, v176
	v_mul_f32_e32 v177, v68, v177
	v_fmac_f32_e32 v174, v238, v48
	v_fmac_f32_e32 v175, v238, v49
	v_fmac_f32_e32 v176, v238, v50
	v_fmac_f32_e32 v177, v238, v51
	v_mul_f32_e32 v174, v178, v174
	v_mul_f32_e32 v175, v179, v175
	v_mul_f32_e32 v176, v180, v176
	v_mul_f32_e32 v177, v181, v177
	v_lshlrev_b32_e32 v168, 16, v92
	v_and_b32_e32 v169, 0xffff0000, v92
	v_lshlrev_b32_e32 v170, 16, v93
	v_and_b32_e32 v171, 0xffff0000, v93
	v_mul_f32_e32 v178, 0xbfb8aa3b, v168
	v_mul_f32_e32 v179, 0xbfb8aa3b, v169
	v_mul_f32_e32 v180, 0xbfb8aa3b, v170
	v_mul_f32_e32 v181, 0xbfb8aa3b, v171
	v_exp_f32_e32 v178, v178
	v_exp_f32_e32 v179, v179
	v_exp_f32_e32 v180, v180
	v_exp_f32_e32 v181, v181
	v_add_f32_e32 v178, 1.0, v178
	v_add_f32_e32 v179, 1.0, v179
	v_add_f32_e32 v180, 1.0, v180
	v_add_f32_e32 v181, 1.0, v181
	v_rcp_f32_e32 v178, v178
	v_rcp_f32_e32 v179, v179
	v_rcp_f32_e32 v180, v180
	v_rcp_f32_e32 v181, v181
	v_mul_f32_e32 v178, v178, v168
	v_mul_f32_e32 v179, v179, v169
	v_mul_f32_e32 v180, v180, v170
	v_mul_f32_e32 v181, v181, v171
	v_mul_f32_e32 v174, v174, v178
	v_mul_f32_e32 v175, v175, v179
	v_mul_f32_e32 v176, v176, v180
	v_mul_f32_e32 v177, v177, v181
	v_cvt_pk_bf16_f32 v182, v174, v175
	v_cvt_pk_bf16_f32 v183, v176, v177
	global_store_dwordx2 v234, v[182:183], s[6:7] offset:0
	v_and_b32_e32 v168, 0xffff0000, v94
	v_lshlrev_b32_e32 v169, 16, v95
	v_and_b32_e32 v170, 0xffff0000, v95
	v_lshlrev_b32_e32 v171, 16, v96
	v_and_b32_e32 v172, 0xffff0000, v96
	v_lshlrev_b32_e32 v173, 16, v97
	v_mul_f32_e32 v178, v83, v168
	v_fmac_f32_e32 v178, v82, v169
	v_fmac_f32_e32 v178, v80, v170
	v_add_f32_e32 v178, v70, v178
	v_mul_f32_e32 v179, v83, v169
	v_fmac_f32_e32 v179, v82, v170
	v_fmac_f32_e32 v179, v80, v171
	v_add_f32_e32 v179, v70, v179
	v_mul_f32_e32 v180, v83, v170
	v_fmac_f32_e32 v180, v82, v171
	v_fmac_f32_e32 v180, v80, v172
	v_add_f32_e32 v180, v70, v180
	v_mul_f32_e32 v181, v83, v171
	v_fmac_f32_e32 v181, v82, v172
	v_fmac_f32_e32 v181, v80, v173
	v_add_f32_e32 v181, v70, v181
	v_lshlrev_b32_e32 v174, 16, v162
	v_and_b32_e32 v175, 0xffff0000, v162
	v_lshlrev_b32_e32 v176, 16, v163
	v_and_b32_e32 v177, 0xffff0000, v163
	v_mul_f32_e32 v174, v68, v174
	v_mul_f32_e32 v175, v68, v175
	v_mul_f32_e32 v176, v68, v176
	v_mul_f32_e32 v177, v68, v177
	v_fmac_f32_e32 v174, v238, v52
	v_fmac_f32_e32 v175, v238, v53
	v_fmac_f32_e32 v176, v238, v54
	v_fmac_f32_e32 v177, v238, v55
	v_mul_f32_e32 v174, v178, v174
	v_mul_f32_e32 v175, v179, v175
	v_mul_f32_e32 v176, v180, v176
	v_mul_f32_e32 v177, v181, v177
	v_lshlrev_b32_e32 v168, 16, v98
	v_and_b32_e32 v169, 0xffff0000, v98
	v_lshlrev_b32_e32 v170, 16, v99
	v_and_b32_e32 v171, 0xffff0000, v99
	v_mul_f32_e32 v178, 0xbfb8aa3b, v168
	v_mul_f32_e32 v179, 0xbfb8aa3b, v169
	v_mul_f32_e32 v180, 0xbfb8aa3b, v170
	v_mul_f32_e32 v181, 0xbfb8aa3b, v171
	v_exp_f32_e32 v178, v178
	v_exp_f32_e32 v179, v179
	v_exp_f32_e32 v180, v180
	v_exp_f32_e32 v181, v181
	v_add_f32_e32 v178, 1.0, v178
	v_add_f32_e32 v179, 1.0, v179
	v_add_f32_e32 v180, 1.0, v180
	v_add_f32_e32 v181, 1.0, v181
	v_rcp_f32_e32 v178, v178
	v_rcp_f32_e32 v179, v179
	v_rcp_f32_e32 v180, v180
	v_rcp_f32_e32 v181, v181
	v_mul_f32_e32 v178, v178, v168
	v_mul_f32_e32 v179, v179, v169
	v_mul_f32_e32 v180, v180, v170
	v_mul_f32_e32 v181, v181, v171
	v_mul_f32_e32 v174, v174, v178
	v_mul_f32_e32 v175, v175, v179
	v_mul_f32_e32 v176, v176, v180
	v_mul_f32_e32 v177, v177, v181
	v_cvt_pk_bf16_f32 v182, v174, v175
	v_cvt_pk_bf16_f32 v183, v176, v177
	global_store_dwordx2 v234, v[182:183], s[6:7] offset:16
	v_and_b32_e32 v168, 0xffff0000, v100
	v_lshlrev_b32_e32 v169, 16, v101
	v_and_b32_e32 v170, 0xffff0000, v101
	v_lshlrev_b32_e32 v171, 16, v102
	v_and_b32_e32 v172, 0xffff0000, v102
	v_lshlrev_b32_e32 v173, 16, v103
	v_mul_f32_e32 v178, v83, v168
	v_fmac_f32_e32 v178, v82, v169
	v_fmac_f32_e32 v178, v80, v170
	v_add_f32_e32 v178, v70, v178
	v_mul_f32_e32 v179, v83, v169
	v_fmac_f32_e32 v179, v82, v170
	v_fmac_f32_e32 v179, v80, v171
	v_add_f32_e32 v179, v70, v179
	v_mul_f32_e32 v180, v83, v170
	v_fmac_f32_e32 v180, v82, v171
	v_fmac_f32_e32 v180, v80, v172
	v_add_f32_e32 v180, v70, v180
	v_mul_f32_e32 v181, v83, v171
	v_fmac_f32_e32 v181, v82, v172
	v_fmac_f32_e32 v181, v80, v173
	v_add_f32_e32 v181, v70, v181
	v_lshlrev_b32_e32 v174, 16, v164
	v_and_b32_e32 v175, 0xffff0000, v164
	v_lshlrev_b32_e32 v176, 16, v165
	v_and_b32_e32 v177, 0xffff0000, v165
	v_mul_f32_e32 v174, v68, v174
; DI float bf2f(unsigned v) { return __uint_as_float(v << 16); }
; DI float bflo(unsigned v) { return __uint_as_float(v << 16); }
; DI float bfhi(unsigned v) { return __uint_as_float(v & 0xffff0000u); }
; DI float siluf(float x) { return x * __builtin_amdgcn_rcpf(1.f + __expf(-x)); }
; DI void sconv4(const u16* row, int t4, float w0, float w1, float w2, float bias, float (&o)[4]) {
;   const uint2 v = *(const uint2*)(row + t4);
;   const float x0 = bflo(v.x), x1 = bfhi(v.x), x2 = bflo(v.y), x3 = bfhi(v.y);
;   const float xm = (t4 > 0) ? bf2f(row[t4 - 1]) : 0.f;
;   const float xp = (t4 + 4 < SEQ) ? bf2f(row[t4 + 4]) : 0.f;
;   o[0] = w0 * xm + w1 * x0 + w2 * x1 + bias;
;   o[1] = w0 * x0 + w1 * x1 + w2 * x2 + bias;
;   o[2] = w0 * x1 + w1 * x2 + w2 * x3 + bias;
;   o[3] = w0 * x2 + w1 * x3 + w2 * xp + bias;
; }
; DI void hyena_item(const P& p, int l, int c, char* smem) {
;     ...
;       for (int rq = 0; rq < 4; ++rq) {
;         const int bq = 32 * I + 8 * rq + 4 * g;
;         const int t4 = 128 * a + bq;
;         float px[4];
;         sconv4(rowx, t4, x0, x1, x2, xb, px);
;         const uint2 zv = *(const uint2*)(U + (bt * 64 + a) * 136 + bq);
;         const uint2 gv = *(const uint2*)(rowg + t4);
;         const float z1[4] = {bflo(zv.x), bfhi(zv.x), bflo(zv.y), bfhi(zv.y)};
;         const float gt[4] = {bflo(gv.x), bfhi(gv.x), bflo(gv.y), bfhi(gv.y)};
;         float yy[4];
; #pragma unroll
;         for (int j = 0; j < 4; ++j) yy[j] = px[j] * (acc[I][4 * rq + j] * invn1 + z1[j] * d1) * siluf(gt[j]);
;         uint2 ov; ov.x = pack2(yy[0], yy[1]); ov.y = pack2(yy[2], yy[3]);
;         *(uint2*)(dst + t4) = ov;
;       }
	v_mul_f32_e32 v175, v68, v175
	v_mul_f32_e32 v176, v68, v176
	v_mul_f32_e32 v177, v68, v177
	v_fmac_f32_e32 v174, v238, v56
	v_fmac_f32_e32 v175, v238, v57
	v_fmac_f32_e32 v176, v238, v58
	v_fmac_f32_e32 v177, v238, v59
	v_mul_f32_e32 v174, v178, v174
	v_mul_f32_e32 v175, v179, v175
	v_mul_f32_e32 v176, v180, v176
	v_mul_f32_e32 v177, v181, v177
	v_lshlrev_b32_e32 v168, 16, v104
	v_and_b32_e32 v169, 0xffff0000, v104
	v_lshlrev_b32_e32 v170, 16, v105
	v_and_b32_e32 v171, 0xffff0000, v105
	v_mul_f32_e32 v178, 0xbfb8aa3b, v168
	v_mul_f32_e32 v179, 0xbfb8aa3b, v169
	v_mul_f32_e32 v180, 0xbfb8aa3b, v170
	v_mul_f32_e32 v181, 0xbfb8aa3b, v171
	v_exp_f32_e32 v178, v178
	v_exp_f32_e32 v179, v179
	v_exp_f32_e32 v180, v180
	v_exp_f32_e32 v181, v181
	v_add_f32_e32 v178, 1.0, v178
	v_add_f32_e32 v179, 1.0, v179
	v_add_f32_e32 v180, 1.0, v180
	v_add_f32_e32 v181, 1.0, v181
	v_rcp_f32_e32 v178, v178
	v_rcp_f32_e32 v179, v179
	v_rcp_f32_e32 v180, v180
	v_rcp_f32_e32 v181, v181
	v_mul_f32_e32 v178, v178, v168
	v_mul_f32_e32 v179, v179, v169
	v_mul_f32_e32 v180, v180, v170
	v_mul_f32_e32 v181, v181, v171
	v_mul_f32_e32 v174, v174, v178
	v_mul_f32_e32 v175, v175, v179
	v_mul_f32_e32 v176, v176, v180
	v_mul_f32_e32 v177, v177, v181
	v_cvt_pk_bf16_f32 v182, v174, v175
	v_cvt_pk_bf16_f32 v183, v176, v177
	global_store_dwordx2 v234, v[182:183], s[6:7] offset:32
	v_and_b32_e32 v168, 0xffff0000, v106
	v_lshlrev_b32_e32 v169, 16, v107
	v_and_b32_e32 v170, 0xffff0000, v107
	v_lshlrev_b32_e32 v171, 16, v108
	v_and_b32_e32 v172, 0xffff0000, v108
	v_lshlrev_b32_e32 v173, 16, v109
	v_mul_f32_e32 v178, v83, v168
	v_fmac_f32_e32 v178, v82, v169
	v_fmac_f32_e32 v178, v80, v170
	v_add_f32_e32 v178, v70, v178
	v_mul_f32_e32 v179, v83, v169
	v_fmac_f32_e32 v179, v82, v170
	v_fmac_f32_e32 v179, v80, v171
	v_add_f32_e32 v179, v70, v179
	v_mul_f32_e32 v180, v83, v170
	v_fmac_f32_e32 v180, v82, v171
	v_fmac_f32_e32 v180, v80, v172
	v_add_f32_e32 v180, v70, v180
	v_mul_f32_e32 v181, v83, v171
	v_fmac_f32_e32 v181, v82, v172
	v_fmac_f32_e32 v181, v80, v173
	v_add_f32_e32 v181, v70, v181
	v_lshlrev_b32_e32 v174, 16, v166
	v_and_b32_e32 v175, 0xffff0000, v166
	v_lshlrev_b32_e32 v176, 16, v167
	v_and_b32_e32 v177, 0xffff0000, v167
	v_mul_f32_e32 v174, v68, v174
	v_mul_f32_e32 v175, v68, v175
	v_mul_f32_e32 v176, v68, v176
	v_mul_f32_e32 v177, v68, v177
	v_fmac_f32_e32 v174, v238, v60
	v_fmac_f32_e32 v175, v238, v61
	v_fmac_f32_e32 v176, v238, v62
	v_fmac_f32_e32 v177, v238, v63
	v_mul_f32_e32 v174, v178, v174
	v_mul_f32_e32 v175, v179, v175
	v_mul_f32_e32 v176, v180, v176
	v_mul_f32_e32 v177, v181, v177
	v_lshlrev_b32_e32 v168, 16, v110
	v_and_b32_e32 v169, 0xffff0000, v110
	v_lshlrev_b32_e32 v170, 16, v111
	v_and_b32_e32 v171, 0xffff0000, v111
	v_mul_f32_e32 v178, 0xbfb8aa3b, v168
	v_mul_f32_e32 v179, 0xbfb8aa3b, v169
	v_mul_f32_e32 v180, 0xbfb8aa3b, v170
	v_mul_f32_e32 v181, 0xbfb8aa3b, v171
	v_exp_f32_e32 v178, v178
	v_exp_f32_e32 v179, v179
	v_exp_f32_e32 v180, v180
	v_exp_f32_e32 v181, v181
	v_add_f32_e32 v178, 1.0, v178
	v_add_f32_e32 v179, 1.0, v179
	v_add_f32_e32 v180, 1.0, v180
	v_add_f32_e32 v181, 1.0, v181
	v_rcp_f32_e32 v178, v178
	v_rcp_f32_e32 v179, v179
	v_rcp_f32_e32 v180, v180
	v_rcp_f32_e32 v181, v181
	v_mul_f32_e32 v178, v178, v168
	v_mul_f32_e32 v179, v179, v169
	v_mul_f32_e32 v180, v180, v170
	v_mul_f32_e32 v181, v181, v171
	v_mul_f32_e32 v174, v174, v178
	v_mul_f32_e32 v175, v175, v179
	v_mul_f32_e32 v176, v176, v180
	v_mul_f32_e32 v177, v177, v181
	v_cvt_pk_bf16_f32 v182, v174, v175
	v_cvt_pk_bf16_f32 v183, v176, v177
	global_store_dwordx2 v234, v[182:183], s[6:7] offset:48
	global_load_dwordx4 v[136:139], v234, s[98:99] offset:128
	global_load_dwordx2 v[140:141], v234, s[100:101] offset:128
	global_load_dwordx4 v[142:145], v234, s[98:99] offset:144
	global_load_dwordx2 v[146:147], v234, s[100:101] offset:144
	global_load_dwordx4 v[148:151], v234, s[98:99] offset:160
	global_load_dwordx2 v[152:153], v234, s[100:101] offset:160
	global_load_dwordx4 v[154:157], v234, s[98:99] offset:176
	global_load_dwordx2 v[158:159], v234, s[100:101] offset:176
	s_waitcnt vmcnt(12)
	ds_read_b64 v[160:161], v235 offset:64
	ds_read_b64 v[162:163], v235 offset:80
	ds_read_b64 v[164:165], v235 offset:96
	ds_read_b64 v[166:167], v235 offset:112
	v_and_b32_e32 v168, 0xffff0000, v112
	v_lshlrev_b32_e32 v169, 16, v113
	v_and_b32_e32 v170, 0xffff0000, v113
	v_lshlrev_b32_e32 v171, 16, v114
	v_and_b32_e32 v172, 0xffff0000, v114
	v_lshlrev_b32_e32 v173, 16, v115
	v_mul_f32_e32 v178, v83, v168
	v_fmac_f32_e32 v178, v82, v169
	v_fmac_f32_e32 v178, v80, v170
	v_add_f32_e32 v178, v70, v178
	v_mul_f32_e32 v179, v83, v169
	v_fmac_f32_e32 v179, v82, v170
	v_fmac_f32_e32 v179, v80, v171
	v_add_f32_e32 v179, v70, v179
	v_mul_f32_e32 v180, v83, v170
	v_fmac_f32_e32 v180, v82, v171
	v_fmac_f32_e32 v180, v80, v172
	v_add_f32_e32 v180, v70, v180
	v_mul_f32_e32 v181, v83, v171
	v_fmac_f32_e32 v181, v82, v172
	v_fmac_f32_e32 v181, v80, v173
	v_add_f32_e32 v181, v70, v181
	s_waitcnt lgkmcnt(0)
; DI float bf2f(unsigned v) { return __uint_as_float(v << 16); }
; DI float bflo(unsigned v) { return __uint_as_float(v << 16); }
; DI float bfhi(unsigned v) { return __uint_as_float(v & 0xffff0000u); }
; DI float siluf(float x) { return x * __builtin_amdgcn_rcpf(1.f + __expf(-x)); }
; DI void sconv4(const u16* row, int t4, float w0, float w1, float w2, float bias, float (&o)[4]) {
;   const uint2 v = *(const uint2*)(row + t4);
;   const float x0 = bflo(v.x), x1 = bfhi(v.x), x2 = bflo(v.y), x3 = bfhi(v.y);
;   const float xm = (t4 > 0) ? bf2f(row[t4 - 1]) : 0.f;
;   const float xp = (t4 + 4 < SEQ) ? bf2f(row[t4 + 4]) : 0.f;
;   o[0] = w0 * xm + w1 * x0 + w2 * x1 + bias;
;   o[1] = w0 * x0 + w1 * x1 + w2 * x2 + bias;
;   o[2] = w0 * x1 + w1 * x2 + w2 * x3 + bias;
;   o[3] = w0 * x2 + w1 * x3 + w2 * xp + bias;
; }
; DI void hyena_item(const P& p, int l, int c, char* smem) {
;     ...
;       for (int rq = 0; rq < 4; ++rq) {
;         const int bq = 32 * I + 8 * rq + 4 * g;
;         const int t4 = 128 * a + bq;
;         float px[4];
;         sconv4(rowx, t4, x0, x1, x2, xb, px);
;         const uint2 zv = *(const uint2*)(U + (bt * 64 + a) * 136 + bq);
;         const uint2 gv = *(const uint2*)(rowg + t4);
;         const float z1[4] = {bflo(zv.x), bfhi(zv.x), bflo(zv.y), bfhi(zv.y)};
;         const float gt[4] = {bflo(gv.x), bfhi(gv.x), bflo(gv.y), bfhi(gv.y)};
;         float yy[4];
; #pragma unroll
;         for (int j = 0; j < 4; ++j) yy[j] = px[j] * (acc[I][4 * rq + j] * invn1 + z1[j] * d1) * siluf(gt[j]);
;         uint2 ov; ov.x = pack2(yy[0], yy[1]); ov.y = pack2(yy[2], yy[3]);
;         *(uint2*)(dst + t4) = ov;
;       }
	v_lshlrev_b32_e32 v174, 16, v160
	v_and_b32_e32 v175, 0xffff0000, v160
	v_lshlrev_b32_e32 v176, 16, v161
	v_and_b32_e32 v177, 0xffff0000, v161
	v_mul_f32_e32 v174, v68, v174
	v_mul_f32_e32 v175, v68, v175
	v_mul_f32_e32 v176, v68, v176
	v_mul_f32_e32 v177, v68, v177
	v_fmac_f32_e32 v174, v238, v32
	v_fmac_f32_e32 v175, v238, v33
	v_fmac_f32_e32 v176, v238, v34
	v_fmac_f32_e32 v177, v238, v35
	v_mul_f32_e32 v174, v178, v174
	v_mul_f32_e32 v175, v179, v175
	v_mul_f32_e32 v176, v180, v176
	v_mul_f32_e32 v177, v181, v177
	v_lshlrev_b32_e32 v168, 16, v116
	v_and_b32_e32 v169, 0xffff0000, v116
	v_lshlrev_b32_e32 v170, 16, v117
	v_and_b32_e32 v171, 0xffff0000, v117
	v_mul_f32_e32 v178, 0xbfb8aa3b, v168
	v_mul_f32_e32 v179, 0xbfb8aa3b, v169
	v_mul_f32_e32 v180, 0xbfb8aa3b, v170
	v_mul_f32_e32 v181, 0xbfb8aa3b, v171
	v_exp_f32_e32 v178, v178
	v_exp_f32_e32 v179, v179
	v_exp_f32_e32 v180, v180
	v_exp_f32_e32 v181, v181
	v_add_f32_e32 v178, 1.0, v178
	v_add_f32_e32 v179, 1.0, v179
	v_add_f32_e32 v180, 1.0, v180
	v_add_f32_e32 v181, 1.0, v181
	v_rcp_f32_e32 v178, v178
	v_rcp_f32_e32 v179, v179
	v_rcp_f32_e32 v180, v180
	v_rcp_f32_e32 v181, v181
	v_mul_f32_e32 v178, v178, v168
	v_mul_f32_e32 v179, v179, v169
	v_mul_f32_e32 v180, v180, v170
	v_mul_f32_e32 v181, v181, v171
	v_mul_f32_e32 v174, v174, v178
	v_mul_f32_e32 v175, v175, v179
	v_mul_f32_e32 v176, v176, v180
	v_mul_f32_e32 v177, v177, v181
	v_cvt_pk_bf16_f32 v182, v174, v175
	v_cvt_pk_bf16_f32 v183, v176, v177
	global_store_dwordx2 v234, v[182:183], s[6:7] offset:64
	v_and_b32_e32 v168, 0xffff0000, v118
	v_lshlrev_b32_e32 v169, 16, v119
	v_and_b32_e32 v170, 0xffff0000, v119
	v_lshlrev_b32_e32 v171, 16, v120
	v_and_b32_e32 v172, 0xffff0000, v120
	v_lshlrev_b32_e32 v173, 16, v121
	v_mul_f32_e32 v178, v83, v168
	v_fmac_f32_e32 v178, v82, v169
	v_fmac_f32_e32 v178, v80, v170
	v_add_f32_e32 v178, v70, v178
	v_mul_f32_e32 v179, v83, v169
	v_fmac_f32_e32 v179, v82, v170
	v_fmac_f32_e32 v179, v80, v171
	v_add_f32_e32 v179, v70, v179
	v_mul_f32_e32 v180, v83, v170
	v_fmac_f32_e32 v180, v82, v171
	v_fmac_f32_e32 v180, v80, v172
	v_add_f32_e32 v180, v70, v180
	v_mul_f32_e32 v181, v83, v171
	v_fmac_f32_e32 v181, v82, v172
	v_fmac_f32_e32 v181, v80, v173
	v_add_f32_e32 v181, v70, v181
	v_lshlrev_b32_e32 v174, 16, v162
	v_and_b32_e32 v175, 0xffff0000, v162
	v_lshlrev_b32_e32 v176, 16, v163
	v_and_b32_e32 v177, 0xffff0000, v163
	v_mul_f32_e32 v174, v68, v174
	v_mul_f32_e32 v175, v68, v175
	v_mul_f32_e32 v176, v68, v176
	v_mul_f32_e32 v177, v68, v177
	v_fmac_f32_e32 v174, v238, v36
	v_fmac_f32_e32 v175, v238, v37
	v_fmac_f32_e32 v176, v238, v38
	v_fmac_f32_e32 v177, v238, v39
	v_mul_f32_e32 v174, v178, v174
	v_mul_f32_e32 v175, v179, v175
	v_mul_f32_e32 v176, v180, v176
	v_mul_f32_e32 v177, v181, v177
	v_lshlrev_b32_e32 v168, 16, v122
	v_and_b32_e32 v169, 0xffff0000, v122
	v_lshlrev_b32_e32 v170, 16, v123
	v_and_b32_e32 v171, 0xffff0000, v123
	v_mul_f32_e32 v178, 0xbfb8aa3b, v168
	v_mul_f32_e32 v179, 0xbfb8aa3b, v169
	v_mul_f32_e32 v180, 0xbfb8aa3b, v170
	v_mul_f32_e32 v181, 0xbfb8aa3b, v171
	v_exp_f32_e32 v178, v178
	v_exp_f32_e32 v179, v179
	v_exp_f32_e32 v180, v180
	v_exp_f32_e32 v181, v181
	v_add_f32_e32 v178, 1.0, v178
	v_add_f32_e32 v179, 1.0, v179
	v_add_f32_e32 v180, 1.0, v180
	v_add_f32_e32 v181, 1.0, v181
	v_rcp_f32_e32 v178, v178
	v_rcp_f32_e32 v179, v179
	v_rcp_f32_e32 v180, v180
	v_rcp_f32_e32 v181, v181
	v_mul_f32_e32 v178, v178, v168
	v_mul_f32_e32 v179, v179, v169
	v_mul_f32_e32 v180, v180, v170
	v_mul_f32_e32 v181, v181, v171
	v_mul_f32_e32 v174, v174, v178
	v_mul_f32_e32 v175, v175, v179
	v_mul_f32_e32 v176, v176, v180
	v_mul_f32_e32 v177, v177, v181
	v_cvt_pk_bf16_f32 v182, v174, v175
	v_cvt_pk_bf16_f32 v183, v176, v177
	global_store_dwordx2 v234, v[182:183], s[6:7] offset:80
	v_and_b32_e32 v168, 0xffff0000, v124
	v_lshlrev_b32_e32 v169, 16, v125
	v_and_b32_e32 v170, 0xffff0000, v125
	v_lshlrev_b32_e32 v171, 16, v126
	v_and_b32_e32 v172, 0xffff0000, v126
	v_lshlrev_b32_e32 v173, 16, v127
	v_mul_f32_e32 v178, v83, v168
	v_fmac_f32_e32 v178, v82, v169
	v_fmac_f32_e32 v178, v80, v170
	v_add_f32_e32 v178, v70, v178
	v_mul_f32_e32 v179, v83, v169
	v_fmac_f32_e32 v179, v82, v170
	v_fmac_f32_e32 v179, v80, v171
	v_add_f32_e32 v179, v70, v179
	v_mul_f32_e32 v180, v83, v170
	v_fmac_f32_e32 v180, v82, v171
	v_fmac_f32_e32 v180, v80, v172
	v_add_f32_e32 v180, v70, v180
	v_mul_f32_e32 v181, v83, v171
	v_fmac_f32_e32 v181, v82, v172
	v_fmac_f32_e32 v181, v80, v173
	v_add_f32_e32 v181, v70, v181
	v_lshlrev_b32_e32 v174, 16, v164
	v_and_b32_e32 v175, 0xffff0000, v164
	v_lshlrev_b32_e32 v176, 16, v165
	v_and_b32_e32 v177, 0xffff0000, v165
	v_mul_f32_e32 v174, v68, v174
	v_mul_f32_e32 v175, v68, v175
	v_mul_f32_e32 v176, v68, v176
	v_mul_f32_e32 v177, v68, v177
	v_fmac_f32_e32 v174, v238, v40
	v_fmac_f32_e32 v175, v238, v41
	v_fmac_f32_e32 v176, v238, v42
	v_fmac_f32_e32 v177, v238, v43
	v_mul_f32_e32 v174, v178, v174
	v_mul_f32_e32 v175, v179, v175
	v_mul_f32_e32 v176, v180, v176
	v_mul_f32_e32 v177, v181, v177
	v_lshlrev_b32_e32 v168, 16, v128
	v_and_b32_e32 v169, 0xffff0000, v128
	v_lshlrev_b32_e32 v170, 16, v129
	v_and_b32_e32 v171, 0xffff0000, v129
	v_mul_f32_e32 v178, 0xbfb8aa3b, v168
	v_mul_f32_e32 v179, 0xbfb8aa3b, v169
	v_mul_f32_e32 v180, 0xbfb8aa3b, v170
	v_mul_f32_e32 v181, 0xbfb8aa3b, v171
	v_exp_f32_e32 v178, v178
	v_exp_f32_e32 v179, v179
	v_exp_f32_e32 v180, v180
	v_exp_f32_e32 v181, v181
	v_add_f32_e32 v178, 1.0, v178
	v_add_f32_e32 v179, 1.0, v179
	v_add_f32_e32 v180, 1.0, v180
	v_add_f32_e32 v181, 1.0, v181
	v_rcp_f32_e32 v178, v178
	v_rcp_f32_e32 v179, v179
	v_rcp_f32_e32 v180, v180
; DI float bf2f(unsigned v) { return __uint_as_float(v << 16); }
; DI float bflo(unsigned v) { return __uint_as_float(v << 16); }
; DI float bfhi(unsigned v) { return __uint_as_float(v & 0xffff0000u); }
; DI float siluf(float x) { return x * __builtin_amdgcn_rcpf(1.f + __expf(-x)); }
; DI void sconv4(const u16* row, int t4, float w0, float w1, float w2, float bias, float (&o)[4]) {
;   const uint2 v = *(const uint2*)(row + t4);
;   const float x0 = bflo(v.x), x1 = bfhi(v.x), x2 = bflo(v.y), x3 = bfhi(v.y);
;   const float xm = (t4 > 0) ? bf2f(row[t4 - 1]) : 0.f;
;   const float xp = (t4 + 4 < SEQ) ? bf2f(row[t4 + 4]) : 0.f;
;   o[0] = w0 * xm + w1 * x0 + w2 * x1 + bias;
;   o[1] = w0 * x0 + w1 * x1 + w2 * x2 + bias;
;   o[2] = w0 * x1 + w1 * x2 + w2 * x3 + bias;
;   o[3] = w0 * x2 + w1 * x3 + w2 * xp + bias;
; }
; DI void hyena_item(const P& p, int l, int c, char* smem) {
;     ...
;       for (int rq = 0; rq < 4; ++rq) {
;         const int bq = 32 * I + 8 * rq + 4 * g;
;         const int t4 = 128 * a + bq;
;         float px[4];
;         sconv4(rowx, t4, x0, x1, x2, xb, px);
;         const uint2 zv = *(const uint2*)(U + (bt * 64 + a) * 136 + bq);
;         const uint2 gv = *(const uint2*)(rowg + t4);
;         const float z1[4] = {bflo(zv.x), bfhi(zv.x), bflo(zv.y), bfhi(zv.y)};
;         const float gt[4] = {bflo(gv.x), bfhi(gv.x), bflo(gv.y), bfhi(gv.y)};
;         float yy[4];
; #pragma unroll
;         for (int j = 0; j < 4; ++j) yy[j] = px[j] * (acc[I][4 * rq + j] * invn1 + z1[j] * d1) * siluf(gt[j]);
;         uint2 ov; ov.x = pack2(yy[0], yy[1]); ov.y = pack2(yy[2], yy[3]);
;         *(uint2*)(dst + t4) = ov;
;       }
	v_rcp_f32_e32 v181, v181
	v_mul_f32_e32 v178, v178, v168
	v_mul_f32_e32 v179, v179, v169
	v_mul_f32_e32 v180, v180, v170
	v_mul_f32_e32 v181, v181, v171
	v_mul_f32_e32 v174, v174, v178
	v_mul_f32_e32 v175, v175, v179
	v_mul_f32_e32 v176, v176, v180
	v_mul_f32_e32 v177, v177, v181
	v_cvt_pk_bf16_f32 v182, v174, v175
	v_cvt_pk_bf16_f32 v183, v176, v177
	global_store_dwordx2 v234, v[182:183], s[6:7] offset:96
	v_and_b32_e32 v168, 0xffff0000, v130
	v_lshlrev_b32_e32 v169, 16, v131
	v_and_b32_e32 v170, 0xffff0000, v131
	v_lshlrev_b32_e32 v171, 16, v132
	v_and_b32_e32 v172, 0xffff0000, v132
	v_lshlrev_b32_e32 v173, 16, v133
	v_mul_f32_e32 v178, v83, v168
	v_fmac_f32_e32 v178, v82, v169
	v_fmac_f32_e32 v178, v80, v170
	v_add_f32_e32 v178, v70, v178
	v_mul_f32_e32 v179, v83, v169
	v_fmac_f32_e32 v179, v82, v170
	v_fmac_f32_e32 v179, v80, v171
	v_add_f32_e32 v179, v70, v179
	v_mul_f32_e32 v180, v83, v170
	v_fmac_f32_e32 v180, v82, v171
	v_fmac_f32_e32 v180, v80, v172
	v_add_f32_e32 v180, v70, v180
	v_mul_f32_e32 v181, v83, v171
	v_fmac_f32_e32 v181, v82, v172
	v_fmac_f32_e32 v181, v80, v173
	v_add_f32_e32 v181, v70, v181
	v_lshlrev_b32_e32 v174, 16, v166
	v_and_b32_e32 v175, 0xffff0000, v166
	v_lshlrev_b32_e32 v176, 16, v167
	v_and_b32_e32 v177, 0xffff0000, v167
	v_mul_f32_e32 v174, v68, v174
	v_mul_f32_e32 v175, v68, v175
	v_mul_f32_e32 v176, v68, v176
	v_mul_f32_e32 v177, v68, v177
	v_fmac_f32_e32 v174, v238, v44
	v_fmac_f32_e32 v175, v238, v45
	v_fmac_f32_e32 v176, v238, v46
	v_fmac_f32_e32 v177, v238, v47
	v_mul_f32_e32 v174, v178, v174
	v_mul_f32_e32 v175, v179, v175
	v_mul_f32_e32 v176, v180, v176
	v_mul_f32_e32 v177, v181, v177
	v_lshlrev_b32_e32 v168, 16, v134
	v_and_b32_e32 v169, 0xffff0000, v134
	v_lshlrev_b32_e32 v170, 16, v135
	v_and_b32_e32 v171, 0xffff0000, v135
	v_mul_f32_e32 v178, 0xbfb8aa3b, v168
	v_mul_f32_e32 v179, 0xbfb8aa3b, v169
	v_mul_f32_e32 v180, 0xbfb8aa3b, v170
	v_mul_f32_e32 v181, 0xbfb8aa3b, v171
	v_exp_f32_e32 v178, v178
	v_exp_f32_e32 v179, v179
	v_exp_f32_e32 v180, v180
	v_exp_f32_e32 v181, v181
	v_add_f32_e32 v178, 1.0, v178
	v_add_f32_e32 v179, 1.0, v179
	v_add_f32_e32 v180, 1.0, v180
	v_add_f32_e32 v181, 1.0, v181
	v_rcp_f32_e32 v178, v178
	v_rcp_f32_e32 v179, v179
	v_rcp_f32_e32 v180, v180
	v_rcp_f32_e32 v181, v181
	v_mul_f32_e32 v178, v178, v168
	v_mul_f32_e32 v179, v179, v169
	v_mul_f32_e32 v180, v180, v170
	v_mul_f32_e32 v181, v181, v171
	v_mul_f32_e32 v174, v174, v178
	v_mul_f32_e32 v175, v175, v179
	v_mul_f32_e32 v176, v176, v180
	v_mul_f32_e32 v177, v177, v181
	v_cvt_pk_bf16_f32 v182, v174, v175
	v_cvt_pk_bf16_f32 v183, v176, v177
	global_store_dwordx2 v234, v[182:183], s[6:7] offset:112
	global_load_dwordx4 v[88:91], v234, s[98:99] offset:192
	global_load_dwordx2 v[92:93], v234, s[100:101] offset:192
	global_load_dwordx4 v[94:97], v234, s[98:99] offset:208
	global_load_dwordx2 v[98:99], v234, s[100:101] offset:208
	global_load_dwordx4 v[100:103], v234, s[98:99] offset:224
	global_load_dwordx2 v[104:105], v234, s[100:101] offset:224
	global_load_dwordx4 v[106:109], v234, s[98:99] offset:240
	global_load_dwordx2 v[110:111], v234, s[100:101] offset:240
	s_waitcnt vmcnt(12)
	ds_read_b64 v[160:161], v235 offset:128
	ds_read_b64 v[162:163], v235 offset:144
	ds_read_b64 v[164:165], v235 offset:160
	ds_read_b64 v[166:167], v235 offset:176
	v_and_b32_e32 v168, 0xffff0000, v136
	v_lshlrev_b32_e32 v169, 16, v137
	v_and_b32_e32 v170, 0xffff0000, v137
	v_lshlrev_b32_e32 v171, 16, v138
	v_and_b32_e32 v172, 0xffff0000, v138
	v_lshlrev_b32_e32 v173, 16, v139
	v_mul_f32_e32 v178, v83, v168
	v_fmac_f32_e32 v178, v82, v169
	v_fmac_f32_e32 v178, v80, v170
	v_add_f32_e32 v178, v70, v178
	v_mul_f32_e32 v179, v83, v169
	v_fmac_f32_e32 v179, v82, v170
	v_fmac_f32_e32 v179, v80, v171
	v_add_f32_e32 v179, v70, v179
	v_mul_f32_e32 v180, v83, v170
	v_fmac_f32_e32 v180, v82, v171
	v_fmac_f32_e32 v180, v80, v172
	v_add_f32_e32 v180, v70, v180
	v_mul_f32_e32 v181, v83, v171
	v_fmac_f32_e32 v181, v82, v172
	v_fmac_f32_e32 v181, v80, v173
	v_add_f32_e32 v181, v70, v181
	s_waitcnt lgkmcnt(0)
	v_lshlrev_b32_e32 v174, 16, v160
	v_and_b32_e32 v175, 0xffff0000, v160
	v_lshlrev_b32_e32 v176, 16, v161
	v_and_b32_e32 v177, 0xffff0000, v161
	v_mul_f32_e32 v174, v68, v174
	v_mul_f32_e32 v175, v68, v175
	v_mul_f32_e32 v176, v68, v176
	v_mul_f32_e32 v177, v68, v177
	v_fmac_f32_e32 v174, v238, v16
	v_fmac_f32_e32 v175, v238, v17
	v_fmac_f32_e32 v176, v238, v18
	v_fmac_f32_e32 v177, v238, v19
	v_mul_f32_e32 v174, v178, v174
	v_mul_f32_e32 v175, v179, v175
	v_mul_f32_e32 v176, v180, v176
	v_mul_f32_e32 v177, v181, v177
	v_lshlrev_b32_e32 v168, 16, v140
	v_and_b32_e32 v169, 0xffff0000, v140
	v_lshlrev_b32_e32 v170, 16, v141
	v_and_b32_e32 v171, 0xffff0000, v141
	v_mul_f32_e32 v178, 0xbfb8aa3b, v168
	v_mul_f32_e32 v179, 0xbfb8aa3b, v169
	v_mul_f32_e32 v180, 0xbfb8aa3b, v170
	v_mul_f32_e32 v181, 0xbfb8aa3b, v171
	v_exp_f32_e32 v178, v178
	v_exp_f32_e32 v179, v179
	v_exp_f32_e32 v180, v180
	v_exp_f32_e32 v181, v181
	v_add_f32_e32 v178, 1.0, v178
	v_add_f32_e32 v179, 1.0, v179
	v_add_f32_e32 v180, 1.0, v180
	v_add_f32_e32 v181, 1.0, v181
	v_rcp_f32_e32 v178, v178
	v_rcp_f32_e32 v179, v179
	v_rcp_f32_e32 v180, v180
	v_rcp_f32_e32 v181, v181
	v_mul_f32_e32 v178, v178, v168
	v_mul_f32_e32 v179, v179, v169
	v_mul_f32_e32 v180, v180, v170
	v_mul_f32_e32 v181, v181, v171
	v_mul_f32_e32 v174, v174, v178
	v_mul_f32_e32 v175, v175, v179
	v_mul_f32_e32 v176, v176, v180
	v_mul_f32_e32 v177, v177, v181
	v_cvt_pk_bf16_f32 v182, v174, v175
	v_cvt_pk_bf16_f32 v183, v176, v177
	global_store_dwordx2 v234, v[182:183], s[6:7] offset:128
	v_and_b32_e32 v168, 0xffff0000, v142
; DI float bf2f(unsigned v) { return __uint_as_float(v << 16); }
; DI float bflo(unsigned v) { return __uint_as_float(v << 16); }
; DI float bfhi(unsigned v) { return __uint_as_float(v & 0xffff0000u); }
; DI float siluf(float x) { return x * __builtin_amdgcn_rcpf(1.f + __expf(-x)); }
; DI void sconv4(const u16* row, int t4, float w0, float w1, float w2, float bias, float (&o)[4]) {
;   const uint2 v = *(const uint2*)(row + t4);
;   const float x0 = bflo(v.x), x1 = bfhi(v.x), x2 = bflo(v.y), x3 = bfhi(v.y);
;   const float xm = (t4 > 0) ? bf2f(row[t4 - 1]) : 0.f;
;   const float xp = (t4 + 4 < SEQ) ? bf2f(row[t4 + 4]) : 0.f;
;   o[0] = w0 * xm + w1 * x0 + w2 * x1 + bias;
;   o[1] = w0 * x0 + w1 * x1 + w2 * x2 + bias;
;   o[2] = w0 * x1 + w1 * x2 + w2 * x3 + bias;
;   o[3] = w0 * x2 + w1 * x3 + w2 * xp + bias;
; }
; DI void hyena_item(const P& p, int l, int c, char* smem) {
;     ...
;       for (int rq = 0; rq < 4; ++rq) {
;         const int bq = 32 * I + 8 * rq + 4 * g;
;         const int t4 = 128 * a + bq;
;         float px[4];
;         sconv4(rowx, t4, x0, x1, x2, xb, px);
;         const uint2 zv = *(const uint2*)(U + (bt * 64 + a) * 136 + bq);
;         const uint2 gv = *(const uint2*)(rowg + t4);
;         const float z1[4] = {bflo(zv.x), bfhi(zv.x), bflo(zv.y), bfhi(zv.y)};
;         const float gt[4] = {bflo(gv.x), bfhi(gv.x), bflo(gv.y), bfhi(gv.y)};
;         float yy[4];
; #pragma unroll
;         for (int j = 0; j < 4; ++j) yy[j] = px[j] * (acc[I][4 * rq + j] * invn1 + z1[j] * d1) * siluf(gt[j]);
;         uint2 ov; ov.x = pack2(yy[0], yy[1]); ov.y = pack2(yy[2], yy[3]);
;         *(uint2*)(dst + t4) = ov;
;       }
	v_lshlrev_b32_e32 v169, 16, v143
	v_and_b32_e32 v170, 0xffff0000, v143
	v_lshlrev_b32_e32 v171, 16, v144
	v_and_b32_e32 v172, 0xffff0000, v144
	v_lshlrev_b32_e32 v173, 16, v145
	v_mul_f32_e32 v178, v83, v168
	v_fmac_f32_e32 v178, v82, v169
	v_fmac_f32_e32 v178, v80, v170
	v_add_f32_e32 v178, v70, v178
	v_mul_f32_e32 v179, v83, v169
	v_fmac_f32_e32 v179, v82, v170
	v_fmac_f32_e32 v179, v80, v171
	v_add_f32_e32 v179, v70, v179
	v_mul_f32_e32 v180, v83, v170
	v_fmac_f32_e32 v180, v82, v171
	v_fmac_f32_e32 v180, v80, v172
	v_add_f32_e32 v180, v70, v180
	v_mul_f32_e32 v181, v83, v171
	v_fmac_f32_e32 v181, v82, v172
	v_fmac_f32_e32 v181, v80, v173
	v_add_f32_e32 v181, v70, v181
	v_lshlrev_b32_e32 v174, 16, v162
	v_and_b32_e32 v175, 0xffff0000, v162
	v_lshlrev_b32_e32 v176, 16, v163
	v_and_b32_e32 v177, 0xffff0000, v163
	v_mul_f32_e32 v174, v68, v174
	v_mul_f32_e32 v175, v68, v175
	v_mul_f32_e32 v176, v68, v176
	v_mul_f32_e32 v177, v68, v177
	v_fmac_f32_e32 v174, v238, v20
	v_fmac_f32_e32 v175, v238, v21
	v_fmac_f32_e32 v176, v238, v22
	v_fmac_f32_e32 v177, v238, v23
	v_mul_f32_e32 v174, v178, v174
	v_mul_f32_e32 v175, v179, v175
	v_mul_f32_e32 v176, v180, v176
	v_mul_f32_e32 v177, v181, v177
	v_lshlrev_b32_e32 v168, 16, v146
	v_and_b32_e32 v169, 0xffff0000, v146
	v_lshlrev_b32_e32 v170, 16, v147
	v_and_b32_e32 v171, 0xffff0000, v147
	v_mul_f32_e32 v178, 0xbfb8aa3b, v168
	v_mul_f32_e32 v179, 0xbfb8aa3b, v169
	v_mul_f32_e32 v180, 0xbfb8aa3b, v170
	v_mul_f32_e32 v181, 0xbfb8aa3b, v171
	v_exp_f32_e32 v178, v178
	v_exp_f32_e32 v179, v179
	v_exp_f32_e32 v180, v180
	v_exp_f32_e32 v181, v181
	v_add_f32_e32 v178, 1.0, v178
	v_add_f32_e32 v179, 1.0, v179
	v_add_f32_e32 v180, 1.0, v180
	v_add_f32_e32 v181, 1.0, v181
	v_rcp_f32_e32 v178, v178
	v_rcp_f32_e32 v179, v179
	v_rcp_f32_e32 v180, v180
	v_rcp_f32_e32 v181, v181
	v_mul_f32_e32 v178, v178, v168
	v_mul_f32_e32 v179, v179, v169
	v_mul_f32_e32 v180, v180, v170
	v_mul_f32_e32 v181, v181, v171
	v_mul_f32_e32 v174, v174, v178
	v_mul_f32_e32 v175, v175, v179
	v_mul_f32_e32 v176, v176, v180
	v_mul_f32_e32 v177, v177, v181
	v_cvt_pk_bf16_f32 v182, v174, v175
	v_cvt_pk_bf16_f32 v183, v176, v177
	global_store_dwordx2 v234, v[182:183], s[6:7] offset:144
	v_and_b32_e32 v168, 0xffff0000, v148
	v_lshlrev_b32_e32 v169, 16, v149
	v_and_b32_e32 v170, 0xffff0000, v149
	v_lshlrev_b32_e32 v171, 16, v150
	v_and_b32_e32 v172, 0xffff0000, v150
	v_lshlrev_b32_e32 v173, 16, v151
	v_mul_f32_e32 v178, v83, v168
	v_fmac_f32_e32 v178, v82, v169
	v_fmac_f32_e32 v178, v80, v170
	v_add_f32_e32 v178, v70, v178
	v_mul_f32_e32 v179, v83, v169
	v_fmac_f32_e32 v179, v82, v170
	v_fmac_f32_e32 v179, v80, v171
	v_add_f32_e32 v179, v70, v179
	v_mul_f32_e32 v180, v83, v170
	v_fmac_f32_e32 v180, v82, v171
	v_fmac_f32_e32 v180, v80, v172
	v_add_f32_e32 v180, v70, v180
	v_mul_f32_e32 v181, v83, v171
	v_fmac_f32_e32 v181, v82, v172
	v_fmac_f32_e32 v181, v80, v173
	v_add_f32_e32 v181, v70, v181
	v_lshlrev_b32_e32 v174, 16, v164
	v_and_b32_e32 v175, 0xffff0000, v164
	v_lshlrev_b32_e32 v176, 16, v165
	v_and_b32_e32 v177, 0xffff0000, v165
	v_mul_f32_e32 v174, v68, v174
	v_mul_f32_e32 v175, v68, v175
	v_mul_f32_e32 v176, v68, v176
	v_mul_f32_e32 v177, v68, v177
	v_fmac_f32_e32 v174, v238, v24
	v_fmac_f32_e32 v175, v238, v25
	v_fmac_f32_e32 v176, v238, v26
	v_fmac_f32_e32 v177, v238, v27
	v_mul_f32_e32 v174, v178, v174
	v_mul_f32_e32 v175, v179, v175
	v_mul_f32_e32 v176, v180, v176
	v_mul_f32_e32 v177, v181, v177
	v_lshlrev_b32_e32 v168, 16, v152
	v_and_b32_e32 v169, 0xffff0000, v152
	v_lshlrev_b32_e32 v170, 16, v153
	v_and_b32_e32 v171, 0xffff0000, v153
	v_mul_f32_e32 v178, 0xbfb8aa3b, v168
	v_mul_f32_e32 v179, 0xbfb8aa3b, v169
	v_mul_f32_e32 v180, 0xbfb8aa3b, v170
	v_mul_f32_e32 v181, 0xbfb8aa3b, v171
	v_exp_f32_e32 v178, v178
	v_exp_f32_e32 v179, v179
	v_exp_f32_e32 v180, v180
	v_exp_f32_e32 v181, v181
	v_add_f32_e32 v178, 1.0, v178
	v_add_f32_e32 v179, 1.0, v179
	v_add_f32_e32 v180, 1.0, v180
	v_add_f32_e32 v181, 1.0, v181
	v_rcp_f32_e32 v178, v178
	v_rcp_f32_e32 v179, v179
	v_rcp_f32_e32 v180, v180
	v_rcp_f32_e32 v181, v181
	v_mul_f32_e32 v178, v178, v168
	v_mul_f32_e32 v179, v179, v169
	v_mul_f32_e32 v180, v180, v170
	v_mul_f32_e32 v181, v181, v171
	v_mul_f32_e32 v174, v174, v178
	v_mul_f32_e32 v175, v175, v179
	v_mul_f32_e32 v176, v176, v180
	v_mul_f32_e32 v177, v177, v181
	v_cvt_pk_bf16_f32 v182, v174, v175
	v_cvt_pk_bf16_f32 v183, v176, v177
	global_store_dwordx2 v234, v[182:183], s[6:7] offset:160
	v_and_b32_e32 v168, 0xffff0000, v154
	v_lshlrev_b32_e32 v169, 16, v155
	v_and_b32_e32 v170, 0xffff0000, v155
	v_lshlrev_b32_e32 v171, 16, v156
	v_and_b32_e32 v172, 0xffff0000, v156
	v_lshlrev_b32_e32 v173, 16, v157
	v_mul_f32_e32 v178, v83, v168
	v_fmac_f32_e32 v178, v82, v169
	v_fmac_f32_e32 v178, v80, v170
	v_add_f32_e32 v178, v70, v178
	v_mul_f32_e32 v179, v83, v169
	v_fmac_f32_e32 v179, v82, v170
	v_fmac_f32_e32 v179, v80, v171
	v_add_f32_e32 v179, v70, v179
	v_mul_f32_e32 v180, v83, v170
	v_fmac_f32_e32 v180, v82, v171
	v_fmac_f32_e32 v180, v80, v172
	v_add_f32_e32 v180, v70, v180
	v_mul_f32_e32 v181, v83, v171
	v_fmac_f32_e32 v181, v82, v172
	v_fmac_f32_e32 v181, v80, v173
	v_add_f32_e32 v181, v70, v181
	v_lshlrev_b32_e32 v174, 16, v166
	v_and_b32_e32 v175, 0xffff0000, v166
	v_lshlrev_b32_e32 v176, 16, v167
	v_and_b32_e32 v177, 0xffff0000, v167
	v_mul_f32_e32 v174, v68, v174
	v_mul_f32_e32 v175, v68, v175
	v_mul_f32_e32 v176, v68, v176
	v_mul_f32_e32 v177, v68, v177
	v_fmac_f32_e32 v174, v238, v28
	v_fmac_f32_e32 v175, v238, v29
	v_fmac_f32_e32 v176, v238, v30
	v_fmac_f32_e32 v177, v238, v31
	v_mul_f32_e32 v174, v178, v174
	v_mul_f32_e32 v175, v179, v175
	v_mul_f32_e32 v176, v180, v176
	v_mul_f32_e32 v177, v181, v177
	v_lshlrev_b32_e32 v168, 16, v158
	v_and_b32_e32 v169, 0xffff0000, v158
	v_lshlrev_b32_e32 v170, 16, v159
	v_and_b32_e32 v171, 0xffff0000, v159
	v_mul_f32_e32 v178, 0xbfb8aa3b, v168
	v_mul_f32_e32 v179, 0xbfb8aa3b, v169
	v_mul_f32_e32 v180, 0xbfb8aa3b, v170
	v_mul_f32_e32 v181, 0xbfb8aa3b, v171
	v_exp_f32_e32 v178, v178
	v_exp_f32_e32 v179, v179
	v_exp_f32_e32 v180, v180
	v_exp_f32_e32 v181, v181
	v_add_f32_e32 v178, 1.0, v178
	v_add_f32_e32 v179, 1.0, v179
	v_add_f32_e32 v180, 1.0, v180
	v_add_f32_e32 v181, 1.0, v181
	v_rcp_f32_e32 v178, v178
	v_rcp_f32_e32 v179, v179
	v_rcp_f32_e32 v180, v180
	v_rcp_f32_e32 v181, v181
	v_mul_f32_e32 v178, v178, v168
	v_mul_f32_e32 v179, v179, v169
	v_mul_f32_e32 v180, v180, v170
	v_mul_f32_e32 v181, v181, v171
	v_mul_f32_e32 v174, v174, v178
	v_mul_f32_e32 v175, v175, v179
	v_mul_f32_e32 v176, v176, v180
	v_mul_f32_e32 v177, v177, v181
	v_cvt_pk_bf16_f32 v182, v174, v175
	v_cvt_pk_bf16_f32 v183, v176, v177
	global_store_dwordx2 v234, v[182:183], s[6:7] offset:176
	s_waitcnt vmcnt(4)
; DI float bf2f(unsigned v) { return __uint_as_float(v << 16); }
; DI float bflo(unsigned v) { return __uint_as_float(v << 16); }
; DI float bfhi(unsigned v) { return __uint_as_float(v & 0xffff0000u); }
; DI float siluf(float x) { return x * __builtin_amdgcn_rcpf(1.f + __expf(-x)); }
; DI void sconv4(const u16* row, int t4, float w0, float w1, float w2, float bias, float (&o)[4]) {
;   const uint2 v = *(const uint2*)(row + t4);
;   const float x0 = bflo(v.x), x1 = bfhi(v.x), x2 = bflo(v.y), x3 = bfhi(v.y);
;   const float xm = (t4 > 0) ? bf2f(row[t4 - 1]) : 0.f;
;   const float xp = (t4 + 4 < SEQ) ? bf2f(row[t4 + 4]) : 0.f;
;   o[0] = w0 * xm + w1 * x0 + w2 * x1 + bias;
;   o[1] = w0 * x0 + w1 * x1 + w2 * x2 + bias;
;   o[2] = w0 * x1 + w1 * x2 + w2 * x3 + bias;
;   o[3] = w0 * x2 + w1 * x3 + w2 * xp + bias;
; }
; DI void hyena_item(const P& p, int l, int c, char* smem) {
;     ...
;       for (int rq = 0; rq < 4; ++rq) {
;         const int bq = 32 * I + 8 * rq + 4 * g;
;         const int t4 = 128 * a + bq;
;         float px[4];
;         sconv4(rowx, t4, x0, x1, x2, xb, px);
;         const uint2 zv = *(const uint2*)(U + (bt * 64 + a) * 136 + bq);
;         const uint2 gv = *(const uint2*)(rowg + t4);
;         const float z1[4] = {bflo(zv.x), bfhi(zv.x), bflo(zv.y), bfhi(zv.y)};
;         const float gt[4] = {bflo(gv.x), bfhi(gv.x), bflo(gv.y), bfhi(gv.y)};
;         float yy[4];
; #pragma unroll
;         for (int j = 0; j < 4; ++j) yy[j] = px[j] * (acc[I][4 * rq + j] * invn1 + z1[j] * d1) * siluf(gt[j]);
;         uint2 ov; ov.x = pack2(yy[0], yy[1]); ov.y = pack2(yy[2], yy[3]);
;         *(uint2*)(dst + t4) = ov;
;       }
	ds_read_b64 v[160:161], v235 offset:192
	ds_read_b64 v[162:163], v235 offset:208
	ds_read_b64 v[164:165], v235 offset:224
	ds_read_b64 v[166:167], v235 offset:240
	v_and_b32_e32 v168, 0xffff0000, v88
	v_lshlrev_b32_e32 v169, 16, v89
	v_and_b32_e32 v170, 0xffff0000, v89
	v_lshlrev_b32_e32 v171, 16, v90
	v_and_b32_e32 v172, 0xffff0000, v90
	v_lshlrev_b32_e32 v173, 16, v91
	v_mul_f32_e32 v178, v83, v168
	v_fmac_f32_e32 v178, v82, v169
	v_fmac_f32_e32 v178, v80, v170
	v_add_f32_e32 v178, v70, v178
	v_mul_f32_e32 v179, v83, v169
	v_fmac_f32_e32 v179, v82, v170
	v_fmac_f32_e32 v179, v80, v171
	v_add_f32_e32 v179, v70, v179
	v_mul_f32_e32 v180, v83, v170
	v_fmac_f32_e32 v180, v82, v171
	v_fmac_f32_e32 v180, v80, v172
	v_add_f32_e32 v180, v70, v180
	v_mul_f32_e32 v181, v83, v171
	v_fmac_f32_e32 v181, v82, v172
	v_fmac_f32_e32 v181, v80, v173
	v_add_f32_e32 v181, v70, v181
	s_waitcnt lgkmcnt(0)
	v_lshlrev_b32_e32 v174, 16, v160
	v_and_b32_e32 v175, 0xffff0000, v160
	v_lshlrev_b32_e32 v176, 16, v161
	v_and_b32_e32 v177, 0xffff0000, v161
	v_mul_f32_e32 v174, v68, v174
	v_mul_f32_e32 v175, v68, v175
	v_mul_f32_e32 v176, v68, v176
	v_mul_f32_e32 v177, v68, v177
	v_fmac_f32_e32 v174, v238, v0
	v_fmac_f32_e32 v175, v238, v1
	v_fmac_f32_e32 v176, v238, v2
	v_fmac_f32_e32 v177, v238, v3
	v_mul_f32_e32 v174, v178, v174
	v_mul_f32_e32 v175, v179, v175
	v_mul_f32_e32 v176, v180, v176
	v_mul_f32_e32 v177, v181, v177
	v_lshlrev_b32_e32 v168, 16, v92
	v_and_b32_e32 v169, 0xffff0000, v92
	v_lshlrev_b32_e32 v170, 16, v93
	v_and_b32_e32 v171, 0xffff0000, v93
	v_mul_f32_e32 v178, 0xbfb8aa3b, v168
	v_mul_f32_e32 v179, 0xbfb8aa3b, v169
	v_mul_f32_e32 v180, 0xbfb8aa3b, v170
	v_mul_f32_e32 v181, 0xbfb8aa3b, v171
	v_exp_f32_e32 v178, v178
	v_exp_f32_e32 v179, v179
	v_exp_f32_e32 v180, v180
	v_exp_f32_e32 v181, v181
	v_add_f32_e32 v178, 1.0, v178
	v_add_f32_e32 v179, 1.0, v179
	v_add_f32_e32 v180, 1.0, v180
	v_add_f32_e32 v181, 1.0, v181
	v_rcp_f32_e32 v178, v178
	v_rcp_f32_e32 v179, v179
	v_rcp_f32_e32 v180, v180
	v_rcp_f32_e32 v181, v181
	v_mul_f32_e32 v178, v178, v168
	v_mul_f32_e32 v179, v179, v169
	v_mul_f32_e32 v180, v180, v170
	v_mul_f32_e32 v181, v181, v171
	v_mul_f32_e32 v174, v174, v178
	v_mul_f32_e32 v175, v175, v179
	v_mul_f32_e32 v176, v176, v180
	v_mul_f32_e32 v177, v177, v181
	v_cvt_pk_bf16_f32 v182, v174, v175
	v_cvt_pk_bf16_f32 v183, v176, v177
	global_store_dwordx2 v234, v[182:183], s[6:7] offset:192
	v_and_b32_e32 v168, 0xffff0000, v94
	v_lshlrev_b32_e32 v169, 16, v95
	v_and_b32_e32 v170, 0xffff0000, v95
	v_lshlrev_b32_e32 v171, 16, v96
	v_and_b32_e32 v172, 0xffff0000, v96
	v_lshlrev_b32_e32 v173, 16, v97
	v_mul_f32_e32 v178, v83, v168
	v_fmac_f32_e32 v178, v82, v169
	v_fmac_f32_e32 v178, v80, v170
	v_add_f32_e32 v178, v70, v178
	v_mul_f32_e32 v179, v83, v169
	v_fmac_f32_e32 v179, v82, v170
	v_fmac_f32_e32 v179, v80, v171
	v_add_f32_e32 v179, v70, v179
	v_mul_f32_e32 v180, v83, v170
	v_fmac_f32_e32 v180, v82, v171
	v_fmac_f32_e32 v180, v80, v172
	v_add_f32_e32 v180, v70, v180
	v_mul_f32_e32 v181, v83, v171
	v_fmac_f32_e32 v181, v82, v172
	v_fmac_f32_e32 v181, v80, v173
	v_add_f32_e32 v181, v70, v181
	v_lshlrev_b32_e32 v174, 16, v162
	v_and_b32_e32 v175, 0xffff0000, v162
	v_lshlrev_b32_e32 v176, 16, v163
	v_and_b32_e32 v177, 0xffff0000, v163
	v_mul_f32_e32 v174, v68, v174
	v_mul_f32_e32 v175, v68, v175
	v_mul_f32_e32 v176, v68, v176
	v_mul_f32_e32 v177, v68, v177
	v_fmac_f32_e32 v174, v238, v4
	v_fmac_f32_e32 v175, v238, v5
	v_fmac_f32_e32 v176, v238, v6
	v_fmac_f32_e32 v177, v238, v7
	v_mul_f32_e32 v174, v178, v174
	v_mul_f32_e32 v175, v179, v175
	v_mul_f32_e32 v176, v180, v176
	v_mul_f32_e32 v177, v181, v177
	v_lshlrev_b32_e32 v168, 16, v98
	v_and_b32_e32 v169, 0xffff0000, v98
	v_lshlrev_b32_e32 v170, 16, v99
	v_and_b32_e32 v171, 0xffff0000, v99
	v_mul_f32_e32 v178, 0xbfb8aa3b, v168
	v_mul_f32_e32 v179, 0xbfb8aa3b, v169
	v_mul_f32_e32 v180, 0xbfb8aa3b, v170
	v_mul_f32_e32 v181, 0xbfb8aa3b, v171
	v_exp_f32_e32 v178, v178
	v_exp_f32_e32 v179, v179
	v_exp_f32_e32 v180, v180
	v_exp_f32_e32 v181, v181
	v_add_f32_e32 v178, 1.0, v178
	v_add_f32_e32 v179, 1.0, v179
	v_add_f32_e32 v180, 1.0, v180
	v_add_f32_e32 v181, 1.0, v181
	v_rcp_f32_e32 v178, v178
	v_rcp_f32_e32 v179, v179
	v_rcp_f32_e32 v180, v180
	v_rcp_f32_e32 v181, v181
	v_mul_f32_e32 v178, v178, v168
	v_mul_f32_e32 v179, v179, v169
	v_mul_f32_e32 v180, v180, v170
	v_mul_f32_e32 v181, v181, v171
	v_mul_f32_e32 v174, v174, v178
	v_mul_f32_e32 v175, v175, v179
	v_mul_f32_e32 v176, v176, v180
	v_mul_f32_e32 v177, v177, v181
	v_cvt_pk_bf16_f32 v182, v174, v175
	v_cvt_pk_bf16_f32 v183, v176, v177
	global_store_dwordx2 v234, v[182:183], s[6:7] offset:208
	v_and_b32_e32 v168, 0xffff0000, v100
; DI float bflo(unsigned v) { return __uint_as_float(v << 16); }
; DI float bfhi(unsigned v) { return __uint_as_float(v & 0xffff0000u); }
; DI float siluf(float x) { return x * __builtin_amdgcn_rcpf(1.f + __expf(-x)); }
; DI void hyena_item(const P& p, int l, int c, char* smem) {
;     ...
;       for (int rq = 0; rq < 4; ++rq) {
;         const int bq = 32 * I + 8 * rq + 4 * g;
;         const int t4 = 128 * a + bq;
;         float px[4];
;         sconv4(rowx, t4, x0, x1, x2, xb, px);
;         const uint2 zv = *(const uint2*)(U + (bt * 64 + a) * 136 + bq);
;         const uint2 gv = *(const uint2*)(rowg + t4);
;         const float z1[4] = {bflo(zv.x), bfhi(zv.x), bflo(zv.y), bfhi(zv.y)};
;         const float gt[4] = {bflo(gv.x), bfhi(gv.x), bflo(gv.y), bfhi(gv.y)};
;         float yy[4];
; #pragma unroll
;         for (int j = 0; j < 4; ++j) yy[j] = px[j] * (acc[I][4 * rq + j] * invn1 + z1[j] * d1) * siluf(gt[j]);
;         uint2 ov; ov.x = pack2(yy[0], yy[1]); ov.y = pack2(yy[2], yy[3]);
;         *(uint2*)(dst + t4) = ov;
;       }
	v_lshlrev_b32_e32 v169, 16, v101
	v_and_b32_e32 v170, 0xffff0000, v101
	v_lshlrev_b32_e32 v171, 16, v102
	v_and_b32_e32 v172, 0xffff0000, v102
	v_lshlrev_b32_e32 v173, 16, v103
	v_mul_f32_e32 v178, v83, v168
	v_fmac_f32_e32 v178, v82, v169
	v_fmac_f32_e32 v178, v80, v170
	v_add_f32_e32 v178, v70, v178
	v_mul_f32_e32 v179, v83, v169
	v_fmac_f32_e32 v179, v82, v170
	v_fmac_f32_e32 v179, v80, v171
	v_add_f32_e32 v179, v70, v179
	v_mul_f32_e32 v180, v83, v170
	v_fmac_f32_e32 v180, v82, v171
	v_fmac_f32_e32 v180, v80, v172
	v_add_f32_e32 v180, v70, v180
	v_mul_f32_e32 v181, v83, v171
	v_fmac_f32_e32 v181, v82, v172
	v_fmac_f32_e32 v181, v80, v173
	v_add_f32_e32 v181, v70, v181
	v_lshlrev_b32_e32 v174, 16, v164
	v_and_b32_e32 v175, 0xffff0000, v164
	v_lshlrev_b32_e32 v176, 16, v165
	v_and_b32_e32 v177, 0xffff0000, v165
	v_mul_f32_e32 v174, v68, v174
	v_mul_f32_e32 v175, v68, v175
	v_mul_f32_e32 v176, v68, v176
	v_mul_f32_e32 v177, v68, v177
	v_fmac_f32_e32 v174, v238, v8
	v_fmac_f32_e32 v175, v238, v9
	v_fmac_f32_e32 v176, v238, v10
	v_fmac_f32_e32 v177, v238, v11
	v_mul_f32_e32 v174, v178, v174
	v_mul_f32_e32 v175, v179, v175
	v_mul_f32_e32 v176, v180, v176
	v_mul_f32_e32 v177, v181, v177
	v_lshlrev_b32_e32 v168, 16, v104
	v_and_b32_e32 v169, 0xffff0000, v104
	v_lshlrev_b32_e32 v170, 16, v105
	v_and_b32_e32 v171, 0xffff0000, v105
	v_mul_f32_e32 v178, 0xbfb8aa3b, v168
	v_mul_f32_e32 v179, 0xbfb8aa3b, v169
	v_mul_f32_e32 v180, 0xbfb8aa3b, v170
	v_mul_f32_e32 v181, 0xbfb8aa3b, v171
	v_exp_f32_e32 v178, v178
	v_exp_f32_e32 v179, v179
	v_exp_f32_e32 v180, v180
	v_exp_f32_e32 v181, v181
	v_add_f32_e32 v178, 1.0, v178
	v_add_f32_e32 v179, 1.0, v179
	v_add_f32_e32 v180, 1.0, v180
	v_add_f32_e32 v181, 1.0, v181
	v_rcp_f32_e32 v178, v178
	v_rcp_f32_e32 v179, v179
	v_rcp_f32_e32 v180, v180
	v_rcp_f32_e32 v181, v181
	v_mul_f32_e32 v178, v178, v168
	v_mul_f32_e32 v179, v179, v169
	v_mul_f32_e32 v180, v180, v170
	v_mul_f32_e32 v181, v181, v171
	v_mul_f32_e32 v174, v174, v178
	v_mul_f32_e32 v175, v175, v179
	v_mul_f32_e32 v176, v176, v180
	v_mul_f32_e32 v177, v177, v181
	v_cvt_pk_bf16_f32 v182, v174, v175
	v_cvt_pk_bf16_f32 v183, v176, v177
	global_store_dwordx2 v234, v[182:183], s[6:7] offset:224
	v_cmp_ne_u32_e32 vcc, 0x1f84, v233
	s_nop 1
	v_and_b32_e32 v168, 0xffff0000, v106
	v_lshlrev_b32_e32 v169, 16, v107
	v_and_b32_e32 v170, 0xffff0000, v107
	v_lshlrev_b32_e32 v171, 16, v108
	v_and_b32_e32 v172, 0xffff0000, v108
	v_lshlrev_b32_e32 v173, 16, v109
	v_cndmask_b32_e32 v173, 0, v173, vcc
	v_mul_f32_e32 v178, v83, v168
	v_fmac_f32_e32 v178, v82, v169
	v_fmac_f32_e32 v178, v80, v170
	v_add_f32_e32 v178, v70, v178
	v_mul_f32_e32 v179, v83, v169
	v_fmac_f32_e32 v179, v82, v170
	v_fmac_f32_e32 v179, v80, v171
	v_add_f32_e32 v179, v70, v179
	v_mul_f32_e32 v180, v83, v170
	v_fmac_f32_e32 v180, v82, v171
	v_fmac_f32_e32 v180, v80, v172
	v_add_f32_e32 v180, v70, v180
	v_mul_f32_e32 v181, v83, v171
	v_fmac_f32_e32 v181, v82, v172
	v_fmac_f32_e32 v181, v80, v173
	v_add_f32_e32 v181, v70, v181
	v_lshlrev_b32_e32 v174, 16, v166
	v_and_b32_e32 v175, 0xffff0000, v166
	v_lshlrev_b32_e32 v176, 16, v167
	v_and_b32_e32 v177, 0xffff0000, v167
	v_mul_f32_e32 v174, v68, v174
	v_mul_f32_e32 v175, v68, v175
	v_mul_f32_e32 v176, v68, v176
	v_mul_f32_e32 v177, v68, v177
	v_fmac_f32_e32 v174, v238, v12
	v_fmac_f32_e32 v175, v238, v13
	v_fmac_f32_e32 v176, v238, v14
	v_fmac_f32_e32 v177, v238, v15
	v_mul_f32_e32 v174, v178, v174
	v_mul_f32_e32 v175, v179, v175
	v_mul_f32_e32 v176, v180, v176
	v_mul_f32_e32 v177, v181, v177
	v_lshlrev_b32_e32 v168, 16, v110
	v_and_b32_e32 v169, 0xffff0000, v110
	v_lshlrev_b32_e32 v170, 16, v111
	v_and_b32_e32 v171, 0xffff0000, v111
	v_mul_f32_e32 v178, 0xbfb8aa3b, v168
	v_mul_f32_e32 v179, 0xbfb8aa3b, v169
	v_mul_f32_e32 v180, 0xbfb8aa3b, v170
	v_mul_f32_e32 v181, 0xbfb8aa3b, v171
	v_exp_f32_e32 v178, v178
	v_exp_f32_e32 v179, v179
	v_exp_f32_e32 v180, v180
	v_exp_f32_e32 v181, v181
	v_add_f32_e32 v178, 1.0, v178
	v_add_f32_e32 v179, 1.0, v179
	v_add_f32_e32 v180, 1.0, v180
	v_add_f32_e32 v181, 1.0, v181
	v_rcp_f32_e32 v178, v178
	v_rcp_f32_e32 v179, v179
	v_rcp_f32_e32 v180, v180
	v_rcp_f32_e32 v181, v181
	v_mul_f32_e32 v178, v178, v168
	v_mul_f32_e32 v179, v179, v169
	v_mul_f32_e32 v180, v180, v170
	v_mul_f32_e32 v181, v181, v171
	v_mul_f32_e32 v174, v174, v178
	v_mul_f32_e32 v175, v175, v179
	v_mul_f32_e32 v176, v176, v180
	v_mul_f32_e32 v177, v177, v181
	v_cvt_pk_bf16_f32 v182, v174, v175
	v_cvt_pk_bf16_f32 v183, v176, v177
	global_store_dwordx2 v234, v[182:183], s[6:7] offset:240
.Lhy1_skip:
	s_mov_b64 s[8:9], 0
.LBB0_463:
	s_or_b64 exec, exec, s[12:13]
	s_and_b64 vcc, exec, s[10:11]
	s_cbranch_vccnz .LBB0_465
	s_branch .LBB0_472
